# early3 with tail priority 2 plus faster partner wake (priority raised before parking, redundant lgkmcnt(0) dropped)
# baseline (speedup 1.0000x reference)
; #define PG8_STAGE(bufoff, gbase, voff) do { _Pragma("unroll") for (int _i = 0; _i < 2; ++_i) \
;         __builtin_amdgcn_global_load_lds((const unsigned*)((const char*)(gbase) + (voff)[_i]), (PG8_LAS unsigned*)(lds + (bufoff) + ldsw + _i * 8192), 16, 0, 0); } while (0)
; #define PG8_LDA(dst, b, h) do { _Pragma("unroll") for (int m = 0; m < 4; ++m) _Pragma("unroll") for (int k = 0; k < 2; ++k) dst[m][k] = *(const PG8_LAS bf16x8*)(lds + PG8_SA(b, h) + aoff + m * 2048 + k * 1024); } while (0)
; #define PG8_LDB(dst, b, h) do { _Pragma("unroll") for (int n = 0; n < 2; ++n) _Pragma("unroll") for (int k = 0; k < 2; ++k) dst[n][k] = *(const PG8_LAS bf16x8*)(lds + PG8_SB(b, h) + boff + n * 2048 + k * 1024); } while (0)
; #define PG8_MMA(ai, bj, At, Bt) do { __builtin_amdgcn_s_setprio(1); _Pragma("unroll") for (int m = 0; m < 4; ++m) _Pragma("unroll") for (int n = 0; n < 2; ++n) _Pragma("unroll") for (int k = 0; k < 2; ++k) \
;         acc[ai][bj][m][n] = __builtin_amdgcn_mfma_f32_16x16x32_bf16(Bt[n][k], At[m][k], acc[ai][bj][m][n], 0, 0, 0); __builtin_amdgcn_s_setprio(0); } while (0)
; #define PG8_WAIT_V(n) asm volatile("s_waitcnt vmcnt(" #n ")" ::: "memory")
; #define PG8_WAIT_L(n) asm volatile("s_waitcnt lgkmcnt(" #n ")" ::: "memory")
; #define PG8_BAR __builtin_amdgcn_s_barrier()
; #define PG8_SCHED __builtin_amdgcn_sched_barrier(0)
; template <class Epi, class Sched, bool ALIGN_EPI = false, bool SP2 = false>
; __device__ __forceinline__ void gemm_phase(PG8_LAS unsigned char* lds, const Gemm g, const Sched& S, const Epi& E) {
;     ...
;         for (int t = 0; t < nt; t += 2) {
;             const bool last = (t == nt - 2);
;             const char* a1 = cA + (size_t)(t + 1) * kstep;
;             const char* a2 = last ? nA : cA + (size_t)(t + 2) * kstep; const char* b2 = last ? nB : cB + (size_t)(t + 2) * kstep;
;             const char* a3 = a2 + kstep; const char* b3 = b2 + kstep;
;             if constexpr (SP2) {
;             PG8_LDB(B0, 0, 0); PG8_LDB(B1, 0, 1); PG8_SCHED; PG8_LDA(At, 0, 0); PG8_STAGE(PG8_SA(1, 1), a1 + hstep, voffA);
;             PG8_WAIT_V(8); PG8_WAIT_L(0); PG8_BAR; PG8_MMA(0, 0, At, B0); PG8_MMA(0, 1, At, B1); PG8_BAR; PG8_SCHED;
;             PG8_LDA(At, 0, 1); PG8_STAGE(PG8_SB(0, 0), b2, voffB); PG8_STAGE(PG8_SB(0, 1), b2 + hstep, voffB); PG8_STAGE(PG8_SA(0, 0), a2, voffA);
.LBB0_200:
	ds_read_b128 v[148:151], v164
	ds_read_b128 v[152:155], v164 offset:1024
	ds_read_b128 v[156:159], v164 offset:2048
	ds_read_b128 v[168:171], v164 offset:3072
	ds_read_b128 v[172:175], v165
	ds_read_b128 v[176:179], v165 offset:1024
	ds_read_b128 v[180:183], v165 offset:2048
	ds_read_b128 v[184:187], v165 offset:3072
	s_add_u32 s52, s70, 0xfff80080
	s_addc_u32 s53, s71, -1
	s_cmp_eq_u32 s93, 28
	s_cselect_b32 s75, s39, s53
	s_cselect_b32 s74, s69, s52
	s_cselect_b32 s73, s35, s92
	s_cselect_b32 s72, s90, s91
	v_lshl_add_u64 v[220:221], s[70:71], 0, v[138:139]
	s_add_i32 m0, s33, 0xc000
	ds_read_b128 v[188:191], v166
	ds_read_b128 v[192:195], v166 offset:1024
	ds_read_b128 v[196:199], v166 offset:2048
	ds_read_b128 v[200:203], v166 offset:3072
	ds_read_b128 v[204:207], v166 offset:4096
	ds_read_b128 v[208:211], v166 offset:5120
	ds_read_b128 v[212:215], v166 offset:6144
	ds_read_b128 v[216:219], v166 offset:7168
	global_load_lds_dwordx4 v[220:221], off
	v_lshl_add_u64 v[220:221], s[70:71], 0, v[140:141]
	s_add_i32 m0, s33, 0xe000
	s_nop 0
	global_load_lds_dwordx4 v[220:221], off
	s_waitcnt vmcnt(8)
	s_waitcnt lgkmcnt(0)
	s_setprio 1
	s_barrier
	v_mfma_f32_16x16x32_bf16 v[124:127], v[148:151], v[188:191], v[124:127]
	v_mfma_f32_16x16x32_bf16 v[120:123], v[156:159], v[188:191], v[120:123]
	v_mfma_f32_16x16x32_bf16 v[116:119], v[148:151], v[196:199], v[116:119]
	v_mfma_f32_16x16x32_bf16 v[108:111], v[156:159], v[196:199], v[108:111]
	v_mfma_f32_16x16x32_bf16 v[100:103], v[148:151], v[204:207], v[100:103]
	v_mfma_f32_16x16x32_bf16 v[92:95], v[156:159], v[204:207], v[92:95]
	v_mfma_f32_16x16x32_bf16 v[84:87], v[148:151], v[212:215], v[84:87]
	v_mfma_f32_16x16x32_bf16 v[76:79], v[156:159], v[212:215], v[76:79]
	v_mfma_f32_16x16x32_bf16 v[124:127], v[152:155], v[192:195], v[124:127]
	v_mfma_f32_16x16x32_bf16 v[120:123], v[168:171], v[192:195], v[120:123]
	v_mfma_f32_16x16x32_bf16 v[116:119], v[152:155], v[200:203], v[116:119]
	v_mfma_f32_16x16x32_bf16 v[108:111], v[168:171], v[200:203], v[108:111]
	v_mfma_f32_16x16x32_bf16 v[100:103], v[152:155], v[208:211], v[100:103]
	v_mfma_f32_16x16x32_bf16 v[92:95], v[168:171], v[208:211], v[92:95]
	v_mfma_f32_16x16x32_bf16 v[84:87], v[152:155], v[216:219], v[84:87]
	v_mfma_f32_16x16x32_bf16 v[76:79], v[168:171], v[216:219], v[76:79]
	s_setprio 0
	s_setprio 1
	v_mfma_f32_16x16x32_bf16 v[112:115], v[172:175], v[188:191], v[112:115]
	v_mfma_f32_16x16x32_bf16 v[104:107], v[180:183], v[188:191], v[104:107]
	v_mfma_f32_16x16x32_bf16 v[96:99], v[172:175], v[196:199], v[96:99]
	v_mfma_f32_16x16x32_bf16 v[88:91], v[180:183], v[196:199], v[88:91]
	v_mfma_f32_16x16x32_bf16 v[80:83], v[172:175], v[204:207], v[80:83]
	v_mfma_f32_16x16x32_bf16 v[72:75], v[180:183], v[204:207], v[72:75]
	v_mfma_f32_16x16x32_bf16 v[68:71], v[172:175], v[212:215], v[68:71]
	v_mfma_f32_16x16x32_bf16 v[64:67], v[180:183], v[212:215], v[64:67]
	v_mfma_f32_16x16x32_bf16 v[112:115], v[176:179], v[192:195], v[112:115]
	v_mfma_f32_16x16x32_bf16 v[104:107], v[184:187], v[192:195], v[104:107]
	v_mfma_f32_16x16x32_bf16 v[96:99], v[176:179], v[200:203], v[96:99]
	v_mfma_f32_16x16x32_bf16 v[88:91], v[184:187], v[200:203], v[88:91]
	v_mfma_f32_16x16x32_bf16 v[80:83], v[176:179], v[208:211], v[80:83]
	s_setprio 2
	s_barrier
	v_mfma_f32_16x16x32_bf16 v[72:75], v[184:187], v[208:211], v[72:75]
	v_mfma_f32_16x16x32_bf16 v[68:71], v[176:179], v[216:219], v[68:71]
	v_mfma_f32_16x16x32_bf16 v[64:67], v[184:187], v[216:219], v[64:67]
	s_setprio 0
	s_add_i32 s52, s84, s3
	v_lshl_add_u64 v[220:221], s[72:73], 0, v[132:133]
	s_mov_b32 m0, s52
	ds_read_b128 v[188:191], v166 offset:16384
	ds_read_b128 v[192:195], v166 offset:17408
	ds_read_b128 v[196:199], v166 offset:18432
	ds_read_b128 v[200:203], v166 offset:19456
	ds_read_b128 v[204:207], v166 offset:20480
	ds_read_b128 v[208:211], v166 offset:21504
	ds_read_b128 v[212:215], v166 offset:22528
	ds_read_b128 v[216:219], v166 offset:23552
	global_load_lds_dwordx4 v[220:221], off
	s_add_i32 m0, s52, 0x2000
	s_add_u32 s96, s72, 0x80000
	v_lshl_add_u64 v[222:223], s[72:73], 0, v[128:129]
	s_addc_u32 s97, s73, 0
	s_add_i32 s52, s85, s3
	global_load_lds_dwordx4 v[222:223], off
	v_lshl_add_u64 v[224:225], s[96:97], 0, v[132:133]
	s_mov_b32 m0, s52
	v_lshl_add_u64 v[226:227], s[74:75], 0, v[130:131]
	global_load_lds_dwordx4 v[224:225], off
	v_lshl_add_u64 v[224:225], s[96:97], 0, v[128:129]
	s_add_i32 m0, s52, 0x2000
	s_nop 0
	global_load_lds_dwordx4 v[224:225], off
	v_lshl_add_u64 v[224:225], s[74:75], 0, v[134:135]
	s_mov_b32 m0, s33
	s_nop 0
	global_load_lds_dwordx4 v[224:225], off
	s_mov_b32 m0, s76
	s_nop 0
	global_load_lds_dwordx4 v[226:227], off
	s_waitcnt vmcnt(8)
	s_waitcnt lgkmcnt(0)
	s_setprio 1
	s_barrier
; #define PG8_STAGE(bufoff, gbase, voff) do { _Pragma("unroll") for (int _i = 0; _i < 2; ++_i) \
;         __builtin_amdgcn_global_load_lds((const unsigned*)((const char*)(gbase) + (voff)[_i]), (PG8_LAS unsigned*)(lds + (bufoff) + ldsw + _i * 8192), 16, 0, 0); } while (0)
; #define PG8_LDA(dst, b, h) do { _Pragma("unroll") for (int m = 0; m < 4; ++m) _Pragma("unroll") for (int k = 0; k < 2; ++k) dst[m][k] = *(const PG8_LAS bf16x8*)(lds + PG8_SA(b, h) + aoff + m * 2048 + k * 1024); } while (0)
; #define PG8_LDB(dst, b, h) do { _Pragma("unroll") for (int n = 0; n < 2; ++n) _Pragma("unroll") for (int k = 0; k < 2; ++k) dst[n][k] = *(const PG8_LAS bf16x8*)(lds + PG8_SB(b, h) + boff + n * 2048 + k * 1024); } while (0)
; #define PG8_MMA(ai, bj, At, Bt) do { __builtin_amdgcn_s_setprio(1); _Pragma("unroll") for (int m = 0; m < 4; ++m) _Pragma("unroll") for (int n = 0; n < 2; ++n) _Pragma("unroll") for (int k = 0; k < 2; ++k) \
;         acc[ai][bj][m][n] = __builtin_amdgcn_mfma_f32_16x16x32_bf16(Bt[n][k], At[m][k], acc[ai][bj][m][n], 0, 0, 0); __builtin_amdgcn_s_setprio(0); } while (0)
; #define PG8_WAIT_V(n) asm volatile("s_waitcnt vmcnt(" #n ")" ::: "memory")
; #define PG8_WAIT_L(n) asm volatile("s_waitcnt lgkmcnt(" #n ")" ::: "memory")
; #define PG8_BAR __builtin_amdgcn_s_barrier()
; #define PG8_SCHED __builtin_amdgcn_sched_barrier(0)
; template <class Epi, class Sched, bool ALIGN_EPI = false, bool SP2 = false>
; __device__ __forceinline__ void gemm_phase(PG8_LAS unsigned char* lds, const Gemm g, const Sched& S, const Epi& E) {
;     ...
;             PG8_WAIT_V(8); PG8_WAIT_L(0); PG8_BAR; PG8_MMA(1, 0, At, B0); PG8_MMA(1, 1, At, B1); PG8_BAR; PG8_SCHED;
;             PG8_LDB(B0, 1, 0); PG8_LDB(B1, 1, 1); PG8_SCHED; PG8_LDA(At, 1, 0); PG8_STAGE(PG8_SA(0, 1), a2 + hstep, voffA);
;             PG8_WAIT_V(8); PG8_WAIT_L(0); PG8_BAR; PG8_MMA(0, 0, At, B0); PG8_MMA(0, 1, At, B1); PG8_BAR; PG8_SCHED;
	v_mfma_f32_16x16x32_bf16 v[60:63], v[148:151], v[188:191], v[60:63]
	v_mfma_f32_16x16x32_bf16 v[56:59], v[156:159], v[188:191], v[56:59]
	v_mfma_f32_16x16x32_bf16 v[52:55], v[148:151], v[196:199], v[52:55]
	v_mfma_f32_16x16x32_bf16 v[44:47], v[156:159], v[196:199], v[44:47]
	v_mfma_f32_16x16x32_bf16 v[36:39], v[148:151], v[204:207], v[36:39]
	v_mfma_f32_16x16x32_bf16 v[28:31], v[156:159], v[204:207], v[28:31]
	v_mfma_f32_16x16x32_bf16 v[20:23], v[148:151], v[212:215], v[20:23]
	v_mfma_f32_16x16x32_bf16 v[12:15], v[156:159], v[212:215], v[12:15]
	v_mfma_f32_16x16x32_bf16 v[60:63], v[152:155], v[192:195], v[60:63]
	v_mfma_f32_16x16x32_bf16 v[56:59], v[168:171], v[192:195], v[56:59]
	v_mfma_f32_16x16x32_bf16 v[52:55], v[152:155], v[200:203], v[52:55]
	v_mfma_f32_16x16x32_bf16 v[44:47], v[168:171], v[200:203], v[44:47]
	v_mfma_f32_16x16x32_bf16 v[36:39], v[152:155], v[208:211], v[36:39]
	v_mfma_f32_16x16x32_bf16 v[28:31], v[168:171], v[208:211], v[28:31]
	v_mfma_f32_16x16x32_bf16 v[20:23], v[152:155], v[216:219], v[20:23]
	v_mfma_f32_16x16x32_bf16 v[12:15], v[168:171], v[216:219], v[12:15]
	s_setprio 0
	s_setprio 1
	v_mfma_f32_16x16x32_bf16 v[48:51], v[172:175], v[188:191], v[48:51]
	v_mfma_f32_16x16x32_bf16 v[40:43], v[180:183], v[188:191], v[40:43]
	v_mfma_f32_16x16x32_bf16 v[32:35], v[172:175], v[196:199], v[32:35]
	v_mfma_f32_16x16x32_bf16 v[24:27], v[180:183], v[196:199], v[24:27]
	v_mfma_f32_16x16x32_bf16 v[16:19], v[172:175], v[204:207], v[16:19]
	v_mfma_f32_16x16x32_bf16 v[8:11], v[180:183], v[204:207], v[8:11]
	v_mfma_f32_16x16x32_bf16 v[4:7], v[172:175], v[212:215], v[4:7]
	v_mfma_f32_16x16x32_bf16 v[0:3], v[180:183], v[212:215], v[0:3]
	v_mfma_f32_16x16x32_bf16 v[48:51], v[176:179], v[192:195], v[48:51]
	v_mfma_f32_16x16x32_bf16 v[40:43], v[184:187], v[192:195], v[40:43]
	v_mfma_f32_16x16x32_bf16 v[32:35], v[176:179], v[200:203], v[32:35]
	v_mfma_f32_16x16x32_bf16 v[24:27], v[184:187], v[200:203], v[24:27]
	v_mfma_f32_16x16x32_bf16 v[16:19], v[176:179], v[208:211], v[16:19]
	s_setprio 2
	s_barrier
	v_mfma_f32_16x16x32_bf16 v[8:11], v[184:187], v[208:211], v[8:11]
	v_mfma_f32_16x16x32_bf16 v[4:7], v[176:179], v[216:219], v[4:7]
	v_mfma_f32_16x16x32_bf16 v[0:3], v[184:187], v[216:219], v[0:3]
	s_setprio 0
	s_add_i32 s52, 0, 0x18000
	v_add_u32_e32 v136, s52, v161
	s_add_i32 s53, 0, 0x1c000
	ds_read_b128 v[148:151], v136
	ds_read_b128 v[152:155], v136 offset:1024
	ds_read_b128 v[156:159], v136 offset:2048
	ds_read_b128 v[168:171], v136 offset:3072
	v_add_u32_e32 v136, s53, v161
	ds_read_b128 v[172:175], v136
	ds_read_b128 v[176:179], v136 offset:1024
	ds_read_b128 v[180:183], v136 offset:2048
	ds_read_b128 v[184:187], v136 offset:3072
	s_add_u32 s74, s74, 0x80000
	s_addc_u32 s75, s75, 0
	s_mov_b32 m0, s77
	v_lshl_add_u64 v[228:229], s[74:75], 0, v[134:135]
	ds_read_b128 v[188:191], v166 offset:32768
	ds_read_b128 v[192:195], v166 offset:33792
	ds_read_b128 v[196:199], v166 offset:34816
	ds_read_b128 v[200:203], v166 offset:35840
	ds_read_b128 v[204:207], v166 offset:36864
	ds_read_b128 v[208:211], v166 offset:37888
	ds_read_b128 v[212:215], v166 offset:38912
	ds_read_b128 v[216:219], v166 offset:39936
	global_load_lds_dwordx4 v[228:229], off
	v_lshl_add_u64 v[228:229], s[74:75], 0, v[130:131]
	s_mov_b32 m0, s78
	s_nop 0
	global_load_lds_dwordx4 v[228:229], off
	s_waitcnt vmcnt(8)
	s_waitcnt lgkmcnt(0)
	s_setprio 1
	s_barrier
	v_mfma_f32_16x16x32_bf16 v[124:127], v[148:151], v[188:191], v[124:127]
	v_mfma_f32_16x16x32_bf16 v[120:123], v[156:159], v[188:191], v[120:123]
	v_mfma_f32_16x16x32_bf16 v[116:119], v[148:151], v[196:199], v[116:119]
	v_mfma_f32_16x16x32_bf16 v[108:111], v[156:159], v[196:199], v[108:111]
	v_mfma_f32_16x16x32_bf16 v[100:103], v[148:151], v[204:207], v[100:103]
	v_mfma_f32_16x16x32_bf16 v[92:95], v[156:159], v[204:207], v[92:95]
	v_mfma_f32_16x16x32_bf16 v[84:87], v[148:151], v[212:215], v[84:87]
	v_mfma_f32_16x16x32_bf16 v[76:79], v[156:159], v[212:215], v[76:79]
	v_mfma_f32_16x16x32_bf16 v[124:127], v[152:155], v[192:195], v[124:127]
	v_mfma_f32_16x16x32_bf16 v[120:123], v[168:171], v[192:195], v[120:123]
	v_mfma_f32_16x16x32_bf16 v[116:119], v[152:155], v[200:203], v[116:119]
	v_mfma_f32_16x16x32_bf16 v[108:111], v[168:171], v[200:203], v[108:111]
	v_mfma_f32_16x16x32_bf16 v[100:103], v[152:155], v[208:211], v[100:103]
	v_mfma_f32_16x16x32_bf16 v[92:95], v[168:171], v[208:211], v[92:95]
	v_mfma_f32_16x16x32_bf16 v[84:87], v[152:155], v[216:219], v[84:87]
	v_mfma_f32_16x16x32_bf16 v[76:79], v[168:171], v[216:219], v[76:79]
	s_setprio 0
	s_setprio 1
	v_mfma_f32_16x16x32_bf16 v[112:115], v[172:175], v[188:191], v[112:115]
	v_mfma_f32_16x16x32_bf16 v[104:107], v[180:183], v[188:191], v[104:107]
	v_mfma_f32_16x16x32_bf16 v[96:99], v[172:175], v[196:199], v[96:99]
	v_mfma_f32_16x16x32_bf16 v[88:91], v[180:183], v[196:199], v[88:91]
	v_mfma_f32_16x16x32_bf16 v[80:83], v[172:175], v[204:207], v[80:83]
	v_mfma_f32_16x16x32_bf16 v[72:75], v[180:183], v[204:207], v[72:75]
	v_mfma_f32_16x16x32_bf16 v[68:71], v[172:175], v[212:215], v[68:71]
	v_mfma_f32_16x16x32_bf16 v[64:67], v[180:183], v[212:215], v[64:67]
	v_mfma_f32_16x16x32_bf16 v[112:115], v[176:179], v[192:195], v[112:115]
	v_mfma_f32_16x16x32_bf16 v[104:107], v[184:187], v[192:195], v[104:107]
	v_mfma_f32_16x16x32_bf16 v[96:99], v[176:179], v[200:203], v[96:99]
	v_mfma_f32_16x16x32_bf16 v[88:91], v[184:187], v[200:203], v[88:91]
	v_mfma_f32_16x16x32_bf16 v[80:83], v[176:179], v[208:211], v[80:83]
	s_setprio 2
	s_barrier
; #define PG8_STAGE(bufoff, gbase, voff) do { _Pragma("unroll") for (int _i = 0; _i < 2; ++_i) \
;         __builtin_amdgcn_global_load_lds((const unsigned*)((const char*)(gbase) + (voff)[_i]), (PG8_LAS unsigned*)(lds + (bufoff) + ldsw + _i * 8192), 16, 0, 0); } while (0)
; #define PG8_LDA(dst, b, h) do { _Pragma("unroll") for (int m = 0; m < 4; ++m) _Pragma("unroll") for (int k = 0; k < 2; ++k) dst[m][k] = *(const PG8_LAS bf16x8*)(lds + PG8_SA(b, h) + aoff + m * 2048 + k * 1024); } while (0)
; #define PG8_MMA(ai, bj, At, Bt) do { __builtin_amdgcn_s_setprio(1); _Pragma("unroll") for (int m = 0; m < 4; ++m) _Pragma("unroll") for (int n = 0; n < 2; ++n) _Pragma("unroll") for (int k = 0; k < 2; ++k) \
;         acc[ai][bj][m][n] = __builtin_amdgcn_mfma_f32_16x16x32_bf16(Bt[n][k], At[m][k], acc[ai][bj][m][n], 0, 0, 0); __builtin_amdgcn_s_setprio(0); } while (0)
; #define PG8_WAIT_V(n) asm volatile("s_waitcnt vmcnt(" #n ")" ::: "memory")
; #define PG8_WAIT_L(n) asm volatile("s_waitcnt lgkmcnt(" #n ")" ::: "memory")
; #define PG8_BAR __builtin_amdgcn_s_barrier()
; #define PG8_SCHED __builtin_amdgcn_sched_barrier(0)
; template <class Epi, class Sched, bool ALIGN_EPI = false, bool SP2 = false>
; __device__ __forceinline__ void gemm_phase(PG8_LAS unsigned char* lds, const Gemm g, const Sched& S, const Epi& E) {
;     ...
;             PG8_WAIT_V(8); PG8_WAIT_L(0); PG8_BAR; PG8_MMA(0, 0, At, B0); PG8_MMA(0, 1, At, B1); PG8_BAR; PG8_SCHED;
;             PG8_LDA(At, 1, 1); PG8_STAGE(PG8_SB(1, 0), b3, voffB); PG8_STAGE(PG8_SB(1, 1), b3 + hstep, voffB); PG8_STAGE(PG8_SA(1, 0), a3, voffA);
;             PG8_WAIT_V(8); PG8_WAIT_L(0); PG8_BAR; PG8_MMA(1, 0, At, B0); PG8_MMA(1, 1, At, B1); PG8_BAR; PG8_SCHED;
;     ...
;         if constexpr (ALIGN_EPI) { if (wr == 0) PG8_BAR; }
	v_mfma_f32_16x16x32_bf16 v[72:75], v[184:187], v[208:211], v[72:75]
	v_mfma_f32_16x16x32_bf16 v[68:71], v[176:179], v[216:219], v[68:71]
	v_mfma_f32_16x16x32_bf16 v[64:67], v[184:187], v[216:219], v[64:67]
	s_setprio 0
	s_add_i32 s52, s52, s3
	v_lshl_add_u64 v[220:221], v[220:221], 0, s[12:13]
	s_mov_b32 m0, s52
	ds_read_b128 v[188:191], v166 offset:49152
	ds_read_b128 v[192:195], v166 offset:50176
	ds_read_b128 v[196:199], v166 offset:51200
	ds_read_b128 v[200:203], v166 offset:52224
	ds_read_b128 v[204:207], v166 offset:53248
	ds_read_b128 v[208:211], v166 offset:54272
	ds_read_b128 v[212:215], v166 offset:55296
	ds_read_b128 v[216:219], v166 offset:56320
	global_load_lds_dwordx4 v[220:221], off
	s_add_i32 m0, s52, 0x2000
	s_add_u32 s72, s72, 0x80080
	v_lshl_add_u64 v[220:221], v[222:223], 0, s[12:13]
	s_addc_u32 s73, s73, 0
	s_add_i32 s52, s53, s3
	global_load_lds_dwordx4 v[220:221], off
	v_lshl_add_u64 v[220:221], s[72:73], 0, v[132:133]
	s_mov_b32 m0, s52
	s_nop 0
	global_load_lds_dwordx4 v[220:221], off
	v_lshl_add_u64 v[220:221], s[72:73], 0, v[128:129]
	s_add_i32 m0, s52, 0x2000
	s_nop 0
	global_load_lds_dwordx4 v[220:221], off
	v_lshl_add_u64 v[220:221], v[224:225], 0, s[12:13]
	s_mov_b32 m0, s80
	s_nop 0
	global_load_lds_dwordx4 v[220:221], off
	v_lshl_add_u64 v[220:221], v[226:227], 0, s[12:13]
	s_mov_b32 m0, s81
	s_nop 0
	global_load_lds_dwordx4 v[220:221], off
	s_waitcnt vmcnt(8)
	s_waitcnt lgkmcnt(0)
	s_setprio 1
	s_barrier
	v_mfma_f32_16x16x32_bf16 v[60:63], v[148:151], v[188:191], v[60:63]
	v_mfma_f32_16x16x32_bf16 v[56:59], v[156:159], v[188:191], v[56:59]
	v_mfma_f32_16x16x32_bf16 v[52:55], v[148:151], v[196:199], v[52:55]
	v_mfma_f32_16x16x32_bf16 v[44:47], v[156:159], v[196:199], v[44:47]
	v_mfma_f32_16x16x32_bf16 v[36:39], v[148:151], v[204:207], v[36:39]
	v_mfma_f32_16x16x32_bf16 v[28:31], v[156:159], v[204:207], v[28:31]
	v_mfma_f32_16x16x32_bf16 v[20:23], v[148:151], v[212:215], v[20:23]
	v_mfma_f32_16x16x32_bf16 v[12:15], v[156:159], v[212:215], v[12:15]
	v_mfma_f32_16x16x32_bf16 v[60:63], v[152:155], v[192:195], v[60:63]
	v_mfma_f32_16x16x32_bf16 v[56:59], v[168:171], v[192:195], v[56:59]
	v_mfma_f32_16x16x32_bf16 v[52:55], v[152:155], v[200:203], v[52:55]
	v_mfma_f32_16x16x32_bf16 v[44:47], v[168:171], v[200:203], v[44:47]
	v_mfma_f32_16x16x32_bf16 v[36:39], v[152:155], v[208:211], v[36:39]
	v_mfma_f32_16x16x32_bf16 v[28:31], v[168:171], v[208:211], v[28:31]
	v_mfma_f32_16x16x32_bf16 v[20:23], v[152:155], v[216:219], v[20:23]
	v_mfma_f32_16x16x32_bf16 v[12:15], v[168:171], v[216:219], v[12:15]
	s_setprio 0
	s_setprio 1
	v_mfma_f32_16x16x32_bf16 v[48:51], v[172:175], v[188:191], v[48:51]
	v_mfma_f32_16x16x32_bf16 v[40:43], v[180:183], v[188:191], v[40:43]
	v_mfma_f32_16x16x32_bf16 v[32:35], v[172:175], v[196:199], v[32:35]
	v_mfma_f32_16x16x32_bf16 v[24:27], v[180:183], v[196:199], v[24:27]
	v_mfma_f32_16x16x32_bf16 v[16:19], v[172:175], v[204:207], v[16:19]
	v_mfma_f32_16x16x32_bf16 v[8:11], v[180:183], v[204:207], v[8:11]
	v_mfma_f32_16x16x32_bf16 v[4:7], v[172:175], v[212:215], v[4:7]
	v_mfma_f32_16x16x32_bf16 v[0:3], v[180:183], v[212:215], v[0:3]
	v_mfma_f32_16x16x32_bf16 v[48:51], v[176:179], v[192:195], v[48:51]
	v_mfma_f32_16x16x32_bf16 v[40:43], v[184:187], v[192:195], v[40:43]
	v_mfma_f32_16x16x32_bf16 v[32:35], v[176:179], v[200:203], v[32:35]
	v_mfma_f32_16x16x32_bf16 v[24:27], v[184:187], v[200:203], v[24:27]
	v_mfma_f32_16x16x32_bf16 v[16:19], v[176:179], v[208:211], v[16:19]
	s_setprio 2
	s_barrier
	v_mfma_f32_16x16x32_bf16 v[8:11], v[184:187], v[208:211], v[8:11]
	v_mfma_f32_16x16x32_bf16 v[4:7], v[176:179], v[216:219], v[4:7]
	v_mfma_f32_16x16x32_bf16 v[0:3], v[184:187], v[216:219], v[0:3]
	s_setprio 0
	s_add_i32 s93, s93, 2
	s_add_u32 s70, s70, 0x100
	s_addc_u32 s71, s71, 0
	s_add_u32 s91, s91, 0x100
	s_addc_u32 s92, s92, 0
	s_cmp_gt_u32 s93, 29
	s_cbranch_scc0 .LBB0_200
	s_and_b64 vcc, exec, s[14:15]
	s_cbranch_vccz .LBB0_203
	s_barrier

; #define PG8_STAGE(bufoff, gbase, voff) do { _Pragma("unroll") for (int _i = 0; _i < 2; ++_i) \
;         __builtin_amdgcn_global_load_lds((const unsigned*)((const char*)(gbase) + (voff)[_i]), (PG8_LAS unsigned*)(lds + (bufoff) + ldsw + _i * 8192), 16, 0, 0); } while (0)
; #define PG8_LDA(dst, b, h) do { _Pragma("unroll") for (int m = 0; m < 4; ++m) _Pragma("unroll") for (int k = 0; k < 2; ++k) dst[m][k] = *(const PG8_LAS bf16x8*)(lds + PG8_SA(b, h) + aoff + m * 2048 + k * 1024); } while (0)
; #define PG8_LDB(dst, b, h) do { _Pragma("unroll") for (int n = 0; n < 2; ++n) _Pragma("unroll") for (int k = 0; k < 2; ++k) dst[n][k] = *(const PG8_LAS bf16x8*)(lds + PG8_SB(b, h) + boff + n * 2048 + k * 1024); } while (0)
; #define PG8_MMA(ai, bj, At, Bt) do { __builtin_amdgcn_s_setprio(1); _Pragma("unroll") for (int m = 0; m < 4; ++m) _Pragma("unroll") for (int n = 0; n < 2; ++n) _Pragma("unroll") for (int k = 0; k < 2; ++k) \
;         acc[ai][bj][m][n] = __builtin_amdgcn_mfma_f32_16x16x32_bf16(Bt[n][k], At[m][k], acc[ai][bj][m][n], 0, 0, 0); __builtin_amdgcn_s_setprio(0); } while (0)
; #define PG8_WAIT_V(n) asm volatile("s_waitcnt vmcnt(" #n ")" ::: "memory")
; #define PG8_WAIT_L(n) asm volatile("s_waitcnt lgkmcnt(" #n ")" ::: "memory")
; #define PG8_BAR __builtin_amdgcn_s_barrier()
; #define PG8_SCHED __builtin_amdgcn_sched_barrier(0)
; template <class Epi, class Sched, bool ALIGN_EPI = false, bool SP2 = false>
; __device__ __forceinline__ void gemm_phase(PG8_LAS unsigned char* lds, const Gemm g, const Sched& S, const Epi& E) {
;     ...
;             const bool last = (t == nt - 2);
;             const char* a1 = cA + (size_t)(t + 1) * kstep;
;             const char* a2 = last ? nA : cA + (size_t)(t + 2) * kstep; const char* b2 = last ? nB : cB + (size_t)(t + 2) * kstep;
;             const char* a3 = a2 + kstep; const char* b3 = b2 + kstep;
;             if constexpr (SP2) {
;             PG8_LDB(B0, 0, 0); PG8_LDB(B1, 0, 1); PG8_SCHED; PG8_LDA(At, 0, 0); PG8_STAGE(PG8_SA(1, 1), a1 + hstep, voffA);
;             PG8_WAIT_V(8); PG8_WAIT_L(0); PG8_BAR; PG8_MMA(0, 0, At, B0); PG8_MMA(0, 1, At, B1); PG8_BAR; PG8_SCHED;
;             PG8_LDA(At, 0, 1); PG8_STAGE(PG8_SB(0, 0), b2, voffB); PG8_STAGE(PG8_SB(0, 1), b2 + hstep, voffB); PG8_STAGE(PG8_SA(0, 0), a2, voffA);
.LBB0_374:
	ds_read_b128 v[128:131], v230
	ds_read_b128 v[132:135], v230 offset:1024
	ds_read_b128 v[158:161], v230 offset:2048
	ds_read_b128 v[162:165], v230 offset:3072
	ds_read_b128 v[166:169], v231
	ds_read_b128 v[170:173], v231 offset:1024
	ds_read_b128 v[174:177], v231 offset:2048
	ds_read_b128 v[178:181], v231 offset:3072
	s_add_u32 s52, s76, 0xfff80080
	s_addc_u32 s53, s77, -1
	s_cmp_eq_u32 vcc_hi, 28
	s_cselect_b32 s81, s11, s53
	s_cselect_b32 s80, s55, s52
	s_cselect_b32 s79, s51, vcc_lo
	s_cselect_b32 s78, s73, s75
	v_lshl_add_u64 v[214:215], s[76:77], 0, v[150:151]
	s_add_i32 m0, s28, 0xc000
	ds_read_b128 v[182:185], v232
	ds_read_b128 v[186:189], v232 offset:1024
	ds_read_b128 v[190:193], v232 offset:2048
	ds_read_b128 v[194:197], v232 offset:3072
	ds_read_b128 v[198:201], v232 offset:4096
	ds_read_b128 v[202:205], v232 offset:5120
	ds_read_b128 v[206:209], v232 offset:6144
	ds_read_b128 v[210:213], v232 offset:7168
	global_load_lds_dwordx4 v[214:215], off
	v_lshl_add_u64 v[214:215], s[76:77], 0, v[152:153]
	s_add_i32 m0, s28, 0xe000
	s_nop 0
	global_load_lds_dwordx4 v[214:215], off
	s_waitcnt vmcnt(8)
	s_waitcnt lgkmcnt(0)
	s_setprio 1
	s_barrier
	v_mfma_f32_16x16x32_bf16 v[124:127], v[128:131], v[182:185], v[124:127]
	v_mfma_f32_16x16x32_bf16 v[120:123], v[158:161], v[182:185], v[120:123]
	v_mfma_f32_16x16x32_bf16 v[116:119], v[128:131], v[190:193], v[116:119]
	v_mfma_f32_16x16x32_bf16 v[112:115], v[158:161], v[190:193], v[112:115]
	v_mfma_f32_16x16x32_bf16 v[108:111], v[128:131], v[198:201], v[108:111]
	v_mfma_f32_16x16x32_bf16 v[104:107], v[158:161], v[198:201], v[104:107]
	v_mfma_f32_16x16x32_bf16 v[100:103], v[128:131], v[206:209], v[100:103]
	v_mfma_f32_16x16x32_bf16 v[96:99], v[158:161], v[206:209], v[96:99]
	v_mfma_f32_16x16x32_bf16 v[124:127], v[132:135], v[186:189], v[124:127]
	v_mfma_f32_16x16x32_bf16 v[120:123], v[162:165], v[186:189], v[120:123]
	v_mfma_f32_16x16x32_bf16 v[116:119], v[132:135], v[194:197], v[116:119]
	v_mfma_f32_16x16x32_bf16 v[112:115], v[162:165], v[194:197], v[112:115]
	v_mfma_f32_16x16x32_bf16 v[108:111], v[132:135], v[202:205], v[108:111]
	v_mfma_f32_16x16x32_bf16 v[104:107], v[162:165], v[202:205], v[104:107]
	v_mfma_f32_16x16x32_bf16 v[100:103], v[132:135], v[210:213], v[100:103]
	v_mfma_f32_16x16x32_bf16 v[96:99], v[162:165], v[210:213], v[96:99]
	s_setprio 0
	s_setprio 1
	v_mfma_f32_16x16x32_bf16 v[60:63], v[166:169], v[182:185], v[60:63]
	v_mfma_f32_16x16x32_bf16 v[56:59], v[174:177], v[182:185], v[56:59]
	v_mfma_f32_16x16x32_bf16 v[52:55], v[166:169], v[190:193], v[52:55]
	v_mfma_f32_16x16x32_bf16 v[48:51], v[174:177], v[190:193], v[48:51]
	v_mfma_f32_16x16x32_bf16 v[44:47], v[166:169], v[198:201], v[44:47]
	v_mfma_f32_16x16x32_bf16 v[40:43], v[174:177], v[198:201], v[40:43]
	v_mfma_f32_16x16x32_bf16 v[36:39], v[166:169], v[206:209], v[36:39]
	v_mfma_f32_16x16x32_bf16 v[32:35], v[174:177], v[206:209], v[32:35]
	v_mfma_f32_16x16x32_bf16 v[60:63], v[170:173], v[186:189], v[60:63]
	v_mfma_f32_16x16x32_bf16 v[56:59], v[178:181], v[186:189], v[56:59]
	v_mfma_f32_16x16x32_bf16 v[52:55], v[170:173], v[194:197], v[52:55]
	v_mfma_f32_16x16x32_bf16 v[48:51], v[178:181], v[194:197], v[48:51]
	v_mfma_f32_16x16x32_bf16 v[44:47], v[170:173], v[202:205], v[44:47]
	s_setprio 2
	s_barrier
	v_mfma_f32_16x16x32_bf16 v[40:43], v[178:181], v[202:205], v[40:43]
	v_mfma_f32_16x16x32_bf16 v[36:39], v[170:173], v[210:213], v[36:39]
	v_mfma_f32_16x16x32_bf16 v[32:35], v[178:181], v[210:213], v[32:35]
	s_setprio 0
	s_add_i32 s52, s93, s3
	v_lshl_add_u64 v[214:215], s[78:79], 0, v[138:139]
	s_mov_b32 m0, s52
	ds_read_b128 v[182:185], v232 offset:16384
	ds_read_b128 v[186:189], v232 offset:17408
	ds_read_b128 v[190:193], v232 offset:18432
	ds_read_b128 v[194:197], v232 offset:19456
	ds_read_b128 v[198:201], v232 offset:20480
	ds_read_b128 v[202:205], v232 offset:21504
	ds_read_b128 v[206:209], v232 offset:22528
	ds_read_b128 v[210:213], v232 offset:23552
	global_load_lds_dwordx4 v[214:215], off
	s_add_i32 m0, s52, 0x2000
	s_add_u32 s52, s78, 0x80000
	v_lshl_add_u64 v[216:217], s[78:79], 0, v[142:143]
	s_addc_u32 s53, s79, 0
	s_add_i32 s56, s10, s3
	global_load_lds_dwordx4 v[216:217], off
	v_lshl_add_u64 v[218:219], s[52:53], 0, v[138:139]
	s_mov_b32 m0, s56
	v_lshl_add_u64 v[220:221], s[80:81], 0, v[140:141]
	global_load_lds_dwordx4 v[218:219], off
	v_lshl_add_u64 v[218:219], s[52:53], 0, v[142:143]
	s_add_i32 m0, s56, 0x2000
	s_nop 0
	global_load_lds_dwordx4 v[218:219], off
	v_lshl_add_u64 v[218:219], s[80:81], 0, v[136:137]
	s_mov_b32 m0, s28
	s_nop 0
	global_load_lds_dwordx4 v[218:219], off
	s_mov_b32 m0, s29
	s_nop 0
	global_load_lds_dwordx4 v[220:221], off
	s_waitcnt vmcnt(8)
	s_waitcnt lgkmcnt(0)
	s_setprio 1
	s_barrier
; #define PG8_STAGE(bufoff, gbase, voff) do { _Pragma("unroll") for (int _i = 0; _i < 2; ++_i) \
;         __builtin_amdgcn_global_load_lds((const unsigned*)((const char*)(gbase) + (voff)[_i]), (PG8_LAS unsigned*)(lds + (bufoff) + ldsw + _i * 8192), 16, 0, 0); } while (0)
; #define PG8_LDA(dst, b, h) do { _Pragma("unroll") for (int m = 0; m < 4; ++m) _Pragma("unroll") for (int k = 0; k < 2; ++k) dst[m][k] = *(const PG8_LAS bf16x8*)(lds + PG8_SA(b, h) + aoff + m * 2048 + k * 1024); } while (0)
; #define PG8_LDB(dst, b, h) do { _Pragma("unroll") for (int n = 0; n < 2; ++n) _Pragma("unroll") for (int k = 0; k < 2; ++k) dst[n][k] = *(const PG8_LAS bf16x8*)(lds + PG8_SB(b, h) + boff + n * 2048 + k * 1024); } while (0)
; #define PG8_MMA(ai, bj, At, Bt) do { __builtin_amdgcn_s_setprio(1); _Pragma("unroll") for (int m = 0; m < 4; ++m) _Pragma("unroll") for (int n = 0; n < 2; ++n) _Pragma("unroll") for (int k = 0; k < 2; ++k) \
;         acc[ai][bj][m][n] = __builtin_amdgcn_mfma_f32_16x16x32_bf16(Bt[n][k], At[m][k], acc[ai][bj][m][n], 0, 0, 0); __builtin_amdgcn_s_setprio(0); } while (0)
; #define PG8_WAIT_V(n) asm volatile("s_waitcnt vmcnt(" #n ")" ::: "memory")
; #define PG8_WAIT_L(n) asm volatile("s_waitcnt lgkmcnt(" #n ")" ::: "memory")
; #define PG8_BAR __builtin_amdgcn_s_barrier()
; #define PG8_SCHED __builtin_amdgcn_sched_barrier(0)
; template <class Epi, class Sched, bool ALIGN_EPI = false, bool SP2 = false>
; __device__ __forceinline__ void gemm_phase(PG8_LAS unsigned char* lds, const Gemm g, const Sched& S, const Epi& E) {
;     ...
;             PG8_WAIT_V(8); PG8_WAIT_L(0); PG8_BAR; PG8_MMA(1, 0, At, B0); PG8_MMA(1, 1, At, B1); PG8_BAR; PG8_SCHED;
;             PG8_LDB(B0, 1, 0); PG8_LDB(B1, 1, 1); PG8_SCHED; PG8_LDA(At, 1, 0); PG8_STAGE(PG8_SA(0, 1), a2 + hstep, voffA);
;             PG8_WAIT_V(8); PG8_WAIT_L(0); PG8_BAR; PG8_MMA(0, 0, At, B0); PG8_MMA(0, 1, At, B1); PG8_BAR; PG8_SCHED;
	v_mfma_f32_16x16x32_bf16 v[92:95], v[128:131], v[182:185], v[92:95]
	v_mfma_f32_16x16x32_bf16 v[88:91], v[158:161], v[182:185], v[88:91]
	v_mfma_f32_16x16x32_bf16 v[84:87], v[128:131], v[190:193], v[84:87]
	v_mfma_f32_16x16x32_bf16 v[80:83], v[158:161], v[190:193], v[80:83]
	v_mfma_f32_16x16x32_bf16 v[76:79], v[128:131], v[198:201], v[76:79]
	v_mfma_f32_16x16x32_bf16 v[72:75], v[158:161], v[198:201], v[72:75]
	v_mfma_f32_16x16x32_bf16 v[68:71], v[128:131], v[206:209], v[68:71]
	v_mfma_f32_16x16x32_bf16 v[64:67], v[158:161], v[206:209], v[64:67]
	v_mfma_f32_16x16x32_bf16 v[92:95], v[132:135], v[186:189], v[92:95]
	v_mfma_f32_16x16x32_bf16 v[88:91], v[162:165], v[186:189], v[88:91]
	v_mfma_f32_16x16x32_bf16 v[84:87], v[132:135], v[194:197], v[84:87]
	v_mfma_f32_16x16x32_bf16 v[80:83], v[162:165], v[194:197], v[80:83]
	v_mfma_f32_16x16x32_bf16 v[76:79], v[132:135], v[202:205], v[76:79]
	v_mfma_f32_16x16x32_bf16 v[72:75], v[162:165], v[202:205], v[72:75]
	v_mfma_f32_16x16x32_bf16 v[68:71], v[132:135], v[210:213], v[68:71]
	v_mfma_f32_16x16x32_bf16 v[64:67], v[162:165], v[210:213], v[64:67]
	s_setprio 0
	s_setprio 1
	v_mfma_f32_16x16x32_bf16 v[28:31], v[166:169], v[182:185], v[28:31]
	v_mfma_f32_16x16x32_bf16 v[24:27], v[174:177], v[182:185], v[24:27]
	v_mfma_f32_16x16x32_bf16 v[20:23], v[166:169], v[190:193], v[20:23]
	v_mfma_f32_16x16x32_bf16 v[16:19], v[174:177], v[190:193], v[16:19]
	v_mfma_f32_16x16x32_bf16 v[12:15], v[166:169], v[198:201], v[12:15]
	v_mfma_f32_16x16x32_bf16 v[8:11], v[174:177], v[198:201], v[8:11]
	v_mfma_f32_16x16x32_bf16 v[4:7], v[166:169], v[206:209], v[4:7]
	v_mfma_f32_16x16x32_bf16 v[0:3], v[174:177], v[206:209], v[0:3]
	v_mfma_f32_16x16x32_bf16 v[28:31], v[170:173], v[186:189], v[28:31]
	v_mfma_f32_16x16x32_bf16 v[24:27], v[178:181], v[186:189], v[24:27]
	v_mfma_f32_16x16x32_bf16 v[20:23], v[170:173], v[194:197], v[20:23]
	v_mfma_f32_16x16x32_bf16 v[16:19], v[178:181], v[194:197], v[16:19]
	v_mfma_f32_16x16x32_bf16 v[12:15], v[170:173], v[202:205], v[12:15]
	s_setprio 2
	s_barrier
	v_mfma_f32_16x16x32_bf16 v[8:11], v[178:181], v[202:205], v[8:11]
	v_mfma_f32_16x16x32_bf16 v[4:7], v[170:173], v[210:213], v[4:7]
	v_mfma_f32_16x16x32_bf16 v[0:3], v[178:181], v[210:213], v[0:3]
	s_setprio 0
	s_add_i32 s56, 0, 0x18000
	s_add_i32 s57, 0, 0x1c000
	v_add_u32_e32 v162, s56, v228
	v_add_u32_e32 v178, s57, v228
	ds_read_b128 v[128:131], v162
	ds_read_b128 v[132:135], v162 offset:1024
	ds_read_b128 v[158:161], v162 offset:2048
	ds_read_b128 v[162:165], v162 offset:3072
	ds_read_b128 v[166:169], v178
	ds_read_b128 v[170:173], v178 offset:1024
	ds_read_b128 v[174:177], v178 offset:2048
	ds_read_b128 v[178:181], v178 offset:3072
	s_add_u32 s52, s80, 0x80000
	s_addc_u32 s53, s81, 0
	s_mov_b32 m0, s33
	v_lshl_add_u64 v[234:235], s[52:53], 0, v[136:137]
	ds_read_b128 v[182:185], v232 offset:32768
	ds_read_b128 v[186:189], v232 offset:33792
	ds_read_b128 v[190:193], v232 offset:34816
	ds_read_b128 v[194:197], v232 offset:35840
	ds_read_b128 v[198:201], v232 offset:36864
	ds_read_b128 v[202:205], v232 offset:37888
	ds_read_b128 v[206:209], v232 offset:38912
	ds_read_b128 v[210:213], v232 offset:39936
	global_load_lds_dwordx4 v[234:235], off
	v_lshl_add_u64 v[234:235], s[52:53], 0, v[140:141]
	s_mov_b32 m0, s38
	s_nop 0
	global_load_lds_dwordx4 v[234:235], off
	s_waitcnt vmcnt(8)
	s_waitcnt lgkmcnt(0)
	s_setprio 1
	s_barrier
	v_mfma_f32_16x16x32_bf16 v[124:127], v[128:131], v[182:185], v[124:127]
	v_mfma_f32_16x16x32_bf16 v[120:123], v[158:161], v[182:185], v[120:123]
	v_mfma_f32_16x16x32_bf16 v[116:119], v[128:131], v[190:193], v[116:119]
	v_mfma_f32_16x16x32_bf16 v[112:115], v[158:161], v[190:193], v[112:115]
	v_mfma_f32_16x16x32_bf16 v[108:111], v[128:131], v[198:201], v[108:111]
	v_mfma_f32_16x16x32_bf16 v[104:107], v[158:161], v[198:201], v[104:107]
	v_mfma_f32_16x16x32_bf16 v[100:103], v[128:131], v[206:209], v[100:103]
	v_mfma_f32_16x16x32_bf16 v[96:99], v[158:161], v[206:209], v[96:99]
	v_mfma_f32_16x16x32_bf16 v[124:127], v[132:135], v[186:189], v[124:127]
	v_mfma_f32_16x16x32_bf16 v[120:123], v[162:165], v[186:189], v[120:123]
	v_mfma_f32_16x16x32_bf16 v[116:119], v[132:135], v[194:197], v[116:119]
	v_mfma_f32_16x16x32_bf16 v[112:115], v[162:165], v[194:197], v[112:115]
	v_mfma_f32_16x16x32_bf16 v[108:111], v[132:135], v[202:205], v[108:111]
	v_mfma_f32_16x16x32_bf16 v[104:107], v[162:165], v[202:205], v[104:107]
	v_mfma_f32_16x16x32_bf16 v[100:103], v[132:135], v[210:213], v[100:103]
	v_mfma_f32_16x16x32_bf16 v[96:99], v[162:165], v[210:213], v[96:99]
	s_setprio 0
	s_setprio 1
	v_mfma_f32_16x16x32_bf16 v[60:63], v[166:169], v[182:185], v[60:63]
	v_mfma_f32_16x16x32_bf16 v[56:59], v[174:177], v[182:185], v[56:59]
	v_mfma_f32_16x16x32_bf16 v[52:55], v[166:169], v[190:193], v[52:55]
	v_mfma_f32_16x16x32_bf16 v[48:51], v[174:177], v[190:193], v[48:51]
	v_mfma_f32_16x16x32_bf16 v[44:47], v[166:169], v[198:201], v[44:47]
	v_mfma_f32_16x16x32_bf16 v[40:43], v[174:177], v[198:201], v[40:43]
	v_mfma_f32_16x16x32_bf16 v[36:39], v[166:169], v[206:209], v[36:39]
	v_mfma_f32_16x16x32_bf16 v[32:35], v[174:177], v[206:209], v[32:35]
	v_mfma_f32_16x16x32_bf16 v[60:63], v[170:173], v[186:189], v[60:63]
	v_mfma_f32_16x16x32_bf16 v[56:59], v[178:181], v[186:189], v[56:59]
	v_mfma_f32_16x16x32_bf16 v[52:55], v[170:173], v[194:197], v[52:55]
	v_mfma_f32_16x16x32_bf16 v[48:51], v[178:181], v[194:197], v[48:51]
	v_mfma_f32_16x16x32_bf16 v[44:47], v[170:173], v[202:205], v[44:47]
	s_setprio 2
	s_barrier
; #define PG8_STAGE(bufoff, gbase, voff) do { _Pragma("unroll") for (int _i = 0; _i < 2; ++_i) \
;         __builtin_amdgcn_global_load_lds((const unsigned*)((const char*)(gbase) + (voff)[_i]), (PG8_LAS unsigned*)(lds + (bufoff) + ldsw + _i * 8192), 16, 0, 0); } while (0)
; #define PG8_LDA(dst, b, h) do { _Pragma("unroll") for (int m = 0; m < 4; ++m) _Pragma("unroll") for (int k = 0; k < 2; ++k) dst[m][k] = *(const PG8_LAS bf16x8*)(lds + PG8_SA(b, h) + aoff + m * 2048 + k * 1024); } while (0)
; #define PG8_MMA(ai, bj, At, Bt) do { __builtin_amdgcn_s_setprio(1); _Pragma("unroll") for (int m = 0; m < 4; ++m) _Pragma("unroll") for (int n = 0; n < 2; ++n) _Pragma("unroll") for (int k = 0; k < 2; ++k) \
;         acc[ai][bj][m][n] = __builtin_amdgcn_mfma_f32_16x16x32_bf16(Bt[n][k], At[m][k], acc[ai][bj][m][n], 0, 0, 0); __builtin_amdgcn_s_setprio(0); } while (0)
; #define PG8_WAIT_V(n) asm volatile("s_waitcnt vmcnt(" #n ")" ::: "memory")
; #define PG8_WAIT_L(n) asm volatile("s_waitcnt lgkmcnt(" #n ")" ::: "memory")
; #define PG8_BAR __builtin_amdgcn_s_barrier()
; #define PG8_SCHED __builtin_amdgcn_sched_barrier(0)
; template <class Epi, class Sched, bool ALIGN_EPI = false, bool SP2 = false>
; __device__ __forceinline__ void gemm_phase(PG8_LAS unsigned char* lds, const Gemm g, const Sched& S, const Epi& E) {
;     ...
;             PG8_WAIT_V(8); PG8_WAIT_L(0); PG8_BAR; PG8_MMA(0, 0, At, B0); PG8_MMA(0, 1, At, B1); PG8_BAR; PG8_SCHED;
;             PG8_LDA(At, 1, 1); PG8_STAGE(PG8_SB(1, 0), b3, voffB); PG8_STAGE(PG8_SB(1, 1), b3 + hstep, voffB); PG8_STAGE(PG8_SA(1, 0), a3, voffA);
;             PG8_WAIT_V(8); PG8_WAIT_L(0); PG8_BAR; PG8_MMA(1, 0, At, B0); PG8_MMA(1, 1, At, B1); PG8_BAR; PG8_SCHED;
;     ...
;         if constexpr (ALIGN_EPI) { if (wr == 0) PG8_BAR; }
	v_mfma_f32_16x16x32_bf16 v[40:43], v[178:181], v[202:205], v[40:43]
	v_mfma_f32_16x16x32_bf16 v[36:39], v[170:173], v[210:213], v[36:39]
	v_mfma_f32_16x16x32_bf16 v[32:35], v[178:181], v[210:213], v[32:35]
	s_setprio 0
	s_add_i32 s52, s56, s3
	v_lshl_add_u64 v[214:215], v[214:215], 0, s[14:15]
	s_mov_b32 m0, s52
	ds_read_b128 v[182:185], v232 offset:49152
	ds_read_b128 v[186:189], v232 offset:50176
	ds_read_b128 v[190:193], v232 offset:51200
	ds_read_b128 v[194:197], v232 offset:52224
	ds_read_b128 v[198:201], v232 offset:53248
	ds_read_b128 v[202:205], v232 offset:54272
	ds_read_b128 v[206:209], v232 offset:55296
	ds_read_b128 v[210:213], v232 offset:56320
	global_load_lds_dwordx4 v[214:215], off
	s_add_i32 m0, s52, 0x2000
	s_add_u32 s52, s78, 0x80080
	v_lshl_add_u64 v[214:215], v[216:217], 0, s[14:15]
	s_addc_u32 s53, s79, 0
	s_add_i32 s56, s57, s3
	global_load_lds_dwordx4 v[214:215], off
	v_lshl_add_u64 v[214:215], s[52:53], 0, v[138:139]
	s_mov_b32 m0, s56
	s_nop 0
	global_load_lds_dwordx4 v[214:215], off
	v_lshl_add_u64 v[214:215], s[52:53], 0, v[142:143]
	s_add_i32 m0, s56, 0x2000
	s_nop 0
	global_load_lds_dwordx4 v[214:215], off
	v_lshl_add_u64 v[214:215], v[218:219], 0, s[14:15]
	s_mov_b32 m0, s88
	s_nop 0
	global_load_lds_dwordx4 v[214:215], off
	v_lshl_add_u64 v[214:215], v[220:221], 0, s[14:15]
	s_mov_b32 m0, s89
	s_nop 0
	global_load_lds_dwordx4 v[214:215], off
	s_waitcnt vmcnt(8)
	s_waitcnt lgkmcnt(0)
	s_setprio 1
	s_barrier
	v_mfma_f32_16x16x32_bf16 v[92:95], v[128:131], v[182:185], v[92:95]
	v_mfma_f32_16x16x32_bf16 v[88:91], v[158:161], v[182:185], v[88:91]
	v_mfma_f32_16x16x32_bf16 v[84:87], v[128:131], v[190:193], v[84:87]
	v_mfma_f32_16x16x32_bf16 v[80:83], v[158:161], v[190:193], v[80:83]
	v_mfma_f32_16x16x32_bf16 v[76:79], v[128:131], v[198:201], v[76:79]
	v_mfma_f32_16x16x32_bf16 v[72:75], v[158:161], v[198:201], v[72:75]
	v_mfma_f32_16x16x32_bf16 v[68:71], v[128:131], v[206:209], v[68:71]
	v_mfma_f32_16x16x32_bf16 v[64:67], v[158:161], v[206:209], v[64:67]
	v_mfma_f32_16x16x32_bf16 v[92:95], v[132:135], v[186:189], v[92:95]
	v_mfma_f32_16x16x32_bf16 v[88:91], v[162:165], v[186:189], v[88:91]
	v_mfma_f32_16x16x32_bf16 v[84:87], v[132:135], v[194:197], v[84:87]
	v_mfma_f32_16x16x32_bf16 v[80:83], v[162:165], v[194:197], v[80:83]
	v_mfma_f32_16x16x32_bf16 v[76:79], v[132:135], v[202:205], v[76:79]
	v_mfma_f32_16x16x32_bf16 v[72:75], v[162:165], v[202:205], v[72:75]
	v_mfma_f32_16x16x32_bf16 v[68:71], v[132:135], v[210:213], v[68:71]
	v_mfma_f32_16x16x32_bf16 v[64:67], v[162:165], v[210:213], v[64:67]
	s_setprio 0
	s_setprio 1
	v_mfma_f32_16x16x32_bf16 v[28:31], v[166:169], v[182:185], v[28:31]
	v_mfma_f32_16x16x32_bf16 v[24:27], v[174:177], v[182:185], v[24:27]
	v_mfma_f32_16x16x32_bf16 v[20:23], v[166:169], v[190:193], v[20:23]
	v_mfma_f32_16x16x32_bf16 v[16:19], v[174:177], v[190:193], v[16:19]
	v_mfma_f32_16x16x32_bf16 v[12:15], v[166:169], v[198:201], v[12:15]
	v_mfma_f32_16x16x32_bf16 v[8:11], v[174:177], v[198:201], v[8:11]
	v_mfma_f32_16x16x32_bf16 v[4:7], v[166:169], v[206:209], v[4:7]
	v_mfma_f32_16x16x32_bf16 v[0:3], v[174:177], v[206:209], v[0:3]
	v_mfma_f32_16x16x32_bf16 v[28:31], v[170:173], v[186:189], v[28:31]
	v_mfma_f32_16x16x32_bf16 v[24:27], v[178:181], v[186:189], v[24:27]
	v_mfma_f32_16x16x32_bf16 v[20:23], v[170:173], v[194:197], v[20:23]
	v_mfma_f32_16x16x32_bf16 v[16:19], v[178:181], v[194:197], v[16:19]
	v_mfma_f32_16x16x32_bf16 v[12:15], v[170:173], v[202:205], v[12:15]
	s_setprio 2
	s_barrier
	v_mfma_f32_16x16x32_bf16 v[8:11], v[178:181], v[202:205], v[8:11]
	v_mfma_f32_16x16x32_bf16 v[4:7], v[170:173], v[210:213], v[4:7]
	v_mfma_f32_16x16x32_bf16 v[0:3], v[178:181], v[210:213], v[0:3]
	s_setprio 0
	s_add_i32 vcc_hi, vcc_hi, 2
	s_add_u32 s76, s76, 0x100
	s_addc_u32 s77, s77, 0
	s_add_u32 s75, s75, 0x100
	s_addc_u32 vcc_lo, vcc_lo, 0
	s_cmp_gt_u32 vcc_hi, 29
	s_cbranch_scc0 .LBB0_374
	s_and_b64 vcc, exec, s[48:49]
	s_cbranch_vccz .LBB0_377
	s_barrier

; #define PG8_STAGE(bufoff, gbase, voff) do { _Pragma("unroll") for (int _i = 0; _i < 2; ++_i) \
;         __builtin_amdgcn_global_load_lds((const unsigned*)((const char*)(gbase) + (voff)[_i]), (PG8_LAS unsigned*)(lds + (bufoff) + ldsw + _i * 8192), 16, 0, 0); } while (0)
; #define PG8_LDA(dst, b, h) do { _Pragma("unroll") for (int m = 0; m < 4; ++m) _Pragma("unroll") for (int k = 0; k < 2; ++k) dst[m][k] = *(const PG8_LAS bf16x8*)(lds + PG8_SA(b, h) + aoff + m * 2048 + k * 1024); } while (0)
; #define PG8_LDB(dst, b, h) do { _Pragma("unroll") for (int n = 0; n < 2; ++n) _Pragma("unroll") for (int k = 0; k < 2; ++k) dst[n][k] = *(const PG8_LAS bf16x8*)(lds + PG8_SB(b, h) + boff + n * 2048 + k * 1024); } while (0)
; #define PG8_MMA(ai, bj, At, Bt) do { __builtin_amdgcn_s_setprio(1); _Pragma("unroll") for (int m = 0; m < 4; ++m) _Pragma("unroll") for (int n = 0; n < 2; ++n) _Pragma("unroll") for (int k = 0; k < 2; ++k) \
;         acc[ai][bj][m][n] = __builtin_amdgcn_mfma_f32_16x16x32_bf16(Bt[n][k], At[m][k], acc[ai][bj][m][n], 0, 0, 0); __builtin_amdgcn_s_setprio(0); } while (0)
; #define PG8_WAIT_V(n) asm volatile("s_waitcnt vmcnt(" #n ")" ::: "memory")
; #define PG8_WAIT_L(n) asm volatile("s_waitcnt lgkmcnt(" #n ")" ::: "memory")
; #define PG8_BAR __builtin_amdgcn_s_barrier()
; #define PG8_SCHED __builtin_amdgcn_sched_barrier(0)
; template <class Epi, class Sched, bool ALIGN_EPI = false, bool SP2 = false>
; __device__ __forceinline__ void gemm_phase(PG8_LAS unsigned char* lds, const Gemm g, const Sched& S, const Epi& E) {
;     ...
;             const bool last = (t == nt - 2);
;             const char* a1 = cA + (size_t)(t + 1) * kstep;
;             const char* a2 = last ? nA : cA + (size_t)(t + 2) * kstep; const char* b2 = last ? nB : cB + (size_t)(t + 2) * kstep;
;             const char* a3 = a2 + kstep; const char* b3 = b2 + kstep;
;             if constexpr (SP2) {
;             PG8_LDB(B0, 0, 0); PG8_LDB(B1, 0, 1); PG8_SCHED; PG8_LDA(At, 0, 0); PG8_STAGE(PG8_SA(1, 1), a1 + hstep, voffA);
;             PG8_WAIT_V(8); PG8_WAIT_L(0); PG8_BAR; PG8_MMA(0, 0, At, B0); PG8_MMA(0, 1, At, B1); PG8_BAR; PG8_SCHED;
;             PG8_LDA(At, 0, 1); PG8_STAGE(PG8_SB(0, 0), b2, voffB); PG8_STAGE(PG8_SB(0, 1), b2 + hstep, voffB); PG8_STAGE(PG8_SA(0, 0), a2, voffA);
.LBB0_410:
	ds_read_b128 v[166:169], v145
	ds_read_b128 v[170:173], v145 offset:1024
	ds_read_b128 v[174:177], v145 offset:2048
	ds_read_b128 v[178:181], v145 offset:3072
	ds_read_b128 v[182:185], v149
	ds_read_b128 v[186:189], v149 offset:1024
	ds_read_b128 v[190:193], v149 offset:2048
	ds_read_b128 v[194:197], v149 offset:3072
	s_add_u32 s52, s74, 0xfff80080
	s_addc_u32 s53, s75, -1
	s_cmp_eq_u32 s51, 4
	s_cselect_b32 s79, s55, s53
	s_cselect_b32 s78, s54, s52
	s_cselect_b32 s77, s69, s49
	s_cselect_b32 s76, s68, s37
	s_mov_b32 m0, s80
	v_lshl_add_u64 v[230:231], s[74:75], 0, v[160:161]
	ds_read_b128 v[198:201], v164
	ds_read_b128 v[202:205], v164 offset:1024
	ds_read_b128 v[206:209], v164 offset:2048
	ds_read_b128 v[210:213], v164 offset:3072
	ds_read_b128 v[214:217], v164 offset:4096
	ds_read_b128 v[218:221], v164 offset:5120
	ds_read_b128 v[222:225], v164 offset:6144
	ds_read_b128 v[226:229], v164 offset:7168
	global_load_lds_dwordx4 v[230:231], off
	v_lshl_add_u64 v[230:231], s[74:75], 0, v[162:163]
	s_mov_b32 m0, s81
	s_nop 0
	global_load_lds_dwordx4 v[230:231], off
	s_waitcnt vmcnt(8)
	s_waitcnt lgkmcnt(0)
	s_setprio 1
	s_barrier
	v_mfma_f32_16x16x32_bf16 v[124:127], v[166:169], v[198:201], v[124:127]
	v_mfma_f32_16x16x32_bf16 v[120:123], v[174:177], v[198:201], v[120:123]
	v_mfma_f32_16x16x32_bf16 v[116:119], v[166:169], v[206:209], v[116:119]
	v_mfma_f32_16x16x32_bf16 v[108:111], v[174:177], v[206:209], v[108:111]
	v_mfma_f32_16x16x32_bf16 v[100:103], v[166:169], v[214:217], v[100:103]
	v_mfma_f32_16x16x32_bf16 v[92:95], v[174:177], v[214:217], v[92:95]
	v_mfma_f32_16x16x32_bf16 v[84:87], v[166:169], v[222:225], v[84:87]
	v_mfma_f32_16x16x32_bf16 v[76:79], v[174:177], v[222:225], v[76:79]
	v_mfma_f32_16x16x32_bf16 v[124:127], v[170:173], v[202:205], v[124:127]
	v_mfma_f32_16x16x32_bf16 v[120:123], v[178:181], v[202:205], v[120:123]
	v_mfma_f32_16x16x32_bf16 v[116:119], v[170:173], v[210:213], v[116:119]
	v_mfma_f32_16x16x32_bf16 v[108:111], v[178:181], v[210:213], v[108:111]
	v_mfma_f32_16x16x32_bf16 v[100:103], v[170:173], v[218:221], v[100:103]
	v_mfma_f32_16x16x32_bf16 v[92:95], v[178:181], v[218:221], v[92:95]
	v_mfma_f32_16x16x32_bf16 v[84:87], v[170:173], v[226:229], v[84:87]
	v_mfma_f32_16x16x32_bf16 v[76:79], v[178:181], v[226:229], v[76:79]
	s_setprio 0
	s_setprio 1
	v_mfma_f32_16x16x32_bf16 v[112:115], v[182:185], v[198:201], v[112:115]
	v_mfma_f32_16x16x32_bf16 v[104:107], v[190:193], v[198:201], v[104:107]
	v_mfma_f32_16x16x32_bf16 v[96:99], v[182:185], v[206:209], v[96:99]
	v_mfma_f32_16x16x32_bf16 v[88:91], v[190:193], v[206:209], v[88:91]
	v_mfma_f32_16x16x32_bf16 v[80:83], v[182:185], v[214:217], v[80:83]
	v_mfma_f32_16x16x32_bf16 v[72:75], v[190:193], v[214:217], v[72:75]
	v_mfma_f32_16x16x32_bf16 v[68:71], v[182:185], v[222:225], v[68:71]
	v_mfma_f32_16x16x32_bf16 v[64:67], v[190:193], v[222:225], v[64:67]
	v_mfma_f32_16x16x32_bf16 v[112:115], v[186:189], v[202:205], v[112:115]
	v_mfma_f32_16x16x32_bf16 v[104:107], v[194:197], v[202:205], v[104:107]
	v_mfma_f32_16x16x32_bf16 v[96:99], v[186:189], v[210:213], v[96:99]
	v_mfma_f32_16x16x32_bf16 v[88:91], v[194:197], v[210:213], v[88:91]
	v_mfma_f32_16x16x32_bf16 v[80:83], v[186:189], v[218:221], v[80:83]
	s_setprio 2
	s_barrier
	v_mfma_f32_16x16x32_bf16 v[72:75], v[194:197], v[218:221], v[72:75]
	v_mfma_f32_16x16x32_bf16 v[68:71], v[186:189], v[226:229], v[68:71]
	v_mfma_f32_16x16x32_bf16 v[64:67], v[194:197], v[226:229], v[64:67]
	s_setprio 0
	s_mov_b32 m0, s84
	v_lshl_add_u64 v[230:231], s[76:77], 0, v[138:139]
	s_add_u32 s52, s76, 0x80000
	ds_read_b128 v[198:201], v164 offset:16384
	ds_read_b128 v[202:205], v164 offset:17408
	ds_read_b128 v[206:209], v164 offset:18432
	ds_read_b128 v[210:213], v164 offset:19456
	ds_read_b128 v[214:217], v164 offset:20480
	ds_read_b128 v[218:221], v164 offset:21504
	ds_read_b128 v[222:225], v164 offset:22528
	ds_read_b128 v[226:229], v164 offset:23552
	global_load_lds_dwordx4 v[230:231], off
	v_lshl_add_u64 v[232:233], s[76:77], 0, v[142:143]
	s_mov_b32 m0, s85
	s_addc_u32 s53, s77, 0
	global_load_lds_dwordx4 v[232:233], off
	v_lshl_add_u64 v[234:235], s[52:53], 0, v[138:139]
	s_mov_b32 m0, s86
	v_lshl_add_u64 v[236:237], s[78:79], 0, v[140:141]
	global_load_lds_dwordx4 v[234:235], off
	v_lshl_add_u64 v[234:235], s[52:53], 0, v[142:143]
	s_mov_b32 m0, s87
	s_nop 0
	global_load_lds_dwordx4 v[234:235], off
	v_lshl_add_u64 v[234:235], s[78:79], 0, v[136:137]
	s_mov_b32 m0, s10
	s_nop 0
	global_load_lds_dwordx4 v[234:235], off
	s_mov_b32 m0, s11
	s_nop 0
	global_load_lds_dwordx4 v[236:237], off
	s_waitcnt vmcnt(8)
	s_waitcnt lgkmcnt(0)
	s_setprio 1
	s_barrier
; #define PG8_STAGE(bufoff, gbase, voff) do { _Pragma("unroll") for (int _i = 0; _i < 2; ++_i) \
;         __builtin_amdgcn_global_load_lds((const unsigned*)((const char*)(gbase) + (voff)[_i]), (PG8_LAS unsigned*)(lds + (bufoff) + ldsw + _i * 8192), 16, 0, 0); } while (0)
; #define PG8_LDA(dst, b, h) do { _Pragma("unroll") for (int m = 0; m < 4; ++m) _Pragma("unroll") for (int k = 0; k < 2; ++k) dst[m][k] = *(const PG8_LAS bf16x8*)(lds + PG8_SA(b, h) + aoff + m * 2048 + k * 1024); } while (0)
; #define PG8_LDB(dst, b, h) do { _Pragma("unroll") for (int n = 0; n < 2; ++n) _Pragma("unroll") for (int k = 0; k < 2; ++k) dst[n][k] = *(const PG8_LAS bf16x8*)(lds + PG8_SB(b, h) + boff + n * 2048 + k * 1024); } while (0)
; #define PG8_MMA(ai, bj, At, Bt) do { __builtin_amdgcn_s_setprio(1); _Pragma("unroll") for (int m = 0; m < 4; ++m) _Pragma("unroll") for (int n = 0; n < 2; ++n) _Pragma("unroll") for (int k = 0; k < 2; ++k) \
;         acc[ai][bj][m][n] = __builtin_amdgcn_mfma_f32_16x16x32_bf16(Bt[n][k], At[m][k], acc[ai][bj][m][n], 0, 0, 0); __builtin_amdgcn_s_setprio(0); } while (0)
; #define PG8_WAIT_V(n) asm volatile("s_waitcnt vmcnt(" #n ")" ::: "memory")
; #define PG8_WAIT_L(n) asm volatile("s_waitcnt lgkmcnt(" #n ")" ::: "memory")
; #define PG8_BAR __builtin_amdgcn_s_barrier()
; #define PG8_SCHED __builtin_amdgcn_sched_barrier(0)
; template <class Epi, class Sched, bool ALIGN_EPI = false, bool SP2 = false>
; __device__ __forceinline__ void gemm_phase(PG8_LAS unsigned char* lds, const Gemm g, const Sched& S, const Epi& E) {
;     ...
;             PG8_WAIT_V(8); PG8_WAIT_L(0); PG8_BAR; PG8_MMA(1, 0, At, B0); PG8_MMA(1, 1, At, B1); PG8_BAR; PG8_SCHED;
;             PG8_LDB(B0, 1, 0); PG8_LDB(B1, 1, 1); PG8_SCHED; PG8_LDA(At, 1, 0); PG8_STAGE(PG8_SA(0, 1), a2 + hstep, voffA);
;             PG8_WAIT_V(8); PG8_WAIT_L(0); PG8_BAR; PG8_MMA(0, 0, At, B0); PG8_MMA(0, 1, At, B1); PG8_BAR; PG8_SCHED;
	v_mfma_f32_16x16x32_bf16 v[60:63], v[166:169], v[198:201], v[60:63]
	v_mfma_f32_16x16x32_bf16 v[56:59], v[174:177], v[198:201], v[56:59]
	v_mfma_f32_16x16x32_bf16 v[52:55], v[166:169], v[206:209], v[52:55]
	v_mfma_f32_16x16x32_bf16 v[44:47], v[174:177], v[206:209], v[44:47]
	v_mfma_f32_16x16x32_bf16 v[36:39], v[166:169], v[214:217], v[36:39]
	v_mfma_f32_16x16x32_bf16 v[28:31], v[174:177], v[214:217], v[28:31]
	v_mfma_f32_16x16x32_bf16 v[20:23], v[166:169], v[222:225], v[20:23]
	v_mfma_f32_16x16x32_bf16 v[12:15], v[174:177], v[222:225], v[12:15]
	v_mfma_f32_16x16x32_bf16 v[60:63], v[170:173], v[202:205], v[60:63]
	v_mfma_f32_16x16x32_bf16 v[56:59], v[178:181], v[202:205], v[56:59]
	v_mfma_f32_16x16x32_bf16 v[52:55], v[170:173], v[210:213], v[52:55]
	v_mfma_f32_16x16x32_bf16 v[44:47], v[178:181], v[210:213], v[44:47]
	v_mfma_f32_16x16x32_bf16 v[36:39], v[170:173], v[218:221], v[36:39]
	v_mfma_f32_16x16x32_bf16 v[28:31], v[178:181], v[218:221], v[28:31]
	v_mfma_f32_16x16x32_bf16 v[20:23], v[170:173], v[226:229], v[20:23]
	v_mfma_f32_16x16x32_bf16 v[12:15], v[178:181], v[226:229], v[12:15]
	s_setprio 0
	s_setprio 1
	v_mfma_f32_16x16x32_bf16 v[48:51], v[182:185], v[198:201], v[48:51]
	v_mfma_f32_16x16x32_bf16 v[40:43], v[190:193], v[198:201], v[40:43]
	v_mfma_f32_16x16x32_bf16 v[32:35], v[182:185], v[206:209], v[32:35]
	v_mfma_f32_16x16x32_bf16 v[24:27], v[190:193], v[206:209], v[24:27]
	v_mfma_f32_16x16x32_bf16 v[16:19], v[182:185], v[214:217], v[16:19]
	v_mfma_f32_16x16x32_bf16 v[8:11], v[190:193], v[214:217], v[8:11]
	v_mfma_f32_16x16x32_bf16 v[4:7], v[182:185], v[222:225], v[4:7]
	v_mfma_f32_16x16x32_bf16 v[0:3], v[190:193], v[222:225], v[0:3]
	v_mfma_f32_16x16x32_bf16 v[48:51], v[186:189], v[202:205], v[48:51]
	v_mfma_f32_16x16x32_bf16 v[40:43], v[194:197], v[202:205], v[40:43]
	v_mfma_f32_16x16x32_bf16 v[32:35], v[186:189], v[210:213], v[32:35]
	v_mfma_f32_16x16x32_bf16 v[24:27], v[194:197], v[210:213], v[24:27]
	v_mfma_f32_16x16x32_bf16 v[16:19], v[186:189], v[218:221], v[16:19]
	s_setprio 2
	s_barrier
	v_mfma_f32_16x16x32_bf16 v[8:11], v[194:197], v[218:221], v[8:11]
	v_mfma_f32_16x16x32_bf16 v[4:7], v[186:189], v[226:229], v[4:7]
	v_mfma_f32_16x16x32_bf16 v[0:3], v[194:197], v[226:229], v[0:3]
	s_setprio 0
	ds_read_b128 v[166:169], v148
	ds_read_b128 v[170:173], v148 offset:1024
	ds_read_b128 v[174:177], v148 offset:2048
	ds_read_b128 v[178:181], v148 offset:3072
	ds_read_b128 v[182:185], v165
	ds_read_b128 v[186:189], v165 offset:1024
	ds_read_b128 v[190:193], v165 offset:2048
	ds_read_b128 v[194:197], v165 offset:3072
	s_add_u32 s52, s78, 0x80000
	s_addc_u32 s53, s79, 0
	s_mov_b32 m0, s28
	v_lshl_add_u64 v[238:239], s[52:53], 0, v[136:137]
	ds_read_b128 v[198:201], v164 offset:32768
	ds_read_b128 v[202:205], v164 offset:33792
	ds_read_b128 v[206:209], v164 offset:34816
	ds_read_b128 v[210:213], v164 offset:35840
	ds_read_b128 v[214:217], v164 offset:36864
	ds_read_b128 v[218:221], v164 offset:37888
	ds_read_b128 v[222:225], v164 offset:38912
	ds_read_b128 v[226:229], v164 offset:39936
	global_load_lds_dwordx4 v[238:239], off
	v_lshl_add_u64 v[238:239], s[52:53], 0, v[140:141]
	s_mov_b32 m0, s29
	s_nop 0
	global_load_lds_dwordx4 v[238:239], off
	s_waitcnt vmcnt(8)
	s_waitcnt lgkmcnt(0)
	s_setprio 1
	s_barrier
	v_mfma_f32_16x16x32_bf16 v[124:127], v[166:169], v[198:201], v[124:127]
	v_mfma_f32_16x16x32_bf16 v[120:123], v[174:177], v[198:201], v[120:123]
	v_mfma_f32_16x16x32_bf16 v[116:119], v[166:169], v[206:209], v[116:119]
	v_mfma_f32_16x16x32_bf16 v[108:111], v[174:177], v[206:209], v[108:111]
	v_mfma_f32_16x16x32_bf16 v[100:103], v[166:169], v[214:217], v[100:103]
	v_mfma_f32_16x16x32_bf16 v[92:95], v[174:177], v[214:217], v[92:95]
	v_mfma_f32_16x16x32_bf16 v[84:87], v[166:169], v[222:225], v[84:87]
	v_mfma_f32_16x16x32_bf16 v[76:79], v[174:177], v[222:225], v[76:79]
	v_mfma_f32_16x16x32_bf16 v[124:127], v[170:173], v[202:205], v[124:127]
	v_mfma_f32_16x16x32_bf16 v[120:123], v[178:181], v[202:205], v[120:123]
	v_mfma_f32_16x16x32_bf16 v[116:119], v[170:173], v[210:213], v[116:119]
	v_mfma_f32_16x16x32_bf16 v[108:111], v[178:181], v[210:213], v[108:111]
	v_mfma_f32_16x16x32_bf16 v[100:103], v[170:173], v[218:221], v[100:103]
	v_mfma_f32_16x16x32_bf16 v[92:95], v[178:181], v[218:221], v[92:95]
	v_mfma_f32_16x16x32_bf16 v[84:87], v[170:173], v[226:229], v[84:87]
	v_mfma_f32_16x16x32_bf16 v[76:79], v[178:181], v[226:229], v[76:79]
	s_setprio 0
	s_setprio 1
	v_mfma_f32_16x16x32_bf16 v[112:115], v[182:185], v[198:201], v[112:115]
	v_mfma_f32_16x16x32_bf16 v[104:107], v[190:193], v[198:201], v[104:107]
	v_mfma_f32_16x16x32_bf16 v[96:99], v[182:185], v[206:209], v[96:99]
	v_mfma_f32_16x16x32_bf16 v[88:91], v[190:193], v[206:209], v[88:91]
	v_mfma_f32_16x16x32_bf16 v[80:83], v[182:185], v[214:217], v[80:83]
	v_mfma_f32_16x16x32_bf16 v[72:75], v[190:193], v[214:217], v[72:75]
	v_mfma_f32_16x16x32_bf16 v[68:71], v[182:185], v[222:225], v[68:71]
	v_mfma_f32_16x16x32_bf16 v[64:67], v[190:193], v[222:225], v[64:67]
	v_mfma_f32_16x16x32_bf16 v[112:115], v[186:189], v[202:205], v[112:115]
	v_mfma_f32_16x16x32_bf16 v[104:107], v[194:197], v[202:205], v[104:107]
	v_mfma_f32_16x16x32_bf16 v[96:99], v[186:189], v[210:213], v[96:99]
	v_mfma_f32_16x16x32_bf16 v[88:91], v[194:197], v[210:213], v[88:91]
	v_mfma_f32_16x16x32_bf16 v[80:83], v[186:189], v[218:221], v[80:83]
	s_setprio 2
	s_barrier
; #define PG8_STAGE(bufoff, gbase, voff) do { _Pragma("unroll") for (int _i = 0; _i < 2; ++_i) \
;         __builtin_amdgcn_global_load_lds((const unsigned*)((const char*)(gbase) + (voff)[_i]), (PG8_LAS unsigned*)(lds + (bufoff) + ldsw + _i * 8192), 16, 0, 0); } while (0)
; #define PG8_LDA(dst, b, h) do { _Pragma("unroll") for (int m = 0; m < 4; ++m) _Pragma("unroll") for (int k = 0; k < 2; ++k) dst[m][k] = *(const PG8_LAS bf16x8*)(lds + PG8_SA(b, h) + aoff + m * 2048 + k * 1024); } while (0)
; #define PG8_MMA(ai, bj, At, Bt) do { __builtin_amdgcn_s_setprio(1); _Pragma("unroll") for (int m = 0; m < 4; ++m) _Pragma("unroll") for (int n = 0; n < 2; ++n) _Pragma("unroll") for (int k = 0; k < 2; ++k) \
;         acc[ai][bj][m][n] = __builtin_amdgcn_mfma_f32_16x16x32_bf16(Bt[n][k], At[m][k], acc[ai][bj][m][n], 0, 0, 0); __builtin_amdgcn_s_setprio(0); } while (0)
; #define PG8_WAIT_V(n) asm volatile("s_waitcnt vmcnt(" #n ")" ::: "memory")
; #define PG8_WAIT_L(n) asm volatile("s_waitcnt lgkmcnt(" #n ")" ::: "memory")
; #define PG8_BAR __builtin_amdgcn_s_barrier()
; #define PG8_SCHED __builtin_amdgcn_sched_barrier(0)
; template <class Epi, class Sched, bool ALIGN_EPI = false, bool SP2 = false>
; __device__ __forceinline__ void gemm_phase(PG8_LAS unsigned char* lds, const Gemm g, const Sched& S, const Epi& E) {
;     ...
;             PG8_WAIT_V(8); PG8_WAIT_L(0); PG8_BAR; PG8_MMA(0, 0, At, B0); PG8_MMA(0, 1, At, B1); PG8_BAR; PG8_SCHED;
;             PG8_LDA(At, 1, 1); PG8_STAGE(PG8_SB(1, 0), b3, voffB); PG8_STAGE(PG8_SB(1, 1), b3 + hstep, voffB); PG8_STAGE(PG8_SA(1, 0), a3, voffA);
;             PG8_WAIT_V(8); PG8_WAIT_L(0); PG8_BAR; PG8_MMA(1, 0, At, B0); PG8_MMA(1, 1, At, B1); PG8_BAR; PG8_SCHED;
;     ...
;         if constexpr (ALIGN_EPI) { if (wr == 0) PG8_BAR; }
	v_mfma_f32_16x16x32_bf16 v[72:75], v[194:197], v[218:221], v[72:75]
	v_mfma_f32_16x16x32_bf16 v[68:71], v[186:189], v[226:229], v[68:71]
	v_mfma_f32_16x16x32_bf16 v[64:67], v[194:197], v[226:229], v[64:67]
	s_setprio 0
	s_mov_b32 m0, s89
	v_lshl_add_u64 v[230:231], v[230:231], 0, s[12:13]
	ds_read_b128 v[198:201], v164 offset:49152
	ds_read_b128 v[202:205], v164 offset:50176
	ds_read_b128 v[206:209], v164 offset:51200
	ds_read_b128 v[210:213], v164 offset:52224
	ds_read_b128 v[214:217], v164 offset:53248
	ds_read_b128 v[218:221], v164 offset:54272
	ds_read_b128 v[222:225], v164 offset:55296
	ds_read_b128 v[226:229], v164 offset:56320
	global_load_lds_dwordx4 v[230:231], off
	s_add_i32 m0, s89, 0x2000
	s_add_u32 s52, s76, 0x80080
	v_lshl_add_u64 v[230:231], v[232:233], 0, s[12:13]
	s_addc_u32 s53, s77, 0
	s_add_i32 s56, s88, s3
	global_load_lds_dwordx4 v[230:231], off
	v_lshl_add_u64 v[230:231], s[52:53], 0, v[138:139]
	s_mov_b32 m0, s56
	s_nop 0
	global_load_lds_dwordx4 v[230:231], off
	v_lshl_add_u64 v[230:231], s[52:53], 0, v[142:143]
	s_add_i32 m0, s56, 0x2000
	s_nop 0
	global_load_lds_dwordx4 v[230:231], off
	v_lshl_add_u64 v[230:231], v[234:235], 0, s[12:13]
	s_mov_b32 m0, s38
	s_nop 0
	global_load_lds_dwordx4 v[230:231], off
	v_lshl_add_u64 v[230:231], v[236:237], 0, s[12:13]
	s_mov_b32 m0, s39
	s_nop 0
	global_load_lds_dwordx4 v[230:231], off
	s_waitcnt vmcnt(8)
	s_waitcnt lgkmcnt(0)
	s_setprio 1
	s_barrier
	v_mfma_f32_16x16x32_bf16 v[60:63], v[166:169], v[198:201], v[60:63]
	v_mfma_f32_16x16x32_bf16 v[56:59], v[174:177], v[198:201], v[56:59]
	v_mfma_f32_16x16x32_bf16 v[52:55], v[166:169], v[206:209], v[52:55]
	v_mfma_f32_16x16x32_bf16 v[44:47], v[174:177], v[206:209], v[44:47]
	v_mfma_f32_16x16x32_bf16 v[36:39], v[166:169], v[214:217], v[36:39]
	v_mfma_f32_16x16x32_bf16 v[28:31], v[174:177], v[214:217], v[28:31]
	v_mfma_f32_16x16x32_bf16 v[20:23], v[166:169], v[222:225], v[20:23]
	v_mfma_f32_16x16x32_bf16 v[12:15], v[174:177], v[222:225], v[12:15]
	v_mfma_f32_16x16x32_bf16 v[60:63], v[170:173], v[202:205], v[60:63]
	v_mfma_f32_16x16x32_bf16 v[56:59], v[178:181], v[202:205], v[56:59]
	v_mfma_f32_16x16x32_bf16 v[52:55], v[170:173], v[210:213], v[52:55]
	v_mfma_f32_16x16x32_bf16 v[44:47], v[178:181], v[210:213], v[44:47]
	v_mfma_f32_16x16x32_bf16 v[36:39], v[170:173], v[218:221], v[36:39]
	v_mfma_f32_16x16x32_bf16 v[28:31], v[178:181], v[218:221], v[28:31]
	v_mfma_f32_16x16x32_bf16 v[20:23], v[170:173], v[226:229], v[20:23]
	v_mfma_f32_16x16x32_bf16 v[12:15], v[178:181], v[226:229], v[12:15]
	s_setprio 0
	s_setprio 1
	v_mfma_f32_16x16x32_bf16 v[48:51], v[182:185], v[198:201], v[48:51]
	v_mfma_f32_16x16x32_bf16 v[40:43], v[190:193], v[198:201], v[40:43]
	v_mfma_f32_16x16x32_bf16 v[32:35], v[182:185], v[206:209], v[32:35]
	v_mfma_f32_16x16x32_bf16 v[24:27], v[190:193], v[206:209], v[24:27]
	v_mfma_f32_16x16x32_bf16 v[16:19], v[182:185], v[214:217], v[16:19]
	v_mfma_f32_16x16x32_bf16 v[8:11], v[190:193], v[214:217], v[8:11]
	v_mfma_f32_16x16x32_bf16 v[4:7], v[182:185], v[222:225], v[4:7]
	v_mfma_f32_16x16x32_bf16 v[0:3], v[190:193], v[222:225], v[0:3]
	v_mfma_f32_16x16x32_bf16 v[48:51], v[186:189], v[202:205], v[48:51]
	v_mfma_f32_16x16x32_bf16 v[40:43], v[194:197], v[202:205], v[40:43]
	v_mfma_f32_16x16x32_bf16 v[32:35], v[186:189], v[210:213], v[32:35]
	v_mfma_f32_16x16x32_bf16 v[24:27], v[194:197], v[210:213], v[24:27]
	v_mfma_f32_16x16x32_bf16 v[16:19], v[186:189], v[218:221], v[16:19]
	s_setprio 2
	s_barrier
	v_mfma_f32_16x16x32_bf16 v[8:11], v[194:197], v[218:221], v[8:11]
	v_mfma_f32_16x16x32_bf16 v[4:7], v[186:189], v[226:229], v[4:7]
	v_mfma_f32_16x16x32_bf16 v[0:3], v[194:197], v[226:229], v[0:3]
	s_setprio 0
	s_add_i32 s51, s51, 2
	s_add_u32 s74, s74, 0x100
	s_addc_u32 s75, s75, 0
	s_add_u32 s37, s37, 0x100
	s_addc_u32 s49, s49, 0
	s_cmp_gt_u32 s51, 5
	s_cbranch_scc0 .LBB0_410
	s_and_b64 vcc, exec, s[14:15]
	s_cbranch_vccz .LBB0_413
	s_barrier

; #define PG8_STAGE(bufoff, gbase, voff) do { _Pragma("unroll") for (int _i = 0; _i < 2; ++_i) \
;         __builtin_amdgcn_global_load_lds((const unsigned*)((const char*)(gbase) + (voff)[_i]), (PG8_LAS unsigned*)(lds + (bufoff) + ldsw + _i * 8192), 16, 0, 0); } while (0)
; #define PG8_LDA(dst, b, h) do { _Pragma("unroll") for (int m = 0; m < 4; ++m) _Pragma("unroll") for (int k = 0; k < 2; ++k) dst[m][k] = *(const PG8_LAS bf16x8*)(lds + PG8_SA(b, h) + aoff + m * 2048 + k * 1024); } while (0)
; #define PG8_LDB(dst, b, h) do { _Pragma("unroll") for (int n = 0; n < 2; ++n) _Pragma("unroll") for (int k = 0; k < 2; ++k) dst[n][k] = *(const PG8_LAS bf16x8*)(lds + PG8_SB(b, h) + boff + n * 2048 + k * 1024); } while (0)
; #define PG8_MMA(ai, bj, At, Bt) do { __builtin_amdgcn_s_setprio(1); _Pragma("unroll") for (int m = 0; m < 4; ++m) _Pragma("unroll") for (int n = 0; n < 2; ++n) _Pragma("unroll") for (int k = 0; k < 2; ++k) \
;         acc[ai][bj][m][n] = __builtin_amdgcn_mfma_f32_16x16x32_bf16(Bt[n][k], At[m][k], acc[ai][bj][m][n], 0, 0, 0); __builtin_amdgcn_s_setprio(0); } while (0)
; #define PG8_WAIT_V(n) asm volatile("s_waitcnt vmcnt(" #n ")" ::: "memory")
; #define PG8_WAIT_L(n) asm volatile("s_waitcnt lgkmcnt(" #n ")" ::: "memory")
; #define PG8_BAR __builtin_amdgcn_s_barrier()
; #define PG8_SCHED __builtin_amdgcn_sched_barrier(0)
; template <class Epi, class Sched, bool ALIGN_EPI = false, bool SP2 = false>
; __device__ __forceinline__ void gemm_phase(PG8_LAS unsigned char* lds, const Gemm g, const Sched& S, const Epi& E) {
;     ...
;             const bool last = (t == nt - 2);
;             const char* a1 = cA + (size_t)(t + 1) * kstep;
;             const char* a2 = last ? nA : cA + (size_t)(t + 2) * kstep; const char* b2 = last ? nB : cB + (size_t)(t + 2) * kstep;
;             const char* a3 = a2 + kstep; const char* b3 = b2 + kstep;
;             if constexpr (SP2) {
;             PG8_LDB(B0, 0, 0); PG8_LDB(B1, 0, 1); PG8_SCHED; PG8_LDA(At, 0, 0); PG8_STAGE(PG8_SA(1, 1), a1 + hstep, voffA);
;             PG8_WAIT_V(8); PG8_WAIT_L(0); PG8_BAR; PG8_MMA(0, 0, At, B0); PG8_MMA(0, 1, At, B1); PG8_BAR; PG8_SCHED;
;             PG8_LDA(At, 0, 1); PG8_STAGE(PG8_SB(0, 0), b2, voffB); PG8_STAGE(PG8_SB(0, 1), b2 + hstep, voffB); PG8_STAGE(PG8_SA(0, 0), a2, voffA);
.LBB0_545:
	ds_read_b128 v[112:115], v174
	ds_read_b128 v[116:119], v174 offset:1024
	ds_read_b128 v[120:123], v174 offset:2048
	ds_read_b128 v[124:127], v174 offset:3072
	ds_read_b128 v[164:167], v175
	ds_read_b128 v[168:171], v175 offset:1024
	ds_read_b128 v[178:181], v175 offset:2048
	ds_read_b128 v[182:185], v175 offset:3072
	s_add_u32 s52, s68, 0xfff80080
	s_addc_u32 s53, s69, -1
	s_cmp_eq_u32 s88, 28
	s_cselect_b32 s73, s41, s53
	s_cselect_b32 s72, s84, s52
	s_cselect_b32 s71, s37, s87
	s_cselect_b32 s70, s85, s86
	v_lshl_add_u64 v[218:219], s[68:69], 0, v[156:157]
	s_add_i32 m0, s39, 0xc000
	ds_read_b128 v[186:189], v176
	ds_read_b128 v[190:193], v176 offset:1024
	ds_read_b128 v[194:197], v176 offset:2048
	ds_read_b128 v[198:201], v176 offset:3072
	ds_read_b128 v[202:205], v176 offset:4096
	ds_read_b128 v[206:209], v176 offset:5120
	ds_read_b128 v[210:213], v176 offset:6144
	ds_read_b128 v[214:217], v176 offset:7168
	global_load_lds_dwordx4 v[218:219], off
	v_lshl_add_u64 v[218:219], s[68:69], 0, v[158:159]
	s_add_i32 m0, s39, 0xe000
	s_nop 0
	global_load_lds_dwordx4 v[218:219], off
	s_waitcnt vmcnt(8)
	s_waitcnt lgkmcnt(0)
	s_setprio 1
	s_barrier
	v_mfma_f32_16x16x32_bf16 v[140:143], v[112:115], v[186:189], v[140:143]
	v_mfma_f32_16x16x32_bf16 v[136:139], v[120:123], v[186:189], v[136:139]
	v_mfma_f32_16x16x32_bf16 v[108:111], v[112:115], v[194:197], v[108:111]
	v_mfma_f32_16x16x32_bf16 v[104:107], v[120:123], v[194:197], v[104:107]
	v_mfma_f32_16x16x32_bf16 v[92:95], v[112:115], v[202:205], v[92:95]
	v_mfma_f32_16x16x32_bf16 v[88:91], v[120:123], v[202:205], v[88:91]
	v_mfma_f32_16x16x32_bf16 v[76:79], v[112:115], v[210:213], v[76:79]
	v_mfma_f32_16x16x32_bf16 v[72:75], v[120:123], v[210:213], v[72:75]
	v_mfma_f32_16x16x32_bf16 v[140:143], v[116:119], v[190:193], v[140:143]
	v_mfma_f32_16x16x32_bf16 v[136:139], v[124:127], v[190:193], v[136:139]
	v_mfma_f32_16x16x32_bf16 v[108:111], v[116:119], v[198:201], v[108:111]
	v_mfma_f32_16x16x32_bf16 v[104:107], v[124:127], v[198:201], v[104:107]
	v_mfma_f32_16x16x32_bf16 v[92:95], v[116:119], v[206:209], v[92:95]
	v_mfma_f32_16x16x32_bf16 v[88:91], v[124:127], v[206:209], v[88:91]
	v_mfma_f32_16x16x32_bf16 v[76:79], v[116:119], v[214:217], v[76:79]
	v_mfma_f32_16x16x32_bf16 v[72:75], v[124:127], v[214:217], v[72:75]
	s_setprio 0
	s_setprio 1
	v_mfma_f32_16x16x32_bf16 v[132:135], v[164:167], v[186:189], v[132:135]
	v_mfma_f32_16x16x32_bf16 v[128:131], v[178:181], v[186:189], v[128:131]
	v_mfma_f32_16x16x32_bf16 v[100:103], v[164:167], v[194:197], v[100:103]
	v_mfma_f32_16x16x32_bf16 v[96:99], v[178:181], v[194:197], v[96:99]
	v_mfma_f32_16x16x32_bf16 v[84:87], v[164:167], v[202:205], v[84:87]
	v_mfma_f32_16x16x32_bf16 v[80:83], v[178:181], v[202:205], v[80:83]
	v_mfma_f32_16x16x32_bf16 v[68:71], v[164:167], v[210:213], v[68:71]
	v_mfma_f32_16x16x32_bf16 v[64:67], v[178:181], v[210:213], v[64:67]
	v_mfma_f32_16x16x32_bf16 v[132:135], v[168:171], v[190:193], v[132:135]
	v_mfma_f32_16x16x32_bf16 v[128:131], v[182:185], v[190:193], v[128:131]
	v_mfma_f32_16x16x32_bf16 v[100:103], v[168:171], v[198:201], v[100:103]
	v_mfma_f32_16x16x32_bf16 v[96:99], v[182:185], v[198:201], v[96:99]
	v_mfma_f32_16x16x32_bf16 v[84:87], v[168:171], v[206:209], v[84:87]
	s_setprio 2
	s_barrier
	v_mfma_f32_16x16x32_bf16 v[80:83], v[182:185], v[206:209], v[80:83]
	v_mfma_f32_16x16x32_bf16 v[68:71], v[168:171], v[214:217], v[68:71]
	v_mfma_f32_16x16x32_bf16 v[64:67], v[182:185], v[214:217], v[64:67]
	s_setprio 0
	s_add_i32 s52, s81, s29
	v_lshl_add_u64 v[218:219], s[70:71], 0, v[152:153]
	s_mov_b32 m0, s52
	ds_read_b128 v[186:189], v176 offset:16384
	ds_read_b128 v[190:193], v176 offset:17408
	ds_read_b128 v[194:197], v176 offset:18432
	ds_read_b128 v[198:201], v176 offset:19456
	ds_read_b128 v[202:205], v176 offset:20480
	ds_read_b128 v[206:209], v176 offset:21504
	ds_read_b128 v[210:213], v176 offset:22528
	ds_read_b128 v[214:217], v176 offset:23552
	global_load_lds_dwordx4 v[218:219], off
	s_add_i32 m0, s52, 0x2000
	s_add_u32 s52, s70, 0x80000
	v_lshl_add_u64 v[220:221], s[70:71], 0, v[148:149]
	s_addc_u32 s53, s71, 0
	s_add_i32 s56, s82, s29
	global_load_lds_dwordx4 v[220:221], off
	v_lshl_add_u64 v[222:223], s[52:53], 0, v[152:153]
	s_mov_b32 m0, s56
	v_lshl_add_u64 v[224:225], s[72:73], 0, v[150:151]
	global_load_lds_dwordx4 v[222:223], off
	v_lshl_add_u64 v[222:223], s[52:53], 0, v[148:149]
	s_add_i32 m0, s56, 0x2000
	s_nop 0
	global_load_lds_dwordx4 v[222:223], off
	v_lshl_add_u64 v[222:223], s[72:73], 0, v[154:155]
	s_mov_b32 m0, s39
	s_nop 0
	global_load_lds_dwordx4 v[222:223], off
	s_mov_b32 m0, s55
	s_nop 0
	global_load_lds_dwordx4 v[224:225], off
	s_waitcnt vmcnt(8)
	s_waitcnt lgkmcnt(0)
	s_setprio 1
	s_barrier
; #define PG8_STAGE(bufoff, gbase, voff) do { _Pragma("unroll") for (int _i = 0; _i < 2; ++_i) \
;         __builtin_amdgcn_global_load_lds((const unsigned*)((const char*)(gbase) + (voff)[_i]), (PG8_LAS unsigned*)(lds + (bufoff) + ldsw + _i * 8192), 16, 0, 0); } while (0)
; #define PG8_LDA(dst, b, h) do { _Pragma("unroll") for (int m = 0; m < 4; ++m) _Pragma("unroll") for (int k = 0; k < 2; ++k) dst[m][k] = *(const PG8_LAS bf16x8*)(lds + PG8_SA(b, h) + aoff + m * 2048 + k * 1024); } while (0)
; #define PG8_LDB(dst, b, h) do { _Pragma("unroll") for (int n = 0; n < 2; ++n) _Pragma("unroll") for (int k = 0; k < 2; ++k) dst[n][k] = *(const PG8_LAS bf16x8*)(lds + PG8_SB(b, h) + boff + n * 2048 + k * 1024); } while (0)
; #define PG8_MMA(ai, bj, At, Bt) do { __builtin_amdgcn_s_setprio(1); _Pragma("unroll") for (int m = 0; m < 4; ++m) _Pragma("unroll") for (int n = 0; n < 2; ++n) _Pragma("unroll") for (int k = 0; k < 2; ++k) \
;         acc[ai][bj][m][n] = __builtin_amdgcn_mfma_f32_16x16x32_bf16(Bt[n][k], At[m][k], acc[ai][bj][m][n], 0, 0, 0); __builtin_amdgcn_s_setprio(0); } while (0)
; #define PG8_WAIT_V(n) asm volatile("s_waitcnt vmcnt(" #n ")" ::: "memory")
; #define PG8_WAIT_L(n) asm volatile("s_waitcnt lgkmcnt(" #n ")" ::: "memory")
; #define PG8_BAR __builtin_amdgcn_s_barrier()
; #define PG8_SCHED __builtin_amdgcn_sched_barrier(0)
; template <class Epi, class Sched, bool ALIGN_EPI = false, bool SP2 = false>
; __device__ __forceinline__ void gemm_phase(PG8_LAS unsigned char* lds, const Gemm g, const Sched& S, const Epi& E) {
;     ...
;             PG8_WAIT_V(8); PG8_WAIT_L(0); PG8_BAR; PG8_MMA(1, 0, At, B0); PG8_MMA(1, 1, At, B1); PG8_BAR; PG8_SCHED;
;             PG8_LDB(B0, 1, 0); PG8_LDB(B1, 1, 1); PG8_SCHED; PG8_LDA(At, 1, 0); PG8_STAGE(PG8_SA(0, 1), a2 + hstep, voffA);
;             PG8_WAIT_V(8); PG8_WAIT_L(0); PG8_BAR; PG8_MMA(0, 0, At, B0); PG8_MMA(0, 1, At, B1); PG8_BAR; PG8_SCHED;
	v_mfma_f32_16x16x32_bf16 v[60:63], v[112:115], v[186:189], v[60:63]
	v_mfma_f32_16x16x32_bf16 v[56:59], v[120:123], v[186:189], v[56:59]
	v_mfma_f32_16x16x32_bf16 v[44:47], v[112:115], v[194:197], v[44:47]
	v_mfma_f32_16x16x32_bf16 v[40:43], v[120:123], v[194:197], v[40:43]
	v_mfma_f32_16x16x32_bf16 v[28:31], v[112:115], v[202:205], v[28:31]
	v_mfma_f32_16x16x32_bf16 v[24:27], v[120:123], v[202:205], v[24:27]
	v_mfma_f32_16x16x32_bf16 v[12:15], v[112:115], v[210:213], v[12:15]
	v_mfma_f32_16x16x32_bf16 v[8:11], v[120:123], v[210:213], v[8:11]
	v_mfma_f32_16x16x32_bf16 v[60:63], v[116:119], v[190:193], v[60:63]
	v_mfma_f32_16x16x32_bf16 v[56:59], v[124:127], v[190:193], v[56:59]
	v_mfma_f32_16x16x32_bf16 v[44:47], v[116:119], v[198:201], v[44:47]
	v_mfma_f32_16x16x32_bf16 v[40:43], v[124:127], v[198:201], v[40:43]
	v_mfma_f32_16x16x32_bf16 v[28:31], v[116:119], v[206:209], v[28:31]
	v_mfma_f32_16x16x32_bf16 v[24:27], v[124:127], v[206:209], v[24:27]
	v_mfma_f32_16x16x32_bf16 v[12:15], v[116:119], v[214:217], v[12:15]
	v_mfma_f32_16x16x32_bf16 v[8:11], v[124:127], v[214:217], v[8:11]
	s_setprio 0
	s_setprio 1
	v_mfma_f32_16x16x32_bf16 v[52:55], v[164:167], v[186:189], v[52:55]
	v_mfma_f32_16x16x32_bf16 v[48:51], v[178:181], v[186:189], v[48:51]
	v_mfma_f32_16x16x32_bf16 v[36:39], v[164:167], v[194:197], v[36:39]
	v_mfma_f32_16x16x32_bf16 v[32:35], v[178:181], v[194:197], v[32:35]
	v_mfma_f32_16x16x32_bf16 v[20:23], v[164:167], v[202:205], v[20:23]
	v_mfma_f32_16x16x32_bf16 v[16:19], v[178:181], v[202:205], v[16:19]
	v_mfma_f32_16x16x32_bf16 v[4:7], v[164:167], v[210:213], v[4:7]
	v_mfma_f32_16x16x32_bf16 v[0:3], v[178:181], v[210:213], v[0:3]
	v_mfma_f32_16x16x32_bf16 v[52:55], v[168:171], v[190:193], v[52:55]
	v_mfma_f32_16x16x32_bf16 v[48:51], v[182:185], v[190:193], v[48:51]
	v_mfma_f32_16x16x32_bf16 v[36:39], v[168:171], v[198:201], v[36:39]
	v_mfma_f32_16x16x32_bf16 v[32:35], v[182:185], v[198:201], v[32:35]
	v_mfma_f32_16x16x32_bf16 v[20:23], v[168:171], v[206:209], v[20:23]
	s_setprio 2
	s_barrier
	v_mfma_f32_16x16x32_bf16 v[16:19], v[182:185], v[206:209], v[16:19]
	v_mfma_f32_16x16x32_bf16 v[4:7], v[168:171], v[214:217], v[4:7]
	v_mfma_f32_16x16x32_bf16 v[0:3], v[182:185], v[214:217], v[0:3]
	s_setprio 0
	s_add_i32 s56, 0, 0x18000
	s_add_i32 s57, 0, 0x1c000
	v_add_u32_e32 v124, s56, v172
	v_add_u32_e32 v177, s57, v172
	ds_read_b128 v[112:115], v124
	ds_read_b128 v[116:119], v124 offset:1024
	ds_read_b128 v[120:123], v124 offset:2048
	ds_read_b128 v[124:127], v124 offset:3072
	ds_read_b128 v[164:167], v177
	ds_read_b128 v[168:171], v177 offset:1024
	ds_read_b128 v[178:181], v177 offset:2048
	ds_read_b128 v[182:185], v177 offset:3072
	s_add_u32 s52, s72, 0x80000
	s_addc_u32 s53, s73, 0
	s_mov_b32 m0, s74
	v_lshl_add_u64 v[226:227], s[52:53], 0, v[154:155]
	ds_read_b128 v[186:189], v176 offset:32768
	ds_read_b128 v[190:193], v176 offset:33792
	ds_read_b128 v[194:197], v176 offset:34816
	ds_read_b128 v[198:201], v176 offset:35840
	ds_read_b128 v[202:205], v176 offset:36864
	ds_read_b128 v[206:209], v176 offset:37888
	ds_read_b128 v[210:213], v176 offset:38912
	ds_read_b128 v[214:217], v176 offset:39936
	global_load_lds_dwordx4 v[226:227], off
	v_lshl_add_u64 v[226:227], s[52:53], 0, v[150:151]
	s_mov_b32 m0, s75
	s_nop 0
	global_load_lds_dwordx4 v[226:227], off
	s_waitcnt vmcnt(8)
	s_waitcnt lgkmcnt(0)
	s_setprio 1
	s_barrier
	v_mfma_f32_16x16x32_bf16 v[140:143], v[112:115], v[186:189], v[140:143]
	v_mfma_f32_16x16x32_bf16 v[136:139], v[120:123], v[186:189], v[136:139]
	v_mfma_f32_16x16x32_bf16 v[108:111], v[112:115], v[194:197], v[108:111]
	v_mfma_f32_16x16x32_bf16 v[104:107], v[120:123], v[194:197], v[104:107]
	v_mfma_f32_16x16x32_bf16 v[92:95], v[112:115], v[202:205], v[92:95]
	v_mfma_f32_16x16x32_bf16 v[88:91], v[120:123], v[202:205], v[88:91]
	v_mfma_f32_16x16x32_bf16 v[76:79], v[112:115], v[210:213], v[76:79]
	v_mfma_f32_16x16x32_bf16 v[72:75], v[120:123], v[210:213], v[72:75]
	v_mfma_f32_16x16x32_bf16 v[140:143], v[116:119], v[190:193], v[140:143]
	v_mfma_f32_16x16x32_bf16 v[136:139], v[124:127], v[190:193], v[136:139]
	v_mfma_f32_16x16x32_bf16 v[108:111], v[116:119], v[198:201], v[108:111]
	v_mfma_f32_16x16x32_bf16 v[104:107], v[124:127], v[198:201], v[104:107]
	v_mfma_f32_16x16x32_bf16 v[92:95], v[116:119], v[206:209], v[92:95]
	v_mfma_f32_16x16x32_bf16 v[88:91], v[124:127], v[206:209], v[88:91]
	v_mfma_f32_16x16x32_bf16 v[76:79], v[116:119], v[214:217], v[76:79]
	v_mfma_f32_16x16x32_bf16 v[72:75], v[124:127], v[214:217], v[72:75]
	s_setprio 0
	s_setprio 1
	v_mfma_f32_16x16x32_bf16 v[132:135], v[164:167], v[186:189], v[132:135]
	v_mfma_f32_16x16x32_bf16 v[128:131], v[178:181], v[186:189], v[128:131]
	v_mfma_f32_16x16x32_bf16 v[100:103], v[164:167], v[194:197], v[100:103]
	v_mfma_f32_16x16x32_bf16 v[96:99], v[178:181], v[194:197], v[96:99]
	v_mfma_f32_16x16x32_bf16 v[84:87], v[164:167], v[202:205], v[84:87]
	v_mfma_f32_16x16x32_bf16 v[80:83], v[178:181], v[202:205], v[80:83]
	v_mfma_f32_16x16x32_bf16 v[68:71], v[164:167], v[210:213], v[68:71]
	v_mfma_f32_16x16x32_bf16 v[64:67], v[178:181], v[210:213], v[64:67]
	v_mfma_f32_16x16x32_bf16 v[132:135], v[168:171], v[190:193], v[132:135]
	v_mfma_f32_16x16x32_bf16 v[128:131], v[182:185], v[190:193], v[128:131]
	v_mfma_f32_16x16x32_bf16 v[100:103], v[168:171], v[198:201], v[100:103]
	v_mfma_f32_16x16x32_bf16 v[96:99], v[182:185], v[198:201], v[96:99]
	v_mfma_f32_16x16x32_bf16 v[84:87], v[168:171], v[206:209], v[84:87]
	s_setprio 2
	s_barrier
; #define PG8_STAGE(bufoff, gbase, voff) do { _Pragma("unroll") for (int _i = 0; _i < 2; ++_i) \
;         __builtin_amdgcn_global_load_lds((const unsigned*)((const char*)(gbase) + (voff)[_i]), (PG8_LAS unsigned*)(lds + (bufoff) + ldsw + _i * 8192), 16, 0, 0); } while (0)
; #define PG8_LDA(dst, b, h) do { _Pragma("unroll") for (int m = 0; m < 4; ++m) _Pragma("unroll") for (int k = 0; k < 2; ++k) dst[m][k] = *(const PG8_LAS bf16x8*)(lds + PG8_SA(b, h) + aoff + m * 2048 + k * 1024); } while (0)
; #define PG8_MMA(ai, bj, At, Bt) do { __builtin_amdgcn_s_setprio(1); _Pragma("unroll") for (int m = 0; m < 4; ++m) _Pragma("unroll") for (int n = 0; n < 2; ++n) _Pragma("unroll") for (int k = 0; k < 2; ++k) \
;         acc[ai][bj][m][n] = __builtin_amdgcn_mfma_f32_16x16x32_bf16(Bt[n][k], At[m][k], acc[ai][bj][m][n], 0, 0, 0); __builtin_amdgcn_s_setprio(0); } while (0)
; #define PG8_WAIT_V(n) asm volatile("s_waitcnt vmcnt(" #n ")" ::: "memory")
; #define PG8_WAIT_L(n) asm volatile("s_waitcnt lgkmcnt(" #n ")" ::: "memory")
; #define PG8_BAR __builtin_amdgcn_s_barrier()
; #define PG8_SCHED __builtin_amdgcn_sched_barrier(0)
; template <class Epi, class Sched, bool ALIGN_EPI = false, bool SP2 = false>
; __device__ __forceinline__ void gemm_phase(PG8_LAS unsigned char* lds, const Gemm g, const Sched& S, const Epi& E) {
;     ...
;             PG8_WAIT_V(8); PG8_WAIT_L(0); PG8_BAR; PG8_MMA(0, 0, At, B0); PG8_MMA(0, 1, At, B1); PG8_BAR; PG8_SCHED;
;             PG8_LDA(At, 1, 1); PG8_STAGE(PG8_SB(1, 0), b3, voffB); PG8_STAGE(PG8_SB(1, 1), b3 + hstep, voffB); PG8_STAGE(PG8_SA(1, 0), a3, voffA);
;             PG8_WAIT_V(8); PG8_WAIT_L(0); PG8_BAR; PG8_MMA(1, 0, At, B0); PG8_MMA(1, 1, At, B1); PG8_BAR; PG8_SCHED;
;     ...
;         if constexpr (ALIGN_EPI) { if (wr == 0) PG8_BAR; }
	v_mfma_f32_16x16x32_bf16 v[80:83], v[182:185], v[206:209], v[80:83]
	v_mfma_f32_16x16x32_bf16 v[68:71], v[168:171], v[214:217], v[68:71]
	v_mfma_f32_16x16x32_bf16 v[64:67], v[182:185], v[214:217], v[64:67]
	s_setprio 0
	s_add_i32 s52, s56, s29
	v_lshl_add_u64 v[218:219], v[218:219], 0, s[12:13]
	s_mov_b32 m0, s52
	ds_read_b128 v[186:189], v176 offset:49152
	ds_read_b128 v[190:193], v176 offset:50176
	ds_read_b128 v[194:197], v176 offset:51200
	ds_read_b128 v[198:201], v176 offset:52224
	ds_read_b128 v[202:205], v176 offset:53248
	ds_read_b128 v[206:209], v176 offset:54272
	ds_read_b128 v[210:213], v176 offset:55296
	ds_read_b128 v[214:217], v176 offset:56320
	global_load_lds_dwordx4 v[218:219], off
	s_add_i32 m0, s52, 0x2000
	s_add_u32 s52, s70, 0x80080
	v_lshl_add_u64 v[218:219], v[220:221], 0, s[12:13]
	s_addc_u32 s53, s71, 0
	s_add_i32 s56, s57, s29
	global_load_lds_dwordx4 v[218:219], off
	v_lshl_add_u64 v[218:219], s[52:53], 0, v[152:153]
	s_mov_b32 m0, s56
	s_nop 0
	global_load_lds_dwordx4 v[218:219], off
	v_lshl_add_u64 v[218:219], s[52:53], 0, v[148:149]
	s_add_i32 m0, s56, 0x2000
	s_nop 0
	global_load_lds_dwordx4 v[218:219], off
	v_lshl_add_u64 v[218:219], v[222:223], 0, s[12:13]
	s_mov_b32 m0, s77
	s_nop 0
	global_load_lds_dwordx4 v[218:219], off
	v_lshl_add_u64 v[218:219], v[224:225], 0, s[12:13]
	s_mov_b32 m0, s78
	s_nop 0
	global_load_lds_dwordx4 v[218:219], off
	s_waitcnt vmcnt(8)
	s_waitcnt lgkmcnt(0)
	s_setprio 1
	s_barrier
	v_mfma_f32_16x16x32_bf16 v[60:63], v[112:115], v[186:189], v[60:63]
	v_mfma_f32_16x16x32_bf16 v[56:59], v[120:123], v[186:189], v[56:59]
	v_mfma_f32_16x16x32_bf16 v[44:47], v[112:115], v[194:197], v[44:47]
	v_mfma_f32_16x16x32_bf16 v[40:43], v[120:123], v[194:197], v[40:43]
	v_mfma_f32_16x16x32_bf16 v[28:31], v[112:115], v[202:205], v[28:31]
	v_mfma_f32_16x16x32_bf16 v[24:27], v[120:123], v[202:205], v[24:27]
	v_mfma_f32_16x16x32_bf16 v[12:15], v[112:115], v[210:213], v[12:15]
	v_mfma_f32_16x16x32_bf16 v[8:11], v[120:123], v[210:213], v[8:11]
	v_mfma_f32_16x16x32_bf16 v[60:63], v[116:119], v[190:193], v[60:63]
	v_mfma_f32_16x16x32_bf16 v[56:59], v[124:127], v[190:193], v[56:59]
	v_mfma_f32_16x16x32_bf16 v[44:47], v[116:119], v[198:201], v[44:47]
	v_mfma_f32_16x16x32_bf16 v[40:43], v[124:127], v[198:201], v[40:43]
	v_mfma_f32_16x16x32_bf16 v[28:31], v[116:119], v[206:209], v[28:31]
	v_mfma_f32_16x16x32_bf16 v[24:27], v[124:127], v[206:209], v[24:27]
	v_mfma_f32_16x16x32_bf16 v[12:15], v[116:119], v[214:217], v[12:15]
	v_mfma_f32_16x16x32_bf16 v[8:11], v[124:127], v[214:217], v[8:11]
	s_setprio 0
	s_setprio 1
	v_mfma_f32_16x16x32_bf16 v[52:55], v[164:167], v[186:189], v[52:55]
	v_mfma_f32_16x16x32_bf16 v[48:51], v[178:181], v[186:189], v[48:51]
	v_mfma_f32_16x16x32_bf16 v[36:39], v[164:167], v[194:197], v[36:39]
	v_mfma_f32_16x16x32_bf16 v[32:35], v[178:181], v[194:197], v[32:35]
	v_mfma_f32_16x16x32_bf16 v[20:23], v[164:167], v[202:205], v[20:23]
	v_mfma_f32_16x16x32_bf16 v[16:19], v[178:181], v[202:205], v[16:19]
	v_mfma_f32_16x16x32_bf16 v[4:7], v[164:167], v[210:213], v[4:7]
	v_mfma_f32_16x16x32_bf16 v[0:3], v[178:181], v[210:213], v[0:3]
	v_mfma_f32_16x16x32_bf16 v[52:55], v[168:171], v[190:193], v[52:55]
	v_mfma_f32_16x16x32_bf16 v[48:51], v[182:185], v[190:193], v[48:51]
	v_mfma_f32_16x16x32_bf16 v[36:39], v[168:171], v[198:201], v[36:39]
	v_mfma_f32_16x16x32_bf16 v[32:35], v[182:185], v[198:201], v[32:35]
	v_mfma_f32_16x16x32_bf16 v[20:23], v[168:171], v[206:209], v[20:23]
	s_setprio 2
	s_barrier
	v_mfma_f32_16x16x32_bf16 v[16:19], v[182:185], v[206:209], v[16:19]
	v_mfma_f32_16x16x32_bf16 v[4:7], v[168:171], v[214:217], v[4:7]
	v_mfma_f32_16x16x32_bf16 v[0:3], v[182:185], v[214:217], v[0:3]
	s_setprio 0
	s_add_i32 s88, s88, 2
	s_add_u32 s68, s68, 0x100
	s_addc_u32 s69, s69, 0
	s_add_u32 s86, s86, 0x100
	s_addc_u32 s87, s87, 0
	s_cmp_gt_u32 s88, 29
	s_cbranch_scc0 .LBB0_545
	s_and_b64 vcc, exec, s[14:15]
	s_cbranch_vccz .LBB0_548
	s_barrier

; #define PG8_STAGE(bufoff, gbase, voff) do { _Pragma("unroll") for (int _i = 0; _i < 2; ++_i) \
;         __builtin_amdgcn_global_load_lds((const unsigned*)((const char*)(gbase) + (voff)[_i]), (PG8_LAS unsigned*)(lds + (bufoff) + ldsw + _i * 8192), 16, 0, 0); } while (0)
; #define PG8_LDA(dst, b, h) do { _Pragma("unroll") for (int m = 0; m < 4; ++m) _Pragma("unroll") for (int k = 0; k < 2; ++k) dst[m][k] = *(const PG8_LAS bf16x8*)(lds + PG8_SA(b, h) + aoff + m * 2048 + k * 1024); } while (0)
; #define PG8_LDB(dst, b, h) do { _Pragma("unroll") for (int n = 0; n < 2; ++n) _Pragma("unroll") for (int k = 0; k < 2; ++k) dst[n][k] = *(const PG8_LAS bf16x8*)(lds + PG8_SB(b, h) + boff + n * 2048 + k * 1024); } while (0)
; #define PG8_MMA(ai, bj, At, Bt) do { __builtin_amdgcn_s_setprio(1); _Pragma("unroll") for (int m = 0; m < 4; ++m) _Pragma("unroll") for (int n = 0; n < 2; ++n) _Pragma("unroll") for (int k = 0; k < 2; ++k) \
;         acc[ai][bj][m][n] = __builtin_amdgcn_mfma_f32_16x16x32_bf16(Bt[n][k], At[m][k], acc[ai][bj][m][n], 0, 0, 0); __builtin_amdgcn_s_setprio(0); } while (0)
; #define PG8_WAIT_V(n) asm volatile("s_waitcnt vmcnt(" #n ")" ::: "memory")
; #define PG8_WAIT_L(n) asm volatile("s_waitcnt lgkmcnt(" #n ")" ::: "memory")
; #define PG8_BAR __builtin_amdgcn_s_barrier()
; #define PG8_SCHED __builtin_amdgcn_sched_barrier(0)
; template <class Epi, class Sched, bool ALIGN_EPI = false, bool SP2 = false>
; __device__ __forceinline__ void gemm_phase(PG8_LAS unsigned char* lds, const Gemm g, const Sched& S, const Epi& E) {
;     ...
;             const bool last = (t == nt - 2);
;             const char* a1 = cA + (size_t)(t + 1) * kstep;
;             const char* a2 = last ? nA : cA + (size_t)(t + 2) * kstep; const char* b2 = last ? nB : cB + (size_t)(t + 2) * kstep;
;             const char* a3 = a2 + kstep; const char* b3 = b2 + kstep;
;             if constexpr (SP2) {
;             PG8_LDB(B0, 0, 0); PG8_LDB(B1, 0, 1); PG8_SCHED; PG8_LDA(At, 0, 0); PG8_STAGE(PG8_SA(1, 1), a1 + hstep, voffA);
;             PG8_WAIT_V(8); PG8_WAIT_L(0); PG8_BAR; PG8_MMA(0, 0, At, B0); PG8_MMA(0, 1, At, B1); PG8_BAR; PG8_SCHED;
;             PG8_LDA(At, 0, 1); PG8_STAGE(PG8_SB(0, 0), b2, voffB); PG8_STAGE(PG8_SB(0, 1), b2 + hstep, voffB); PG8_STAGE(PG8_SA(0, 0), a2, voffA);
.LBB0_624:
	ds_read_b128 v[128:131], v214
	ds_read_b128 v[132:135], v214 offset:1024
	ds_read_b128 v[158:161], v214 offset:2048
	ds_read_b128 v[162:165], v214 offset:3072
	ds_read_b128 v[166:169], v215
	ds_read_b128 v[170:173], v215 offset:1024
	ds_read_b128 v[174:177], v215 offset:2048
	ds_read_b128 v[178:181], v215 offset:3072
	s_add_u32 s52, s74, 0xffe00080
	s_addc_u32 s53, s75, -1
	s_cmpk_eq_i32 vcc_hi, 0x7c
	s_cselect_b32 s79, s51, s53
	s_cselect_b32 s78, s71, s52
	s_cselect_b32 s77, s49, vcc_lo
	s_cselect_b32 s76, s73, s93
	v_lshl_add_u64 v[226:227], s[74:75], 0, v[150:151]
	s_add_i32 m0, s83, 0xc000
	ds_read_b128 v[182:185], v216
	ds_read_b128 v[186:189], v216 offset:1024
	ds_read_b128 v[190:193], v216 offset:2048
	ds_read_b128 v[194:197], v216 offset:3072
	ds_read_b128 v[198:201], v216 offset:4096
	ds_read_b128 v[202:205], v216 offset:5120
	ds_read_b128 v[218:221], v216 offset:6144
	ds_read_b128 v[222:225], v216 offset:7168
	global_load_lds_dwordx4 v[226:227], off
	v_lshl_add_u64 v[226:227], s[74:75], 0, v[152:153]
	s_add_i32 m0, s83, 0xe000
	s_nop 0
	global_load_lds_dwordx4 v[226:227], off
	s_waitcnt vmcnt(8)
	s_waitcnt lgkmcnt(0)
	s_setprio 1
	s_barrier
	v_mfma_f32_16x16x32_bf16 v[124:127], v[128:131], v[182:185], v[124:127]
	v_mfma_f32_16x16x32_bf16 v[120:123], v[158:161], v[182:185], v[120:123]
	v_mfma_f32_16x16x32_bf16 v[116:119], v[128:131], v[190:193], v[116:119]
	v_mfma_f32_16x16x32_bf16 v[112:115], v[158:161], v[190:193], v[112:115]
	v_mfma_f32_16x16x32_bf16 v[108:111], v[128:131], v[198:201], v[108:111]
	v_mfma_f32_16x16x32_bf16 v[104:107], v[158:161], v[198:201], v[104:107]
	v_mfma_f32_16x16x32_bf16 v[100:103], v[128:131], v[218:221], v[100:103]
	v_mfma_f32_16x16x32_bf16 v[96:99], v[158:161], v[218:221], v[96:99]
	v_mfma_f32_16x16x32_bf16 v[124:127], v[132:135], v[186:189], v[124:127]
	v_mfma_f32_16x16x32_bf16 v[120:123], v[162:165], v[186:189], v[120:123]
	v_mfma_f32_16x16x32_bf16 v[116:119], v[132:135], v[194:197], v[116:119]
	v_mfma_f32_16x16x32_bf16 v[112:115], v[162:165], v[194:197], v[112:115]
	v_mfma_f32_16x16x32_bf16 v[108:111], v[132:135], v[202:205], v[108:111]
	v_mfma_f32_16x16x32_bf16 v[104:107], v[162:165], v[202:205], v[104:107]
	v_mfma_f32_16x16x32_bf16 v[100:103], v[132:135], v[222:225], v[100:103]
	v_mfma_f32_16x16x32_bf16 v[96:99], v[162:165], v[222:225], v[96:99]
	s_setprio 0
	s_setprio 1
	v_mfma_f32_16x16x32_bf16 v[60:63], v[166:169], v[182:185], v[60:63]
	v_mfma_f32_16x16x32_bf16 v[56:59], v[174:177], v[182:185], v[56:59]
	v_mfma_f32_16x16x32_bf16 v[52:55], v[166:169], v[190:193], v[52:55]
	v_mfma_f32_16x16x32_bf16 v[48:51], v[174:177], v[190:193], v[48:51]
	v_mfma_f32_16x16x32_bf16 v[44:47], v[166:169], v[198:201], v[44:47]
	v_mfma_f32_16x16x32_bf16 v[40:43], v[174:177], v[198:201], v[40:43]
	v_mfma_f32_16x16x32_bf16 v[36:39], v[166:169], v[218:221], v[36:39]
	v_mfma_f32_16x16x32_bf16 v[32:35], v[174:177], v[218:221], v[32:35]
	v_mfma_f32_16x16x32_bf16 v[60:63], v[170:173], v[186:189], v[60:63]
	v_mfma_f32_16x16x32_bf16 v[56:59], v[178:181], v[186:189], v[56:59]
	v_mfma_f32_16x16x32_bf16 v[52:55], v[170:173], v[194:197], v[52:55]
	v_mfma_f32_16x16x32_bf16 v[48:51], v[178:181], v[194:197], v[48:51]
	v_mfma_f32_16x16x32_bf16 v[44:47], v[170:173], v[202:205], v[44:47]
	s_setprio 2
	s_barrier
	v_mfma_f32_16x16x32_bf16 v[40:43], v[178:181], v[202:205], v[40:43]
	v_mfma_f32_16x16x32_bf16 v[36:39], v[170:173], v[222:225], v[36:39]
	v_mfma_f32_16x16x32_bf16 v[32:35], v[178:181], v[222:225], v[32:35]
	s_setprio 0
	s_add_i32 s52, s33, s82
	v_lshl_add_u64 v[226:227], s[76:77], 0, v[138:139]
	s_mov_b32 m0, s52
	ds_read_b128 v[182:185], v216 offset:16384
	ds_read_b128 v[186:189], v216 offset:17408
	ds_read_b128 v[190:193], v216 offset:18432
	ds_read_b128 v[194:197], v216 offset:19456
	ds_read_b128 v[198:201], v216 offset:20480
	ds_read_b128 v[202:205], v216 offset:21504
	ds_read_b128 v[218:221], v216 offset:22528
	ds_read_b128 v[222:225], v216 offset:23552
	global_load_lds_dwordx4 v[226:227], off
	s_add_i32 m0, s52, 0x2000
	s_add_u32 s52, s76, 0x200000
	v_lshl_add_u64 v[228:229], s[76:77], 0, v[142:143]
	s_addc_u32 s53, s77, 0
	s_add_i32 s56, s92, s82
	global_load_lds_dwordx4 v[228:229], off
	v_lshl_add_u64 v[230:231], s[52:53], 0, v[138:139]
	s_mov_b32 m0, s56
	v_lshl_add_u64 v[232:233], s[78:79], 0, v[140:141]
	global_load_lds_dwordx4 v[230:231], off
	v_lshl_add_u64 v[230:231], s[52:53], 0, v[142:143]
	s_add_i32 m0, s56, 0x2000
	s_nop 0
	global_load_lds_dwordx4 v[230:231], off
	v_lshl_add_u64 v[230:231], s[78:79], 0, v[136:137]
	s_mov_b32 m0, s83
	s_nop 0
	global_load_lds_dwordx4 v[230:231], off
	s_mov_b32 m0, s84
	s_nop 0
	global_load_lds_dwordx4 v[232:233], off
	s_waitcnt vmcnt(8)
	s_waitcnt lgkmcnt(0)
	s_setprio 1
	s_barrier
; #define PG8_STAGE(bufoff, gbase, voff) do { _Pragma("unroll") for (int _i = 0; _i < 2; ++_i) \
;         __builtin_amdgcn_global_load_lds((const unsigned*)((const char*)(gbase) + (voff)[_i]), (PG8_LAS unsigned*)(lds + (bufoff) + ldsw + _i * 8192), 16, 0, 0); } while (0)
; #define PG8_LDA(dst, b, h) do { _Pragma("unroll") for (int m = 0; m < 4; ++m) _Pragma("unroll") for (int k = 0; k < 2; ++k) dst[m][k] = *(const PG8_LAS bf16x8*)(lds + PG8_SA(b, h) + aoff + m * 2048 + k * 1024); } while (0)
; #define PG8_LDB(dst, b, h) do { _Pragma("unroll") for (int n = 0; n < 2; ++n) _Pragma("unroll") for (int k = 0; k < 2; ++k) dst[n][k] = *(const PG8_LAS bf16x8*)(lds + PG8_SB(b, h) + boff + n * 2048 + k * 1024); } while (0)
; #define PG8_MMA(ai, bj, At, Bt) do { __builtin_amdgcn_s_setprio(1); _Pragma("unroll") for (int m = 0; m < 4; ++m) _Pragma("unroll") for (int n = 0; n < 2; ++n) _Pragma("unroll") for (int k = 0; k < 2; ++k) \
;         acc[ai][bj][m][n] = __builtin_amdgcn_mfma_f32_16x16x32_bf16(Bt[n][k], At[m][k], acc[ai][bj][m][n], 0, 0, 0); __builtin_amdgcn_s_setprio(0); } while (0)
; #define PG8_WAIT_V(n) asm volatile("s_waitcnt vmcnt(" #n ")" ::: "memory")
; #define PG8_WAIT_L(n) asm volatile("s_waitcnt lgkmcnt(" #n ")" ::: "memory")
; #define PG8_BAR __builtin_amdgcn_s_barrier()
; #define PG8_SCHED __builtin_amdgcn_sched_barrier(0)
; template <class Epi, class Sched, bool ALIGN_EPI = false, bool SP2 = false>
; __device__ __forceinline__ void gemm_phase(PG8_LAS unsigned char* lds, const Gemm g, const Sched& S, const Epi& E) {
;     ...
;             PG8_WAIT_V(8); PG8_WAIT_L(0); PG8_BAR; PG8_MMA(1, 0, At, B0); PG8_MMA(1, 1, At, B1); PG8_BAR; PG8_SCHED;
;             PG8_LDB(B0, 1, 0); PG8_LDB(B1, 1, 1); PG8_SCHED; PG8_LDA(At, 1, 0); PG8_STAGE(PG8_SA(0, 1), a2 + hstep, voffA);
;             PG8_WAIT_V(8); PG8_WAIT_L(0); PG8_BAR; PG8_MMA(0, 0, At, B0); PG8_MMA(0, 1, At, B1); PG8_BAR; PG8_SCHED;
	v_mfma_f32_16x16x32_bf16 v[92:95], v[128:131], v[182:185], v[92:95]
	v_mfma_f32_16x16x32_bf16 v[88:91], v[158:161], v[182:185], v[88:91]
	v_mfma_f32_16x16x32_bf16 v[84:87], v[128:131], v[190:193], v[84:87]
	v_mfma_f32_16x16x32_bf16 v[80:83], v[158:161], v[190:193], v[80:83]
	v_mfma_f32_16x16x32_bf16 v[76:79], v[128:131], v[198:201], v[76:79]
	v_mfma_f32_16x16x32_bf16 v[72:75], v[158:161], v[198:201], v[72:75]
	v_mfma_f32_16x16x32_bf16 v[68:71], v[128:131], v[218:221], v[68:71]
	v_mfma_f32_16x16x32_bf16 v[64:67], v[158:161], v[218:221], v[64:67]
	v_mfma_f32_16x16x32_bf16 v[92:95], v[132:135], v[186:189], v[92:95]
	v_mfma_f32_16x16x32_bf16 v[88:91], v[162:165], v[186:189], v[88:91]
	v_mfma_f32_16x16x32_bf16 v[84:87], v[132:135], v[194:197], v[84:87]
	v_mfma_f32_16x16x32_bf16 v[80:83], v[162:165], v[194:197], v[80:83]
	v_mfma_f32_16x16x32_bf16 v[76:79], v[132:135], v[202:205], v[76:79]
	v_mfma_f32_16x16x32_bf16 v[72:75], v[162:165], v[202:205], v[72:75]
	v_mfma_f32_16x16x32_bf16 v[68:71], v[132:135], v[222:225], v[68:71]
	v_mfma_f32_16x16x32_bf16 v[64:67], v[162:165], v[222:225], v[64:67]
	s_setprio 0
	s_setprio 1
	v_mfma_f32_16x16x32_bf16 v[28:31], v[166:169], v[182:185], v[28:31]
	v_mfma_f32_16x16x32_bf16 v[24:27], v[174:177], v[182:185], v[24:27]
	v_mfma_f32_16x16x32_bf16 v[20:23], v[166:169], v[190:193], v[20:23]
	v_mfma_f32_16x16x32_bf16 v[16:19], v[174:177], v[190:193], v[16:19]
	v_mfma_f32_16x16x32_bf16 v[12:15], v[166:169], v[198:201], v[12:15]
	v_mfma_f32_16x16x32_bf16 v[8:11], v[174:177], v[198:201], v[8:11]
	v_mfma_f32_16x16x32_bf16 v[4:7], v[166:169], v[218:221], v[4:7]
	v_mfma_f32_16x16x32_bf16 v[0:3], v[174:177], v[218:221], v[0:3]
	v_mfma_f32_16x16x32_bf16 v[28:31], v[170:173], v[186:189], v[28:31]
	v_mfma_f32_16x16x32_bf16 v[24:27], v[178:181], v[186:189], v[24:27]
	v_mfma_f32_16x16x32_bf16 v[20:23], v[170:173], v[194:197], v[20:23]
	v_mfma_f32_16x16x32_bf16 v[16:19], v[178:181], v[194:197], v[16:19]
	v_mfma_f32_16x16x32_bf16 v[12:15], v[170:173], v[202:205], v[12:15]
	s_setprio 2
	s_barrier
	v_mfma_f32_16x16x32_bf16 v[8:11], v[178:181], v[202:205], v[8:11]
	v_mfma_f32_16x16x32_bf16 v[4:7], v[170:173], v[222:225], v[4:7]
	v_mfma_f32_16x16x32_bf16 v[0:3], v[178:181], v[222:225], v[0:3]
	s_setprio 0
	s_add_i32 s56, 0, 0x18000
	s_add_i32 s57, 0, 0x1c000
	v_add_u32_e32 v162, s56, v212
	v_add_u32_e32 v178, s57, v212
	ds_read_b128 v[128:131], v162
	ds_read_b128 v[132:135], v162 offset:1024
	ds_read_b128 v[158:161], v162 offset:2048
	ds_read_b128 v[162:165], v162 offset:3072
	ds_read_b128 v[166:169], v178
	ds_read_b128 v[170:173], v178 offset:1024
	ds_read_b128 v[174:177], v178 offset:2048
	ds_read_b128 v[178:181], v178 offset:3072
	s_add_u32 s52, s78, 0x200000
	s_addc_u32 s53, s79, 0
	s_mov_b32 m0, s85
	v_lshl_add_u64 v[234:235], s[52:53], 0, v[136:137]
	ds_read_b128 v[182:185], v216 offset:32768
	ds_read_b128 v[186:189], v216 offset:33792
	ds_read_b128 v[190:193], v216 offset:34816
	ds_read_b128 v[194:197], v216 offset:35840
	ds_read_b128 v[198:201], v216 offset:36864
	ds_read_b128 v[202:205], v216 offset:37888
	ds_read_b128 v[218:221], v216 offset:38912
	ds_read_b128 v[222:225], v216 offset:39936
	global_load_lds_dwordx4 v[234:235], off
	v_lshl_add_u64 v[234:235], s[52:53], 0, v[140:141]
	s_mov_b32 m0, s86
	s_nop 0
	global_load_lds_dwordx4 v[234:235], off
	s_waitcnt vmcnt(8)
	s_waitcnt lgkmcnt(0)
	s_setprio 1
	s_barrier
	v_mfma_f32_16x16x32_bf16 v[124:127], v[128:131], v[182:185], v[124:127]
	v_mfma_f32_16x16x32_bf16 v[120:123], v[158:161], v[182:185], v[120:123]
	v_mfma_f32_16x16x32_bf16 v[116:119], v[128:131], v[190:193], v[116:119]
	v_mfma_f32_16x16x32_bf16 v[112:115], v[158:161], v[190:193], v[112:115]
	v_mfma_f32_16x16x32_bf16 v[108:111], v[128:131], v[198:201], v[108:111]
	v_mfma_f32_16x16x32_bf16 v[104:107], v[158:161], v[198:201], v[104:107]
	v_mfma_f32_16x16x32_bf16 v[100:103], v[128:131], v[218:221], v[100:103]
	v_mfma_f32_16x16x32_bf16 v[96:99], v[158:161], v[218:221], v[96:99]
	v_mfma_f32_16x16x32_bf16 v[124:127], v[132:135], v[186:189], v[124:127]
	v_mfma_f32_16x16x32_bf16 v[120:123], v[162:165], v[186:189], v[120:123]
	v_mfma_f32_16x16x32_bf16 v[116:119], v[132:135], v[194:197], v[116:119]
	v_mfma_f32_16x16x32_bf16 v[112:115], v[162:165], v[194:197], v[112:115]
	v_mfma_f32_16x16x32_bf16 v[108:111], v[132:135], v[202:205], v[108:111]
	v_mfma_f32_16x16x32_bf16 v[104:107], v[162:165], v[202:205], v[104:107]
	v_mfma_f32_16x16x32_bf16 v[100:103], v[132:135], v[222:225], v[100:103]
	v_mfma_f32_16x16x32_bf16 v[96:99], v[162:165], v[222:225], v[96:99]
	s_setprio 0
	s_setprio 1
	v_mfma_f32_16x16x32_bf16 v[60:63], v[166:169], v[182:185], v[60:63]
	v_mfma_f32_16x16x32_bf16 v[56:59], v[174:177], v[182:185], v[56:59]
	v_mfma_f32_16x16x32_bf16 v[52:55], v[166:169], v[190:193], v[52:55]
	v_mfma_f32_16x16x32_bf16 v[48:51], v[174:177], v[190:193], v[48:51]
	v_mfma_f32_16x16x32_bf16 v[44:47], v[166:169], v[198:201], v[44:47]
	v_mfma_f32_16x16x32_bf16 v[40:43], v[174:177], v[198:201], v[40:43]
	v_mfma_f32_16x16x32_bf16 v[36:39], v[166:169], v[218:221], v[36:39]
	v_mfma_f32_16x16x32_bf16 v[32:35], v[174:177], v[218:221], v[32:35]
	v_mfma_f32_16x16x32_bf16 v[60:63], v[170:173], v[186:189], v[60:63]
	v_mfma_f32_16x16x32_bf16 v[56:59], v[178:181], v[186:189], v[56:59]
	v_mfma_f32_16x16x32_bf16 v[52:55], v[170:173], v[194:197], v[52:55]
	v_mfma_f32_16x16x32_bf16 v[48:51], v[178:181], v[194:197], v[48:51]
	v_mfma_f32_16x16x32_bf16 v[44:47], v[170:173], v[202:205], v[44:47]
	s_setprio 2
	s_barrier
; #define PG8_STAGE(bufoff, gbase, voff) do { _Pragma("unroll") for (int _i = 0; _i < 2; ++_i) \
;         __builtin_amdgcn_global_load_lds((const unsigned*)((const char*)(gbase) + (voff)[_i]), (PG8_LAS unsigned*)(lds + (bufoff) + ldsw + _i * 8192), 16, 0, 0); } while (0)
; #define PG8_LDA(dst, b, h) do { _Pragma("unroll") for (int m = 0; m < 4; ++m) _Pragma("unroll") for (int k = 0; k < 2; ++k) dst[m][k] = *(const PG8_LAS bf16x8*)(lds + PG8_SA(b, h) + aoff + m * 2048 + k * 1024); } while (0)
; #define PG8_MMA(ai, bj, At, Bt) do { __builtin_amdgcn_s_setprio(1); _Pragma("unroll") for (int m = 0; m < 4; ++m) _Pragma("unroll") for (int n = 0; n < 2; ++n) _Pragma("unroll") for (int k = 0; k < 2; ++k) \
;         acc[ai][bj][m][n] = __builtin_amdgcn_mfma_f32_16x16x32_bf16(Bt[n][k], At[m][k], acc[ai][bj][m][n], 0, 0, 0); __builtin_amdgcn_s_setprio(0); } while (0)
; #define PG8_WAIT_V(n) asm volatile("s_waitcnt vmcnt(" #n ")" ::: "memory")
; #define PG8_WAIT_L(n) asm volatile("s_waitcnt lgkmcnt(" #n ")" ::: "memory")
; #define PG8_BAR __builtin_amdgcn_s_barrier()
; #define PG8_SCHED __builtin_amdgcn_sched_barrier(0)
; template <class Epi, class Sched, bool ALIGN_EPI = false, bool SP2 = false>
; __device__ __forceinline__ void gemm_phase(PG8_LAS unsigned char* lds, const Gemm g, const Sched& S, const Epi& E) {
;     ...
;             PG8_WAIT_V(8); PG8_WAIT_L(0); PG8_BAR; PG8_MMA(0, 0, At, B0); PG8_MMA(0, 1, At, B1); PG8_BAR; PG8_SCHED;
;             PG8_LDA(At, 1, 1); PG8_STAGE(PG8_SB(1, 0), b3, voffB); PG8_STAGE(PG8_SB(1, 1), b3 + hstep, voffB); PG8_STAGE(PG8_SA(1, 0), a3, voffA);
;             PG8_WAIT_V(8); PG8_WAIT_L(0); PG8_BAR; PG8_MMA(1, 0, At, B0); PG8_MMA(1, 1, At, B1); PG8_BAR; PG8_SCHED;
;     ...
;         if constexpr (ALIGN_EPI) { if (wr == 0) PG8_BAR; }
	v_mfma_f32_16x16x32_bf16 v[40:43], v[178:181], v[202:205], v[40:43]
	v_mfma_f32_16x16x32_bf16 v[36:39], v[170:173], v[222:225], v[36:39]
	v_mfma_f32_16x16x32_bf16 v[32:35], v[178:181], v[222:225], v[32:35]
	s_setprio 0
	s_add_i32 s52, s56, s82
	v_lshl_add_u64 v[226:227], v[226:227], 0, s[36:37]
	s_mov_b32 m0, s52
	ds_read_b128 v[182:185], v216 offset:49152
	ds_read_b128 v[186:189], v216 offset:50176
	ds_read_b128 v[190:193], v216 offset:51200
	ds_read_b128 v[194:197], v216 offset:52224
	ds_read_b128 v[198:201], v216 offset:53248
	ds_read_b128 v[202:205], v216 offset:54272
	ds_read_b128 v[218:221], v216 offset:55296
	ds_read_b128 v[222:225], v216 offset:56320
	global_load_lds_dwordx4 v[226:227], off
	s_add_i32 m0, s52, 0x2000
	s_add_u32 s52, s76, 0x200080
	v_lshl_add_u64 v[226:227], v[228:229], 0, s[36:37]
	s_addc_u32 s53, s77, 0
	s_add_i32 s56, s57, s82
	global_load_lds_dwordx4 v[226:227], off
	v_lshl_add_u64 v[226:227], s[52:53], 0, v[138:139]
	s_mov_b32 m0, s56
	s_nop 0
	global_load_lds_dwordx4 v[226:227], off
	v_lshl_add_u64 v[226:227], s[52:53], 0, v[142:143]
	s_add_i32 m0, s56, 0x2000
	s_nop 0
	global_load_lds_dwordx4 v[226:227], off
	v_lshl_add_u64 v[226:227], v[230:231], 0, s[36:37]
	s_mov_b32 m0, s94
	s_nop 0
	global_load_lds_dwordx4 v[226:227], off
	v_lshl_add_u64 v[226:227], v[232:233], 0, s[36:37]
	s_mov_b32 m0, s95
	s_nop 0
	global_load_lds_dwordx4 v[226:227], off
	s_waitcnt vmcnt(8)
	s_waitcnt lgkmcnt(0)
	s_setprio 1
	s_barrier
	v_mfma_f32_16x16x32_bf16 v[92:95], v[128:131], v[182:185], v[92:95]
	v_mfma_f32_16x16x32_bf16 v[88:91], v[158:161], v[182:185], v[88:91]
	v_mfma_f32_16x16x32_bf16 v[84:87], v[128:131], v[190:193], v[84:87]
	v_mfma_f32_16x16x32_bf16 v[80:83], v[158:161], v[190:193], v[80:83]
	v_mfma_f32_16x16x32_bf16 v[76:79], v[128:131], v[198:201], v[76:79]
	v_mfma_f32_16x16x32_bf16 v[72:75], v[158:161], v[198:201], v[72:75]
	v_mfma_f32_16x16x32_bf16 v[68:71], v[128:131], v[218:221], v[68:71]
	v_mfma_f32_16x16x32_bf16 v[64:67], v[158:161], v[218:221], v[64:67]
	v_mfma_f32_16x16x32_bf16 v[92:95], v[132:135], v[186:189], v[92:95]
	v_mfma_f32_16x16x32_bf16 v[88:91], v[162:165], v[186:189], v[88:91]
	v_mfma_f32_16x16x32_bf16 v[84:87], v[132:135], v[194:197], v[84:87]
	v_mfma_f32_16x16x32_bf16 v[80:83], v[162:165], v[194:197], v[80:83]
	v_mfma_f32_16x16x32_bf16 v[76:79], v[132:135], v[202:205], v[76:79]
	v_mfma_f32_16x16x32_bf16 v[72:75], v[162:165], v[202:205], v[72:75]
	v_mfma_f32_16x16x32_bf16 v[68:71], v[132:135], v[222:225], v[68:71]
	v_mfma_f32_16x16x32_bf16 v[64:67], v[162:165], v[222:225], v[64:67]
	s_setprio 0
	s_setprio 1
	v_mfma_f32_16x16x32_bf16 v[28:31], v[166:169], v[182:185], v[28:31]
	v_mfma_f32_16x16x32_bf16 v[24:27], v[174:177], v[182:185], v[24:27]
	v_mfma_f32_16x16x32_bf16 v[20:23], v[166:169], v[190:193], v[20:23]
	v_mfma_f32_16x16x32_bf16 v[16:19], v[174:177], v[190:193], v[16:19]
	v_mfma_f32_16x16x32_bf16 v[12:15], v[166:169], v[198:201], v[12:15]
	v_mfma_f32_16x16x32_bf16 v[8:11], v[174:177], v[198:201], v[8:11]
	v_mfma_f32_16x16x32_bf16 v[4:7], v[166:169], v[218:221], v[4:7]
	v_mfma_f32_16x16x32_bf16 v[0:3], v[174:177], v[218:221], v[0:3]
	v_mfma_f32_16x16x32_bf16 v[28:31], v[170:173], v[186:189], v[28:31]
	v_mfma_f32_16x16x32_bf16 v[24:27], v[178:181], v[186:189], v[24:27]
	v_mfma_f32_16x16x32_bf16 v[20:23], v[170:173], v[194:197], v[20:23]
	v_mfma_f32_16x16x32_bf16 v[16:19], v[178:181], v[194:197], v[16:19]
	v_mfma_f32_16x16x32_bf16 v[12:15], v[170:173], v[202:205], v[12:15]
	s_setprio 2
	s_barrier
	v_mfma_f32_16x16x32_bf16 v[8:11], v[178:181], v[202:205], v[8:11]
	v_mfma_f32_16x16x32_bf16 v[4:7], v[170:173], v[222:225], v[4:7]
	v_mfma_f32_16x16x32_bf16 v[0:3], v[178:181], v[222:225], v[0:3]
	s_setprio 0
	s_add_i32 vcc_hi, vcc_hi, 2
	s_add_u32 s74, s74, 0x100
	s_addc_u32 s75, s75, 0
	s_add_u32 s93, s93, 0x100
	s_addc_u32 vcc_lo, vcc_lo, 0
	s_cmpk_gt_u32 vcc_hi, 0x7d
	s_cbranch_scc0 .LBB0_624
	s_and_b64 vcc, exec, s[40:41]
	s_cbranch_vccz .LBB0_627
	s_barrier

; #define PG8_STAGE(bufoff, gbase, voff) do { _Pragma("unroll") for (int _i = 0; _i < 2; ++_i) \
;         __builtin_amdgcn_global_load_lds((const unsigned*)((const char*)(gbase) + (voff)[_i]), (PG8_LAS unsigned*)(lds + (bufoff) + ldsw + _i * 8192), 16, 0, 0); } while (0)
; #define PG8_LDA(dst, b, h) do { _Pragma("unroll") for (int m = 0; m < 4; ++m) _Pragma("unroll") for (int k = 0; k < 2; ++k) dst[m][k] = *(const PG8_LAS bf16x8*)(lds + PG8_SA(b, h) + aoff + m * 2048 + k * 1024); } while (0)
; #define PG8_LDB(dst, b, h) do { _Pragma("unroll") for (int n = 0; n < 2; ++n) _Pragma("unroll") for (int k = 0; k < 2; ++k) dst[n][k] = *(const PG8_LAS bf16x8*)(lds + PG8_SB(b, h) + boff + n * 2048 + k * 1024); } while (0)
; #define PG8_MMA(ai, bj, At, Bt) do { __builtin_amdgcn_s_setprio(1); _Pragma("unroll") for (int m = 0; m < 4; ++m) _Pragma("unroll") for (int n = 0; n < 2; ++n) _Pragma("unroll") for (int k = 0; k < 2; ++k) \
;         acc[ai][bj][m][n] = __builtin_amdgcn_mfma_f32_16x16x32_bf16(Bt[n][k], At[m][k], acc[ai][bj][m][n], 0, 0, 0); __builtin_amdgcn_s_setprio(0); } while (0)
; #define PG8_WAIT_V(n) asm volatile("s_waitcnt vmcnt(" #n ")" ::: "memory")
; #define PG8_WAIT_L(n) asm volatile("s_waitcnt lgkmcnt(" #n ")" ::: "memory")
; #define PG8_BAR __builtin_amdgcn_s_barrier()
; #define PG8_SCHED __builtin_amdgcn_sched_barrier(0)
; template <class Epi, class Sched, bool ALIGN_EPI = false, bool SP2 = false>
; __device__ __forceinline__ void gemm_phase(PG8_LAS unsigned char* lds, const Gemm g, const Sched& S, const Epi& E) {
;     ...
;             const bool last = (t == nt - 2);
;             const char* a1 = cA + (size_t)(t + 1) * kstep;
;             const char* a2 = last ? nA : cA + (size_t)(t + 2) * kstep; const char* b2 = last ? nB : cB + (size_t)(t + 2) * kstep;
;             const char* a3 = a2 + kstep; const char* b3 = b2 + kstep;
;             if constexpr (SP2) {
;             PG8_LDB(B0, 0, 0); PG8_LDB(B1, 0, 1); PG8_SCHED; PG8_LDA(At, 0, 0); PG8_STAGE(PG8_SA(1, 1), a1 + hstep, voffA);
;             PG8_WAIT_V(8); PG8_WAIT_L(0); PG8_BAR; PG8_MMA(0, 0, At, B0); PG8_MMA(0, 1, At, B1); PG8_BAR; PG8_SCHED;
;             PG8_LDA(At, 0, 1); PG8_STAGE(PG8_SB(0, 0), b2, voffB); PG8_STAGE(PG8_SB(0, 1), b2 + hstep, voffB); PG8_STAGE(PG8_SA(0, 0), a2, voffA);
.LBB0_660:
	ds_read_b128 v[166:169], v145
	ds_read_b128 v[170:173], v145 offset:1024
	ds_read_b128 v[174:177], v145 offset:2048
	ds_read_b128 v[178:181], v145 offset:3072
	ds_read_b128 v[182:185], v149
	ds_read_b128 v[186:189], v149 offset:1024
	ds_read_b128 v[190:193], v149 offset:2048
	ds_read_b128 v[194:197], v149 offset:3072
	s_add_u32 s52, s72, 0xffe00080
	s_addc_u32 s53, s73, -1
	s_cmp_eq_u32 s49, 28
	s_cselect_b32 s77, s51, s53
	s_cselect_b32 s76, s50, s52
	s_cselect_b32 s75, s55, s41
	s_cselect_b32 s74, s54, s37
	s_mov_b32 m0, s82
	v_lshl_add_u64 v[230:231], s[72:73], 0, v[160:161]
	ds_read_b128 v[198:201], v164
	ds_read_b128 v[202:205], v164 offset:1024
	ds_read_b128 v[206:209], v164 offset:2048
	ds_read_b128 v[210:213], v164 offset:3072
	ds_read_b128 v[214:217], v164 offset:4096
	ds_read_b128 v[218:221], v164 offset:5120
	ds_read_b128 v[222:225], v164 offset:6144
	ds_read_b128 v[226:229], v164 offset:7168
	global_load_lds_dwordx4 v[230:231], off
	v_lshl_add_u64 v[230:231], s[72:73], 0, v[162:163]
	s_mov_b32 m0, s83
	s_nop 0
	global_load_lds_dwordx4 v[230:231], off
	s_waitcnt vmcnt(8)
	s_waitcnt lgkmcnt(0)
	s_setprio 1
	s_barrier
	v_mfma_f32_16x16x32_bf16 v[124:127], v[166:169], v[198:201], v[124:127]
	v_mfma_f32_16x16x32_bf16 v[120:123], v[174:177], v[198:201], v[120:123]
	v_mfma_f32_16x16x32_bf16 v[116:119], v[166:169], v[206:209], v[116:119]
	v_mfma_f32_16x16x32_bf16 v[108:111], v[174:177], v[206:209], v[108:111]
	v_mfma_f32_16x16x32_bf16 v[100:103], v[166:169], v[214:217], v[100:103]
	v_mfma_f32_16x16x32_bf16 v[92:95], v[174:177], v[214:217], v[92:95]
	v_mfma_f32_16x16x32_bf16 v[84:87], v[166:169], v[222:225], v[84:87]
	v_mfma_f32_16x16x32_bf16 v[76:79], v[174:177], v[222:225], v[76:79]
	v_mfma_f32_16x16x32_bf16 v[124:127], v[170:173], v[202:205], v[124:127]
	v_mfma_f32_16x16x32_bf16 v[120:123], v[178:181], v[202:205], v[120:123]
	v_mfma_f32_16x16x32_bf16 v[116:119], v[170:173], v[210:213], v[116:119]
	v_mfma_f32_16x16x32_bf16 v[108:111], v[178:181], v[210:213], v[108:111]
	v_mfma_f32_16x16x32_bf16 v[100:103], v[170:173], v[218:221], v[100:103]
	v_mfma_f32_16x16x32_bf16 v[92:95], v[178:181], v[218:221], v[92:95]
	v_mfma_f32_16x16x32_bf16 v[84:87], v[170:173], v[226:229], v[84:87]
	v_mfma_f32_16x16x32_bf16 v[76:79], v[178:181], v[226:229], v[76:79]
	s_setprio 0
	s_setprio 1
	v_mfma_f32_16x16x32_bf16 v[112:115], v[182:185], v[198:201], v[112:115]
	v_mfma_f32_16x16x32_bf16 v[104:107], v[190:193], v[198:201], v[104:107]
	v_mfma_f32_16x16x32_bf16 v[96:99], v[182:185], v[206:209], v[96:99]
	v_mfma_f32_16x16x32_bf16 v[88:91], v[190:193], v[206:209], v[88:91]
	v_mfma_f32_16x16x32_bf16 v[80:83], v[182:185], v[214:217], v[80:83]
	v_mfma_f32_16x16x32_bf16 v[72:75], v[190:193], v[214:217], v[72:75]
	v_mfma_f32_16x16x32_bf16 v[68:71], v[182:185], v[222:225], v[68:71]
	v_mfma_f32_16x16x32_bf16 v[64:67], v[190:193], v[222:225], v[64:67]
	v_mfma_f32_16x16x32_bf16 v[112:115], v[186:189], v[202:205], v[112:115]
	v_mfma_f32_16x16x32_bf16 v[104:107], v[194:197], v[202:205], v[104:107]
	v_mfma_f32_16x16x32_bf16 v[96:99], v[186:189], v[210:213], v[96:99]
	v_mfma_f32_16x16x32_bf16 v[88:91], v[194:197], v[210:213], v[88:91]
	v_mfma_f32_16x16x32_bf16 v[80:83], v[186:189], v[218:221], v[80:83]
	s_setprio 2
	s_barrier
	v_mfma_f32_16x16x32_bf16 v[72:75], v[194:197], v[218:221], v[72:75]
	v_mfma_f32_16x16x32_bf16 v[68:71], v[186:189], v[226:229], v[68:71]
	v_mfma_f32_16x16x32_bf16 v[64:67], v[194:197], v[226:229], v[64:67]
	s_setprio 0
	s_mov_b32 m0, s84
	v_lshl_add_u64 v[230:231], s[74:75], 0, v[138:139]
	s_add_u32 s52, s74, 0x200000
	ds_read_b128 v[198:201], v164 offset:16384
	ds_read_b128 v[202:205], v164 offset:17408
	ds_read_b128 v[206:209], v164 offset:18432
	ds_read_b128 v[210:213], v164 offset:19456
	ds_read_b128 v[214:217], v164 offset:20480
	ds_read_b128 v[218:221], v164 offset:21504
	ds_read_b128 v[222:225], v164 offset:22528
	ds_read_b128 v[226:229], v164 offset:23552
	global_load_lds_dwordx4 v[230:231], off
	v_lshl_add_u64 v[232:233], s[74:75], 0, v[142:143]
	s_mov_b32 m0, s85
	s_addc_u32 s53, s75, 0
	global_load_lds_dwordx4 v[232:233], off
	v_lshl_add_u64 v[234:235], s[52:53], 0, v[138:139]
	s_mov_b32 m0, s86
	v_lshl_add_u64 v[236:237], s[76:77], 0, v[140:141]
	global_load_lds_dwordx4 v[234:235], off
	v_lshl_add_u64 v[234:235], s[52:53], 0, v[142:143]
	s_mov_b32 m0, s87
	s_nop 0
	global_load_lds_dwordx4 v[234:235], off
	v_lshl_add_u64 v[234:235], s[76:77], 0, v[136:137]
	s_mov_b32 m0, s28
	s_nop 0
	global_load_lds_dwordx4 v[234:235], off
	s_mov_b32 m0, s29
	s_nop 0
	global_load_lds_dwordx4 v[236:237], off
	s_waitcnt vmcnt(8)
	s_waitcnt lgkmcnt(0)
	s_setprio 1
	s_barrier
; #define PG8_STAGE(bufoff, gbase, voff) do { _Pragma("unroll") for (int _i = 0; _i < 2; ++_i) \
;         __builtin_amdgcn_global_load_lds((const unsigned*)((const char*)(gbase) + (voff)[_i]), (PG8_LAS unsigned*)(lds + (bufoff) + ldsw + _i * 8192), 16, 0, 0); } while (0)
; #define PG8_LDA(dst, b, h) do { _Pragma("unroll") for (int m = 0; m < 4; ++m) _Pragma("unroll") for (int k = 0; k < 2; ++k) dst[m][k] = *(const PG8_LAS bf16x8*)(lds + PG8_SA(b, h) + aoff + m * 2048 + k * 1024); } while (0)
; #define PG8_LDB(dst, b, h) do { _Pragma("unroll") for (int n = 0; n < 2; ++n) _Pragma("unroll") for (int k = 0; k < 2; ++k) dst[n][k] = *(const PG8_LAS bf16x8*)(lds + PG8_SB(b, h) + boff + n * 2048 + k * 1024); } while (0)
; #define PG8_MMA(ai, bj, At, Bt) do { __builtin_amdgcn_s_setprio(1); _Pragma("unroll") for (int m = 0; m < 4; ++m) _Pragma("unroll") for (int n = 0; n < 2; ++n) _Pragma("unroll") for (int k = 0; k < 2; ++k) \
;         acc[ai][bj][m][n] = __builtin_amdgcn_mfma_f32_16x16x32_bf16(Bt[n][k], At[m][k], acc[ai][bj][m][n], 0, 0, 0); __builtin_amdgcn_s_setprio(0); } while (0)
; #define PG8_WAIT_V(n) asm volatile("s_waitcnt vmcnt(" #n ")" ::: "memory")
; #define PG8_WAIT_L(n) asm volatile("s_waitcnt lgkmcnt(" #n ")" ::: "memory")
; #define PG8_BAR __builtin_amdgcn_s_barrier()
; #define PG8_SCHED __builtin_amdgcn_sched_barrier(0)
; template <class Epi, class Sched, bool ALIGN_EPI = false, bool SP2 = false>
; __device__ __forceinline__ void gemm_phase(PG8_LAS unsigned char* lds, const Gemm g, const Sched& S, const Epi& E) {
;     ...
;             PG8_WAIT_V(8); PG8_WAIT_L(0); PG8_BAR; PG8_MMA(1, 0, At, B0); PG8_MMA(1, 1, At, B1); PG8_BAR; PG8_SCHED;
;             PG8_LDB(B0, 1, 0); PG8_LDB(B1, 1, 1); PG8_SCHED; PG8_LDA(At, 1, 0); PG8_STAGE(PG8_SA(0, 1), a2 + hstep, voffA);
;             PG8_WAIT_V(8); PG8_WAIT_L(0); PG8_BAR; PG8_MMA(0, 0, At, B0); PG8_MMA(0, 1, At, B1); PG8_BAR; PG8_SCHED;
	v_mfma_f32_16x16x32_bf16 v[60:63], v[166:169], v[198:201], v[60:63]
	v_mfma_f32_16x16x32_bf16 v[56:59], v[174:177], v[198:201], v[56:59]
	v_mfma_f32_16x16x32_bf16 v[52:55], v[166:169], v[206:209], v[52:55]
	v_mfma_f32_16x16x32_bf16 v[44:47], v[174:177], v[206:209], v[44:47]
	v_mfma_f32_16x16x32_bf16 v[36:39], v[166:169], v[214:217], v[36:39]
	v_mfma_f32_16x16x32_bf16 v[28:31], v[174:177], v[214:217], v[28:31]
	v_mfma_f32_16x16x32_bf16 v[20:23], v[166:169], v[222:225], v[20:23]
	v_mfma_f32_16x16x32_bf16 v[12:15], v[174:177], v[222:225], v[12:15]
	v_mfma_f32_16x16x32_bf16 v[60:63], v[170:173], v[202:205], v[60:63]
	v_mfma_f32_16x16x32_bf16 v[56:59], v[178:181], v[202:205], v[56:59]
	v_mfma_f32_16x16x32_bf16 v[52:55], v[170:173], v[210:213], v[52:55]
	v_mfma_f32_16x16x32_bf16 v[44:47], v[178:181], v[210:213], v[44:47]
	v_mfma_f32_16x16x32_bf16 v[36:39], v[170:173], v[218:221], v[36:39]
	v_mfma_f32_16x16x32_bf16 v[28:31], v[178:181], v[218:221], v[28:31]
	v_mfma_f32_16x16x32_bf16 v[20:23], v[170:173], v[226:229], v[20:23]
	v_mfma_f32_16x16x32_bf16 v[12:15], v[178:181], v[226:229], v[12:15]
	s_setprio 0
	s_setprio 1
	v_mfma_f32_16x16x32_bf16 v[48:51], v[182:185], v[198:201], v[48:51]
	v_mfma_f32_16x16x32_bf16 v[40:43], v[190:193], v[198:201], v[40:43]
	v_mfma_f32_16x16x32_bf16 v[32:35], v[182:185], v[206:209], v[32:35]
	v_mfma_f32_16x16x32_bf16 v[24:27], v[190:193], v[206:209], v[24:27]
	v_mfma_f32_16x16x32_bf16 v[16:19], v[182:185], v[214:217], v[16:19]
	v_mfma_f32_16x16x32_bf16 v[8:11], v[190:193], v[214:217], v[8:11]
	v_mfma_f32_16x16x32_bf16 v[4:7], v[182:185], v[222:225], v[4:7]
	v_mfma_f32_16x16x32_bf16 v[0:3], v[190:193], v[222:225], v[0:3]
	v_mfma_f32_16x16x32_bf16 v[48:51], v[186:189], v[202:205], v[48:51]
	v_mfma_f32_16x16x32_bf16 v[40:43], v[194:197], v[202:205], v[40:43]
	v_mfma_f32_16x16x32_bf16 v[32:35], v[186:189], v[210:213], v[32:35]
	v_mfma_f32_16x16x32_bf16 v[24:27], v[194:197], v[210:213], v[24:27]
	v_mfma_f32_16x16x32_bf16 v[16:19], v[186:189], v[218:221], v[16:19]
	s_setprio 2
	s_barrier
	v_mfma_f32_16x16x32_bf16 v[8:11], v[194:197], v[218:221], v[8:11]
	v_mfma_f32_16x16x32_bf16 v[4:7], v[186:189], v[226:229], v[4:7]
	v_mfma_f32_16x16x32_bf16 v[0:3], v[194:197], v[226:229], v[0:3]
	s_setprio 0
	ds_read_b128 v[166:169], v148
	ds_read_b128 v[170:173], v148 offset:1024
	ds_read_b128 v[174:177], v148 offset:2048
	ds_read_b128 v[178:181], v148 offset:3072
	ds_read_b128 v[182:185], v165
	ds_read_b128 v[186:189], v165 offset:1024
	ds_read_b128 v[190:193], v165 offset:2048
	ds_read_b128 v[194:197], v165 offset:3072
	s_add_u32 s52, s76, 0x200000
	s_addc_u32 s53, s77, 0
	s_mov_b32 m0, s33
	v_lshl_add_u64 v[238:239], s[52:53], 0, v[136:137]
	ds_read_b128 v[198:201], v164 offset:32768
	ds_read_b128 v[202:205], v164 offset:33792
	ds_read_b128 v[206:209], v164 offset:34816
	ds_read_b128 v[210:213], v164 offset:35840
	ds_read_b128 v[214:217], v164 offset:36864
	ds_read_b128 v[218:221], v164 offset:37888
	ds_read_b128 v[222:225], v164 offset:38912
	ds_read_b128 v[226:229], v164 offset:39936
	global_load_lds_dwordx4 v[238:239], off
	v_lshl_add_u64 v[238:239], s[52:53], 0, v[140:141]
	s_mov_b32 m0, s38
	s_nop 0
	global_load_lds_dwordx4 v[238:239], off
	s_waitcnt vmcnt(8)
	s_waitcnt lgkmcnt(0)
	s_setprio 1
	s_barrier
	v_mfma_f32_16x16x32_bf16 v[124:127], v[166:169], v[198:201], v[124:127]
	v_mfma_f32_16x16x32_bf16 v[120:123], v[174:177], v[198:201], v[120:123]
	v_mfma_f32_16x16x32_bf16 v[116:119], v[166:169], v[206:209], v[116:119]
	v_mfma_f32_16x16x32_bf16 v[108:111], v[174:177], v[206:209], v[108:111]
	v_mfma_f32_16x16x32_bf16 v[100:103], v[166:169], v[214:217], v[100:103]
	v_mfma_f32_16x16x32_bf16 v[92:95], v[174:177], v[214:217], v[92:95]
	v_mfma_f32_16x16x32_bf16 v[84:87], v[166:169], v[222:225], v[84:87]
	v_mfma_f32_16x16x32_bf16 v[76:79], v[174:177], v[222:225], v[76:79]
	v_mfma_f32_16x16x32_bf16 v[124:127], v[170:173], v[202:205], v[124:127]
	v_mfma_f32_16x16x32_bf16 v[120:123], v[178:181], v[202:205], v[120:123]
	v_mfma_f32_16x16x32_bf16 v[116:119], v[170:173], v[210:213], v[116:119]
	v_mfma_f32_16x16x32_bf16 v[108:111], v[178:181], v[210:213], v[108:111]
	v_mfma_f32_16x16x32_bf16 v[100:103], v[170:173], v[218:221], v[100:103]
	v_mfma_f32_16x16x32_bf16 v[92:95], v[178:181], v[218:221], v[92:95]
	v_mfma_f32_16x16x32_bf16 v[84:87], v[170:173], v[226:229], v[84:87]
	v_mfma_f32_16x16x32_bf16 v[76:79], v[178:181], v[226:229], v[76:79]
	s_setprio 0
	s_setprio 1
	v_mfma_f32_16x16x32_bf16 v[112:115], v[182:185], v[198:201], v[112:115]
	v_mfma_f32_16x16x32_bf16 v[104:107], v[190:193], v[198:201], v[104:107]
	v_mfma_f32_16x16x32_bf16 v[96:99], v[182:185], v[206:209], v[96:99]
	v_mfma_f32_16x16x32_bf16 v[88:91], v[190:193], v[206:209], v[88:91]
	v_mfma_f32_16x16x32_bf16 v[80:83], v[182:185], v[214:217], v[80:83]
	v_mfma_f32_16x16x32_bf16 v[72:75], v[190:193], v[214:217], v[72:75]
	v_mfma_f32_16x16x32_bf16 v[68:71], v[182:185], v[222:225], v[68:71]
	v_mfma_f32_16x16x32_bf16 v[64:67], v[190:193], v[222:225], v[64:67]
	v_mfma_f32_16x16x32_bf16 v[112:115], v[186:189], v[202:205], v[112:115]
	v_mfma_f32_16x16x32_bf16 v[104:107], v[194:197], v[202:205], v[104:107]
	v_mfma_f32_16x16x32_bf16 v[96:99], v[186:189], v[210:213], v[96:99]
	v_mfma_f32_16x16x32_bf16 v[88:91], v[194:197], v[210:213], v[88:91]
	v_mfma_f32_16x16x32_bf16 v[80:83], v[186:189], v[218:221], v[80:83]
	s_setprio 2
	s_barrier
; #define PG8_STAGE(bufoff, gbase, voff) do { _Pragma("unroll") for (int _i = 0; _i < 2; ++_i) \
;         __builtin_amdgcn_global_load_lds((const unsigned*)((const char*)(gbase) + (voff)[_i]), (PG8_LAS unsigned*)(lds + (bufoff) + ldsw + _i * 8192), 16, 0, 0); } while (0)
; #define PG8_LDA(dst, b, h) do { _Pragma("unroll") for (int m = 0; m < 4; ++m) _Pragma("unroll") for (int k = 0; k < 2; ++k) dst[m][k] = *(const PG8_LAS bf16x8*)(lds + PG8_SA(b, h) + aoff + m * 2048 + k * 1024); } while (0)
; #define PG8_MMA(ai, bj, At, Bt) do { __builtin_amdgcn_s_setprio(1); _Pragma("unroll") for (int m = 0; m < 4; ++m) _Pragma("unroll") for (int n = 0; n < 2; ++n) _Pragma("unroll") for (int k = 0; k < 2; ++k) \
;         acc[ai][bj][m][n] = __builtin_amdgcn_mfma_f32_16x16x32_bf16(Bt[n][k], At[m][k], acc[ai][bj][m][n], 0, 0, 0); __builtin_amdgcn_s_setprio(0); } while (0)
; #define PG8_WAIT_V(n) asm volatile("s_waitcnt vmcnt(" #n ")" ::: "memory")
; #define PG8_WAIT_L(n) asm volatile("s_waitcnt lgkmcnt(" #n ")" ::: "memory")
; #define PG8_BAR __builtin_amdgcn_s_barrier()
; #define PG8_SCHED __builtin_amdgcn_sched_barrier(0)
; template <class Epi, class Sched, bool ALIGN_EPI = false, bool SP2 = false>
; __device__ __forceinline__ void gemm_phase(PG8_LAS unsigned char* lds, const Gemm g, const Sched& S, const Epi& E) {
;     ...
;             PG8_WAIT_V(8); PG8_WAIT_L(0); PG8_BAR; PG8_MMA(0, 0, At, B0); PG8_MMA(0, 1, At, B1); PG8_BAR; PG8_SCHED;
;             PG8_LDA(At, 1, 1); PG8_STAGE(PG8_SB(1, 0), b3, voffB); PG8_STAGE(PG8_SB(1, 1), b3 + hstep, voffB); PG8_STAGE(PG8_SA(1, 0), a3, voffA);
;             PG8_WAIT_V(8); PG8_WAIT_L(0); PG8_BAR; PG8_MMA(1, 0, At, B0); PG8_MMA(1, 1, At, B1); PG8_BAR; PG8_SCHED;
;     ...
;         if constexpr (ALIGN_EPI) { if (wr == 0) PG8_BAR; }
	v_mfma_f32_16x16x32_bf16 v[72:75], v[194:197], v[218:221], v[72:75]
	v_mfma_f32_16x16x32_bf16 v[68:71], v[186:189], v[226:229], v[68:71]
	v_mfma_f32_16x16x32_bf16 v[64:67], v[194:197], v[226:229], v[64:67]
	s_setprio 0
	s_mov_b32 m0, s89
	v_lshl_add_u64 v[230:231], v[230:231], 0, s[12:13]
	ds_read_b128 v[198:201], v164 offset:49152
	ds_read_b128 v[202:205], v164 offset:50176
	ds_read_b128 v[206:209], v164 offset:51200
	ds_read_b128 v[210:213], v164 offset:52224
	ds_read_b128 v[214:217], v164 offset:53248
	ds_read_b128 v[218:221], v164 offset:54272
	ds_read_b128 v[222:225], v164 offset:55296
	ds_read_b128 v[226:229], v164 offset:56320
	global_load_lds_dwordx4 v[230:231], off
	s_add_i32 m0, s89, 0x2000
	s_add_u32 s52, s74, 0x200080
	v_lshl_add_u64 v[230:231], v[232:233], 0, s[12:13]
	s_addc_u32 s53, s75, 0
	s_add_i32 s56, s88, s3
	global_load_lds_dwordx4 v[230:231], off
	v_lshl_add_u64 v[230:231], s[52:53], 0, v[138:139]
	s_mov_b32 m0, s56
	s_nop 0
	global_load_lds_dwordx4 v[230:231], off
	v_lshl_add_u64 v[230:231], s[52:53], 0, v[142:143]
	s_add_i32 m0, s56, 0x2000
	s_nop 0
	global_load_lds_dwordx4 v[230:231], off
	v_lshl_add_u64 v[230:231], v[234:235], 0, s[12:13]
	s_mov_b32 m0, s71
	s_nop 0
	global_load_lds_dwordx4 v[230:231], off
	v_lshl_add_u64 v[230:231], v[236:237], 0, s[12:13]
	s_mov_b32 m0, s78
	s_nop 0
	global_load_lds_dwordx4 v[230:231], off
	s_waitcnt vmcnt(8)
	s_waitcnt lgkmcnt(0)
	s_setprio 1
	s_barrier
	v_mfma_f32_16x16x32_bf16 v[60:63], v[166:169], v[198:201], v[60:63]
	v_mfma_f32_16x16x32_bf16 v[56:59], v[174:177], v[198:201], v[56:59]
	v_mfma_f32_16x16x32_bf16 v[52:55], v[166:169], v[206:209], v[52:55]
	v_mfma_f32_16x16x32_bf16 v[44:47], v[174:177], v[206:209], v[44:47]
	v_mfma_f32_16x16x32_bf16 v[36:39], v[166:169], v[214:217], v[36:39]
	v_mfma_f32_16x16x32_bf16 v[28:31], v[174:177], v[214:217], v[28:31]
	v_mfma_f32_16x16x32_bf16 v[20:23], v[166:169], v[222:225], v[20:23]
	v_mfma_f32_16x16x32_bf16 v[12:15], v[174:177], v[222:225], v[12:15]
	v_mfma_f32_16x16x32_bf16 v[60:63], v[170:173], v[202:205], v[60:63]
	v_mfma_f32_16x16x32_bf16 v[56:59], v[178:181], v[202:205], v[56:59]
	v_mfma_f32_16x16x32_bf16 v[52:55], v[170:173], v[210:213], v[52:55]
	v_mfma_f32_16x16x32_bf16 v[44:47], v[178:181], v[210:213], v[44:47]
	v_mfma_f32_16x16x32_bf16 v[36:39], v[170:173], v[218:221], v[36:39]
	v_mfma_f32_16x16x32_bf16 v[28:31], v[178:181], v[218:221], v[28:31]
	v_mfma_f32_16x16x32_bf16 v[20:23], v[170:173], v[226:229], v[20:23]
	v_mfma_f32_16x16x32_bf16 v[12:15], v[178:181], v[226:229], v[12:15]
	s_setprio 0
	s_setprio 1
	v_mfma_f32_16x16x32_bf16 v[48:51], v[182:185], v[198:201], v[48:51]
	v_mfma_f32_16x16x32_bf16 v[40:43], v[190:193], v[198:201], v[40:43]
	v_mfma_f32_16x16x32_bf16 v[32:35], v[182:185], v[206:209], v[32:35]
	v_mfma_f32_16x16x32_bf16 v[24:27], v[190:193], v[206:209], v[24:27]
	v_mfma_f32_16x16x32_bf16 v[16:19], v[182:185], v[214:217], v[16:19]
	v_mfma_f32_16x16x32_bf16 v[8:11], v[190:193], v[214:217], v[8:11]
	v_mfma_f32_16x16x32_bf16 v[4:7], v[182:185], v[222:225], v[4:7]
	v_mfma_f32_16x16x32_bf16 v[0:3], v[190:193], v[222:225], v[0:3]
	v_mfma_f32_16x16x32_bf16 v[48:51], v[186:189], v[202:205], v[48:51]
	v_mfma_f32_16x16x32_bf16 v[40:43], v[194:197], v[202:205], v[40:43]
	v_mfma_f32_16x16x32_bf16 v[32:35], v[186:189], v[210:213], v[32:35]
	v_mfma_f32_16x16x32_bf16 v[24:27], v[194:197], v[210:213], v[24:27]
	v_mfma_f32_16x16x32_bf16 v[16:19], v[186:189], v[218:221], v[16:19]
	s_setprio 2
	s_barrier
	v_mfma_f32_16x16x32_bf16 v[8:11], v[194:197], v[218:221], v[8:11]
	v_mfma_f32_16x16x32_bf16 v[4:7], v[186:189], v[226:229], v[4:7]
	v_mfma_f32_16x16x32_bf16 v[0:3], v[194:197], v[226:229], v[0:3]
	s_setprio 0
	s_add_i32 s49, s49, 2
	s_add_u32 s72, s72, 0x100
	s_addc_u32 s73, s73, 0
	s_add_u32 s37, s37, 0x100
	s_addc_u32 s41, s41, 0
	s_cmp_gt_u32 s49, 29
	s_cbranch_scc0 .LBB0_660
	s_and_b64 vcc, exec, s[14:15]
	s_cbranch_vccz .LBB0_663
	s_barrier

; #define PG8_STAGE(bufoff, gbase, voff) do { _Pragma("unroll") for (int _i = 0; _i < 2; ++_i) \
;         __builtin_amdgcn_global_load_lds((const unsigned*)((const char*)(gbase) + (voff)[_i]), (PG8_LAS unsigned*)(lds + (bufoff) + ldsw + _i * 8192), 16, 0, 0); } while (0)
; #define PG8_LDA(dst, b, h) do { _Pragma("unroll") for (int m = 0; m < 4; ++m) _Pragma("unroll") for (int k = 0; k < 2; ++k) dst[m][k] = *(const PG8_LAS bf16x8*)(lds + PG8_SA(b, h) + aoff + m * 2048 + k * 1024); } while (0)
; #define PG8_LDB(dst, b, h) do { _Pragma("unroll") for (int n = 0; n < 2; ++n) _Pragma("unroll") for (int k = 0; k < 2; ++k) dst[n][k] = *(const PG8_LAS bf16x8*)(lds + PG8_SB(b, h) + boff + n * 2048 + k * 1024); } while (0)
; #define PG8_MMA(ai, bj, At, Bt) do { __builtin_amdgcn_s_setprio(1); _Pragma("unroll") for (int m = 0; m < 4; ++m) _Pragma("unroll") for (int n = 0; n < 2; ++n) _Pragma("unroll") for (int k = 0; k < 2; ++k) \
;         acc[ai][bj][m][n] = __builtin_amdgcn_mfma_f32_16x16x32_bf16(Bt[n][k], At[m][k], acc[ai][bj][m][n], 0, 0, 0); __builtin_amdgcn_s_setprio(0); } while (0)
; #define PG8_WAIT_V(n) asm volatile("s_waitcnt vmcnt(" #n ")" ::: "memory")
; #define PG8_WAIT_L(n) asm volatile("s_waitcnt lgkmcnt(" #n ")" ::: "memory")
; #define PG8_BAR __builtin_amdgcn_s_barrier()
; #define PG8_SCHED __builtin_amdgcn_sched_barrier(0)
; template <class Epi, class Sched, bool ALIGN_EPI = false, bool SP2 = false>
; __device__ __forceinline__ void gemm_phase(PG8_LAS unsigned char* lds, const Gemm g, const Sched& S, const Epi& E) {
;     ...
;             const bool last = (t == nt - 2);
;             const char* a1 = cA + (size_t)(t + 1) * kstep;
;             const char* a2 = last ? nA : cA + (size_t)(t + 2) * kstep; const char* b2 = last ? nB : cB + (size_t)(t + 2) * kstep;
;             const char* a3 = a2 + kstep; const char* b3 = b2 + kstep;
;             if constexpr (SP2) {
;             PG8_LDB(B0, 0, 0); PG8_LDB(B1, 0, 1); PG8_SCHED; PG8_LDA(At, 0, 0); PG8_STAGE(PG8_SA(1, 1), a1 + hstep, voffA);
;             PG8_WAIT_V(8); PG8_WAIT_L(0); PG8_BAR; PG8_MMA(0, 0, At, B0); PG8_MMA(0, 1, At, B1); PG8_BAR; PG8_SCHED;
;             PG8_LDA(At, 0, 1); PG8_STAGE(PG8_SB(0, 0), b2, voffB); PG8_STAGE(PG8_SB(0, 1), b2 + hstep, voffB); PG8_STAGE(PG8_SA(0, 0), a2, voffA);
.LBB0_809:
	ds_read_b128 v[128:131], v180
	ds_read_b128 v[132:135], v180 offset:1024
	ds_read_b128 v[136:139], v180 offset:2048
	ds_read_b128 v[140:143], v180 offset:3072
	ds_read_b128 v[160:163], v181
	ds_read_b128 v[164:167], v181 offset:1024
	ds_read_b128 v[184:187], v181 offset:2048
	ds_read_b128 v[188:191], v181 offset:3072
	s_add_u32 s52, s72, 0xfff80080
	s_addc_u32 s53, s73, -1
	s_cmp_eq_u32 s92, 28
	s_cselect_b32 s77, s5, s53
	s_cselect_b32 s76, s49, s52
	s_cselect_b32 s75, s45, s91
	s_cselect_b32 s74, s89, s90
	v_lshl_add_u64 v[168:169], s[72:73], 0, v[154:155]
	s_add_i32 m0, s71, 0xc000
	ds_read_b128 v[192:195], v182
	ds_read_b128 v[196:199], v182 offset:1024
	ds_read_b128 v[200:203], v182 offset:2048
	ds_read_b128 v[204:207], v182 offset:3072
	ds_read_b128 v[208:211], v182 offset:4096
	ds_read_b128 v[212:215], v182 offset:5120
	ds_read_b128 v[216:219], v182 offset:6144
	ds_read_b128 v[220:223], v182 offset:7168
	global_load_lds_dwordx4 v[168:169], off
	v_lshl_add_u64 v[168:169], s[72:73], 0, v[156:157]
	s_add_i32 m0, s71, 0xe000
	s_nop 0
	global_load_lds_dwordx4 v[168:169], off
	s_waitcnt vmcnt(8)
	s_waitcnt lgkmcnt(0)
	s_setprio 1
	s_barrier
	v_mfma_f32_16x16x32_bf16 v[124:127], v[128:131], v[192:195], v[124:127]
	v_mfma_f32_16x16x32_bf16 v[120:123], v[136:139], v[192:195], v[120:123]
	v_mfma_f32_16x16x32_bf16 v[108:111], v[128:131], v[200:203], v[108:111]
	v_mfma_f32_16x16x32_bf16 v[104:107], v[136:139], v[200:203], v[104:107]
	v_mfma_f32_16x16x32_bf16 v[92:95], v[128:131], v[208:211], v[92:95]
	v_mfma_f32_16x16x32_bf16 v[88:91], v[136:139], v[208:211], v[88:91]
	v_mfma_f32_16x16x32_bf16 v[76:79], v[128:131], v[216:219], v[76:79]
	v_mfma_f32_16x16x32_bf16 v[72:75], v[136:139], v[216:219], v[72:75]
	v_mfma_f32_16x16x32_bf16 v[124:127], v[132:135], v[196:199], v[124:127]
	v_mfma_f32_16x16x32_bf16 v[120:123], v[140:143], v[196:199], v[120:123]
	v_mfma_f32_16x16x32_bf16 v[108:111], v[132:135], v[204:207], v[108:111]
	v_mfma_f32_16x16x32_bf16 v[104:107], v[140:143], v[204:207], v[104:107]
	v_mfma_f32_16x16x32_bf16 v[92:95], v[132:135], v[212:215], v[92:95]
	v_mfma_f32_16x16x32_bf16 v[88:91], v[140:143], v[212:215], v[88:91]
	v_mfma_f32_16x16x32_bf16 v[76:79], v[132:135], v[220:223], v[76:79]
	v_mfma_f32_16x16x32_bf16 v[72:75], v[140:143], v[220:223], v[72:75]
	s_setprio 0
	s_setprio 1
	v_mfma_f32_16x16x32_bf16 v[116:119], v[160:163], v[192:195], v[116:119]
	v_mfma_f32_16x16x32_bf16 v[112:115], v[184:187], v[192:195], v[112:115]
	v_mfma_f32_16x16x32_bf16 v[100:103], v[160:163], v[200:203], v[100:103]
	v_mfma_f32_16x16x32_bf16 v[96:99], v[184:187], v[200:203], v[96:99]
	v_mfma_f32_16x16x32_bf16 v[84:87], v[160:163], v[208:211], v[84:87]
	v_mfma_f32_16x16x32_bf16 v[80:83], v[184:187], v[208:211], v[80:83]
	v_mfma_f32_16x16x32_bf16 v[68:71], v[160:163], v[216:219], v[68:71]
	v_mfma_f32_16x16x32_bf16 v[64:67], v[184:187], v[216:219], v[64:67]
	v_mfma_f32_16x16x32_bf16 v[116:119], v[164:167], v[196:199], v[116:119]
	v_mfma_f32_16x16x32_bf16 v[112:115], v[188:191], v[196:199], v[112:115]
	v_mfma_f32_16x16x32_bf16 v[100:103], v[164:167], v[204:207], v[100:103]
	v_mfma_f32_16x16x32_bf16 v[96:99], v[188:191], v[204:207], v[96:99]
	v_mfma_f32_16x16x32_bf16 v[84:87], v[164:167], v[212:215], v[84:87]
	s_setprio 2
	s_barrier
	v_mfma_f32_16x16x32_bf16 v[80:83], v[188:191], v[212:215], v[80:83]
	v_mfma_f32_16x16x32_bf16 v[68:71], v[164:167], v[220:223], v[68:71]
	v_mfma_f32_16x16x32_bf16 v[64:67], v[188:191], v[220:223], v[64:67]
	s_setprio 0
	s_add_i32 s52, s83, s78
	v_lshl_add_u64 v[168:169], s[74:75], 0, v[148:149]
	s_mov_b32 m0, s52
	ds_read_b128 v[192:195], v182 offset:16384
	ds_read_b128 v[196:199], v182 offset:17408
	ds_read_b128 v[200:203], v182 offset:18432
	ds_read_b128 v[204:207], v182 offset:19456
	ds_read_b128 v[208:211], v182 offset:20480
	ds_read_b128 v[212:215], v182 offset:21504
	ds_read_b128 v[216:219], v182 offset:22528
	ds_read_b128 v[220:223], v182 offset:23552
	global_load_lds_dwordx4 v[168:169], off
	s_add_i32 m0, s52, 0x2000
	s_add_u32 s52, s74, 0x80000
	v_lshl_add_u64 v[224:225], s[74:75], 0, v[152:153]
	s_addc_u32 s53, s75, 0
	s_add_i32 s56, s84, s78
	global_load_lds_dwordx4 v[224:225], off
	v_lshl_add_u64 v[226:227], s[52:53], 0, v[148:149]
	s_mov_b32 m0, s56
	v_lshl_add_u64 v[228:229], s[76:77], 0, v[150:151]
	global_load_lds_dwordx4 v[226:227], off
	v_lshl_add_u64 v[226:227], s[52:53], 0, v[152:153]
	s_add_i32 m0, s56, 0x2000
	s_nop 0
	global_load_lds_dwordx4 v[226:227], off
	v_lshl_add_u64 v[226:227], s[76:77], 0, v[144:145]
	s_mov_b32 m0, s71
	s_nop 0
	global_load_lds_dwordx4 v[226:227], off
	s_mov_b32 m0, s79
	s_nop 0
	global_load_lds_dwordx4 v[228:229], off
	s_waitcnt vmcnt(8)
	s_waitcnt lgkmcnt(0)
	s_setprio 1
	s_barrier
; #define PG8_STAGE(bufoff, gbase, voff) do { _Pragma("unroll") for (int _i = 0; _i < 2; ++_i) \
;         __builtin_amdgcn_global_load_lds((const unsigned*)((const char*)(gbase) + (voff)[_i]), (PG8_LAS unsigned*)(lds + (bufoff) + ldsw + _i * 8192), 16, 0, 0); } while (0)
; #define PG8_LDA(dst, b, h) do { _Pragma("unroll") for (int m = 0; m < 4; ++m) _Pragma("unroll") for (int k = 0; k < 2; ++k) dst[m][k] = *(const PG8_LAS bf16x8*)(lds + PG8_SA(b, h) + aoff + m * 2048 + k * 1024); } while (0)
; #define PG8_LDB(dst, b, h) do { _Pragma("unroll") for (int n = 0; n < 2; ++n) _Pragma("unroll") for (int k = 0; k < 2; ++k) dst[n][k] = *(const PG8_LAS bf16x8*)(lds + PG8_SB(b, h) + boff + n * 2048 + k * 1024); } while (0)
; #define PG8_MMA(ai, bj, At, Bt) do { __builtin_amdgcn_s_setprio(1); _Pragma("unroll") for (int m = 0; m < 4; ++m) _Pragma("unroll") for (int n = 0; n < 2; ++n) _Pragma("unroll") for (int k = 0; k < 2; ++k) \
;         acc[ai][bj][m][n] = __builtin_amdgcn_mfma_f32_16x16x32_bf16(Bt[n][k], At[m][k], acc[ai][bj][m][n], 0, 0, 0); __builtin_amdgcn_s_setprio(0); } while (0)
; #define PG8_WAIT_V(n) asm volatile("s_waitcnt vmcnt(" #n ")" ::: "memory")
; #define PG8_WAIT_L(n) asm volatile("s_waitcnt lgkmcnt(" #n ")" ::: "memory")
; #define PG8_BAR __builtin_amdgcn_s_barrier()
; #define PG8_SCHED __builtin_amdgcn_sched_barrier(0)
; template <class Epi, class Sched, bool ALIGN_EPI = false, bool SP2 = false>
; __device__ __forceinline__ void gemm_phase(PG8_LAS unsigned char* lds, const Gemm g, const Sched& S, const Epi& E) {
;     ...
;             PG8_WAIT_V(8); PG8_WAIT_L(0); PG8_BAR; PG8_MMA(1, 0, At, B0); PG8_MMA(1, 1, At, B1); PG8_BAR; PG8_SCHED;
;             PG8_LDB(B0, 1, 0); PG8_LDB(B1, 1, 1); PG8_SCHED; PG8_LDA(At, 1, 0); PG8_STAGE(PG8_SA(0, 1), a2 + hstep, voffA);
;             PG8_WAIT_V(8); PG8_WAIT_L(0); PG8_BAR; PG8_MMA(0, 0, At, B0); PG8_MMA(0, 1, At, B1); PG8_BAR; PG8_SCHED;
	v_mfma_f32_16x16x32_bf16 v[60:63], v[128:131], v[192:195], v[60:63]
	v_mfma_f32_16x16x32_bf16 v[56:59], v[136:139], v[192:195], v[56:59]
	v_mfma_f32_16x16x32_bf16 v[44:47], v[128:131], v[200:203], v[44:47]
	v_mfma_f32_16x16x32_bf16 v[40:43], v[136:139], v[200:203], v[40:43]
	v_mfma_f32_16x16x32_bf16 v[28:31], v[128:131], v[208:211], v[28:31]
	v_mfma_f32_16x16x32_bf16 v[24:27], v[136:139], v[208:211], v[24:27]
	v_mfma_f32_16x16x32_bf16 v[12:15], v[128:131], v[216:219], v[12:15]
	v_mfma_f32_16x16x32_bf16 v[8:11], v[136:139], v[216:219], v[8:11]
	v_mfma_f32_16x16x32_bf16 v[60:63], v[132:135], v[196:199], v[60:63]
	v_mfma_f32_16x16x32_bf16 v[56:59], v[140:143], v[196:199], v[56:59]
	v_mfma_f32_16x16x32_bf16 v[44:47], v[132:135], v[204:207], v[44:47]
	v_mfma_f32_16x16x32_bf16 v[40:43], v[140:143], v[204:207], v[40:43]
	v_mfma_f32_16x16x32_bf16 v[28:31], v[132:135], v[212:215], v[28:31]
	v_mfma_f32_16x16x32_bf16 v[24:27], v[140:143], v[212:215], v[24:27]
	v_mfma_f32_16x16x32_bf16 v[12:15], v[132:135], v[220:223], v[12:15]
	v_mfma_f32_16x16x32_bf16 v[8:11], v[140:143], v[220:223], v[8:11]
	s_setprio 0
	s_setprio 1
	v_mfma_f32_16x16x32_bf16 v[52:55], v[160:163], v[192:195], v[52:55]
	v_mfma_f32_16x16x32_bf16 v[48:51], v[184:187], v[192:195], v[48:51]
	v_mfma_f32_16x16x32_bf16 v[36:39], v[160:163], v[200:203], v[36:39]
	v_mfma_f32_16x16x32_bf16 v[32:35], v[184:187], v[200:203], v[32:35]
	v_mfma_f32_16x16x32_bf16 v[20:23], v[160:163], v[208:211], v[20:23]
	v_mfma_f32_16x16x32_bf16 v[16:19], v[184:187], v[208:211], v[16:19]
	v_mfma_f32_16x16x32_bf16 v[4:7], v[160:163], v[216:219], v[4:7]
	v_mfma_f32_16x16x32_bf16 v[0:3], v[184:187], v[216:219], v[0:3]
	v_mfma_f32_16x16x32_bf16 v[52:55], v[164:167], v[196:199], v[52:55]
	v_mfma_f32_16x16x32_bf16 v[48:51], v[188:191], v[196:199], v[48:51]
	v_mfma_f32_16x16x32_bf16 v[36:39], v[164:167], v[204:207], v[36:39]
	v_mfma_f32_16x16x32_bf16 v[32:35], v[188:191], v[204:207], v[32:35]
	v_mfma_f32_16x16x32_bf16 v[20:23], v[164:167], v[212:215], v[20:23]
	s_setprio 2
	s_barrier
	v_mfma_f32_16x16x32_bf16 v[16:19], v[188:191], v[212:215], v[16:19]
	v_mfma_f32_16x16x32_bf16 v[4:7], v[164:167], v[220:223], v[4:7]
	v_mfma_f32_16x16x32_bf16 v[0:3], v[188:191], v[220:223], v[0:3]
	s_setprio 0
	s_add_i32 s56, 0, 0x18000
	s_add_i32 s57, 0, 0x1c000
	v_add_u32_e32 v140, s56, v171
	v_add_u32_e32 v188, s57, v171
	ds_read_b128 v[128:131], v140
	ds_read_b128 v[132:135], v140 offset:1024
	ds_read_b128 v[136:139], v140 offset:2048
	ds_read_b128 v[140:143], v140 offset:3072
	ds_read_b128 v[160:163], v188
	ds_read_b128 v[164:167], v188 offset:1024
	ds_read_b128 v[184:187], v188 offset:2048
	ds_read_b128 v[188:191], v188 offset:3072
	s_add_u32 s52, s76, 0x80000
	s_addc_u32 s53, s77, 0
	s_mov_b32 m0, s80
	v_lshl_add_u64 v[230:231], s[52:53], 0, v[144:145]
	ds_read_b128 v[192:195], v182 offset:32768
	ds_read_b128 v[196:199], v182 offset:33792
	ds_read_b128 v[200:203], v182 offset:34816
	ds_read_b128 v[204:207], v182 offset:35840
	ds_read_b128 v[208:211], v182 offset:36864
	ds_read_b128 v[212:215], v182 offset:37888
	ds_read_b128 v[216:219], v182 offset:38912
	ds_read_b128 v[220:223], v182 offset:39936
	global_load_lds_dwordx4 v[230:231], off
	v_lshl_add_u64 v[230:231], s[52:53], 0, v[150:151]
	s_mov_b32 m0, s81
	s_nop 0
	global_load_lds_dwordx4 v[230:231], off
	s_waitcnt vmcnt(8)
	s_waitcnt lgkmcnt(0)
	s_setprio 1
	s_barrier
	v_mfma_f32_16x16x32_bf16 v[124:127], v[128:131], v[192:195], v[124:127]
	v_mfma_f32_16x16x32_bf16 v[120:123], v[136:139], v[192:195], v[120:123]
	v_mfma_f32_16x16x32_bf16 v[108:111], v[128:131], v[200:203], v[108:111]
	v_mfma_f32_16x16x32_bf16 v[104:107], v[136:139], v[200:203], v[104:107]
	v_mfma_f32_16x16x32_bf16 v[92:95], v[128:131], v[208:211], v[92:95]
	v_mfma_f32_16x16x32_bf16 v[88:91], v[136:139], v[208:211], v[88:91]
	v_mfma_f32_16x16x32_bf16 v[76:79], v[128:131], v[216:219], v[76:79]
	v_mfma_f32_16x16x32_bf16 v[72:75], v[136:139], v[216:219], v[72:75]
	v_mfma_f32_16x16x32_bf16 v[124:127], v[132:135], v[196:199], v[124:127]
	v_mfma_f32_16x16x32_bf16 v[120:123], v[140:143], v[196:199], v[120:123]
	v_mfma_f32_16x16x32_bf16 v[108:111], v[132:135], v[204:207], v[108:111]
	v_mfma_f32_16x16x32_bf16 v[104:107], v[140:143], v[204:207], v[104:107]
	v_mfma_f32_16x16x32_bf16 v[92:95], v[132:135], v[212:215], v[92:95]
	v_mfma_f32_16x16x32_bf16 v[88:91], v[140:143], v[212:215], v[88:91]
	v_mfma_f32_16x16x32_bf16 v[76:79], v[132:135], v[220:223], v[76:79]
	v_mfma_f32_16x16x32_bf16 v[72:75], v[140:143], v[220:223], v[72:75]
	s_setprio 0
	s_setprio 1
	v_mfma_f32_16x16x32_bf16 v[116:119], v[160:163], v[192:195], v[116:119]
	v_mfma_f32_16x16x32_bf16 v[112:115], v[184:187], v[192:195], v[112:115]
	v_mfma_f32_16x16x32_bf16 v[100:103], v[160:163], v[200:203], v[100:103]
	v_mfma_f32_16x16x32_bf16 v[96:99], v[184:187], v[200:203], v[96:99]
	v_mfma_f32_16x16x32_bf16 v[84:87], v[160:163], v[208:211], v[84:87]
	v_mfma_f32_16x16x32_bf16 v[80:83], v[184:187], v[208:211], v[80:83]
	v_mfma_f32_16x16x32_bf16 v[68:71], v[160:163], v[216:219], v[68:71]
	v_mfma_f32_16x16x32_bf16 v[64:67], v[184:187], v[216:219], v[64:67]
	v_mfma_f32_16x16x32_bf16 v[116:119], v[164:167], v[196:199], v[116:119]
	v_mfma_f32_16x16x32_bf16 v[112:115], v[188:191], v[196:199], v[112:115]
	v_mfma_f32_16x16x32_bf16 v[100:103], v[164:167], v[204:207], v[100:103]
	v_mfma_f32_16x16x32_bf16 v[96:99], v[188:191], v[204:207], v[96:99]
	v_mfma_f32_16x16x32_bf16 v[84:87], v[164:167], v[212:215], v[84:87]
	s_setprio 2
	s_barrier
; #define PG8_STAGE(bufoff, gbase, voff) do { _Pragma("unroll") for (int _i = 0; _i < 2; ++_i) \
;         __builtin_amdgcn_global_load_lds((const unsigned*)((const char*)(gbase) + (voff)[_i]), (PG8_LAS unsigned*)(lds + (bufoff) + ldsw + _i * 8192), 16, 0, 0); } while (0)
; #define PG8_LDA(dst, b, h) do { _Pragma("unroll") for (int m = 0; m < 4; ++m) _Pragma("unroll") for (int k = 0; k < 2; ++k) dst[m][k] = *(const PG8_LAS bf16x8*)(lds + PG8_SA(b, h) + aoff + m * 2048 + k * 1024); } while (0)
; #define PG8_MMA(ai, bj, At, Bt) do { __builtin_amdgcn_s_setprio(1); _Pragma("unroll") for (int m = 0; m < 4; ++m) _Pragma("unroll") for (int n = 0; n < 2; ++n) _Pragma("unroll") for (int k = 0; k < 2; ++k) \
;         acc[ai][bj][m][n] = __builtin_amdgcn_mfma_f32_16x16x32_bf16(Bt[n][k], At[m][k], acc[ai][bj][m][n], 0, 0, 0); __builtin_amdgcn_s_setprio(0); } while (0)
; #define PG8_WAIT_V(n) asm volatile("s_waitcnt vmcnt(" #n ")" ::: "memory")
; #define PG8_WAIT_L(n) asm volatile("s_waitcnt lgkmcnt(" #n ")" ::: "memory")
; #define PG8_BAR __builtin_amdgcn_s_barrier()
; #define PG8_SCHED __builtin_amdgcn_sched_barrier(0)
; template <class Epi, class Sched, bool ALIGN_EPI = false, bool SP2 = false>
; __device__ __forceinline__ void gemm_phase(PG8_LAS unsigned char* lds, const Gemm g, const Sched& S, const Epi& E) {
;     ...
;             PG8_WAIT_V(8); PG8_WAIT_L(0); PG8_BAR; PG8_MMA(0, 0, At, B0); PG8_MMA(0, 1, At, B1); PG8_BAR; PG8_SCHED;
;             PG8_LDA(At, 1, 1); PG8_STAGE(PG8_SB(1, 0), b3, voffB); PG8_STAGE(PG8_SB(1, 1), b3 + hstep, voffB); PG8_STAGE(PG8_SA(1, 0), a3, voffA);
;             PG8_WAIT_V(8); PG8_WAIT_L(0); PG8_BAR; PG8_MMA(1, 0, At, B0); PG8_MMA(1, 1, At, B1); PG8_BAR; PG8_SCHED;
;     ...
;         if constexpr (ALIGN_EPI) { if (wr == 0) PG8_BAR; }
	v_mfma_f32_16x16x32_bf16 v[80:83], v[188:191], v[212:215], v[80:83]
	v_mfma_f32_16x16x32_bf16 v[68:71], v[164:167], v[220:223], v[68:71]
	v_mfma_f32_16x16x32_bf16 v[64:67], v[188:191], v[220:223], v[64:67]
	s_setprio 0
	s_add_i32 s52, s56, s78
	v_lshl_add_u64 v[168:169], v[168:169], 0, s[40:41]
	s_mov_b32 m0, s52
	ds_read_b128 v[192:195], v182 offset:49152
	ds_read_b128 v[196:199], v182 offset:50176
	ds_read_b128 v[200:203], v182 offset:51200
	ds_read_b128 v[204:207], v182 offset:52224
	ds_read_b128 v[208:211], v182 offset:53248
	ds_read_b128 v[212:215], v182 offset:54272
	ds_read_b128 v[216:219], v182 offset:55296
	ds_read_b128 v[220:223], v182 offset:56320
	global_load_lds_dwordx4 v[168:169], off
	s_add_i32 m0, s52, 0x2000
	s_add_u32 s52, s74, 0x80080
	v_lshl_add_u64 v[168:169], v[224:225], 0, s[40:41]
	s_addc_u32 s53, s75, 0
	s_add_i32 s56, s57, s78
	global_load_lds_dwordx4 v[168:169], off
	v_lshl_add_u64 v[168:169], s[52:53], 0, v[148:149]
	s_mov_b32 m0, s56
	s_nop 0
	global_load_lds_dwordx4 v[168:169], off
	v_lshl_add_u64 v[168:169], s[52:53], 0, v[152:153]
	s_add_i32 m0, s56, 0x2000
	s_nop 0
	global_load_lds_dwordx4 v[168:169], off
	v_lshl_add_u64 v[168:169], v[226:227], 0, s[40:41]
	s_mov_b32 m0, s3
	s_nop 0
	global_load_lds_dwordx4 v[168:169], off
	v_lshl_add_u64 v[168:169], v[228:229], 0, s[40:41]
	s_mov_b32 m0, s28
	s_nop 0
	global_load_lds_dwordx4 v[168:169], off
	s_waitcnt vmcnt(8)
	s_waitcnt lgkmcnt(0)
	s_setprio 1
	s_barrier
	v_mfma_f32_16x16x32_bf16 v[60:63], v[128:131], v[192:195], v[60:63]
	v_mfma_f32_16x16x32_bf16 v[56:59], v[136:139], v[192:195], v[56:59]
	v_mfma_f32_16x16x32_bf16 v[44:47], v[128:131], v[200:203], v[44:47]
	v_mfma_f32_16x16x32_bf16 v[40:43], v[136:139], v[200:203], v[40:43]
	v_mfma_f32_16x16x32_bf16 v[28:31], v[128:131], v[208:211], v[28:31]
	v_mfma_f32_16x16x32_bf16 v[24:27], v[136:139], v[208:211], v[24:27]
	v_mfma_f32_16x16x32_bf16 v[12:15], v[128:131], v[216:219], v[12:15]
	v_mfma_f32_16x16x32_bf16 v[8:11], v[136:139], v[216:219], v[8:11]
	v_mfma_f32_16x16x32_bf16 v[60:63], v[132:135], v[196:199], v[60:63]
	v_mfma_f32_16x16x32_bf16 v[56:59], v[140:143], v[196:199], v[56:59]
	v_mfma_f32_16x16x32_bf16 v[44:47], v[132:135], v[204:207], v[44:47]
	v_mfma_f32_16x16x32_bf16 v[40:43], v[140:143], v[204:207], v[40:43]
	v_mfma_f32_16x16x32_bf16 v[28:31], v[132:135], v[212:215], v[28:31]
	v_mfma_f32_16x16x32_bf16 v[24:27], v[140:143], v[212:215], v[24:27]
	v_mfma_f32_16x16x32_bf16 v[12:15], v[132:135], v[220:223], v[12:15]
	v_mfma_f32_16x16x32_bf16 v[8:11], v[140:143], v[220:223], v[8:11]
	s_setprio 0
	s_setprio 1
	v_mfma_f32_16x16x32_bf16 v[52:55], v[160:163], v[192:195], v[52:55]
	v_mfma_f32_16x16x32_bf16 v[48:51], v[184:187], v[192:195], v[48:51]
	v_mfma_f32_16x16x32_bf16 v[36:39], v[160:163], v[200:203], v[36:39]
	v_mfma_f32_16x16x32_bf16 v[32:35], v[184:187], v[200:203], v[32:35]
	v_mfma_f32_16x16x32_bf16 v[20:23], v[160:163], v[208:211], v[20:23]
	v_mfma_f32_16x16x32_bf16 v[16:19], v[184:187], v[208:211], v[16:19]
	v_mfma_f32_16x16x32_bf16 v[4:7], v[160:163], v[216:219], v[4:7]
	v_mfma_f32_16x16x32_bf16 v[0:3], v[184:187], v[216:219], v[0:3]
	v_mfma_f32_16x16x32_bf16 v[52:55], v[164:167], v[196:199], v[52:55]
	v_mfma_f32_16x16x32_bf16 v[48:51], v[188:191], v[196:199], v[48:51]
	v_mfma_f32_16x16x32_bf16 v[36:39], v[164:167], v[204:207], v[36:39]
	v_mfma_f32_16x16x32_bf16 v[32:35], v[188:191], v[204:207], v[32:35]
	v_mfma_f32_16x16x32_bf16 v[20:23], v[164:167], v[212:215], v[20:23]
	s_setprio 2
	s_barrier
	v_mfma_f32_16x16x32_bf16 v[16:19], v[188:191], v[212:215], v[16:19]
	v_mfma_f32_16x16x32_bf16 v[4:7], v[164:167], v[220:223], v[4:7]
	v_mfma_f32_16x16x32_bf16 v[0:3], v[188:191], v[220:223], v[0:3]
	s_setprio 0
	s_add_i32 s92, s92, 2
	s_add_u32 s72, s72, 0x100
	s_addc_u32 s73, s73, 0
	s_add_u32 s90, s90, 0x100
	s_addc_u32 s91, s91, 0
	s_cmp_gt_u32 s92, 29
	s_cbranch_scc0 .LBB0_809
	s_and_b64 vcc, exec, s[42:43]
	s_cbranch_vccz .LBB0_812
	s_barrier

; #define PG8_STAGE(bufoff, gbase, voff) do { _Pragma("unroll") for (int _i = 0; _i < 2; ++_i) \
;         __builtin_amdgcn_global_load_lds((const unsigned*)((const char*)(gbase) + (voff)[_i]), (PG8_LAS unsigned*)(lds + (bufoff) + ldsw + _i * 8192), 16, 0, 0); } while (0)
; #define PG8_LDA(dst, b, h) do { _Pragma("unroll") for (int m = 0; m < 4; ++m) _Pragma("unroll") for (int k = 0; k < 2; ++k) dst[m][k] = *(const PG8_LAS bf16x8*)(lds + PG8_SA(b, h) + aoff + m * 2048 + k * 1024); } while (0)
; #define PG8_LDB(dst, b, h) do { _Pragma("unroll") for (int n = 0; n < 2; ++n) _Pragma("unroll") for (int k = 0; k < 2; ++k) dst[n][k] = *(const PG8_LAS bf16x8*)(lds + PG8_SB(b, h) + boff + n * 2048 + k * 1024); } while (0)
; #define PG8_MMA(ai, bj, At, Bt) do { __builtin_amdgcn_s_setprio(1); _Pragma("unroll") for (int m = 0; m < 4; ++m) _Pragma("unroll") for (int n = 0; n < 2; ++n) _Pragma("unroll") for (int k = 0; k < 2; ++k) \
;         acc[ai][bj][m][n] = __builtin_amdgcn_mfma_f32_16x16x32_bf16(Bt[n][k], At[m][k], acc[ai][bj][m][n], 0, 0, 0); __builtin_amdgcn_s_setprio(0); } while (0)
; #define PG8_WAIT_V(n) asm volatile("s_waitcnt vmcnt(" #n ")" ::: "memory")
; #define PG8_WAIT_L(n) asm volatile("s_waitcnt lgkmcnt(" #n ")" ::: "memory")
; #define PG8_BAR __builtin_amdgcn_s_barrier()
; #define PG8_SCHED __builtin_amdgcn_sched_barrier(0)
; template <class Epi, class Sched, bool ALIGN_EPI = false, bool SP2 = false>
; __device__ __forceinline__ void gemm_phase(PG8_LAS unsigned char* lds, const Gemm g, const Sched& S, const Epi& E) {
;     ...
;             const bool last = (t == nt - 2);
;             const char* a1 = cA + (size_t)(t + 1) * kstep;
;             const char* a2 = last ? nA : cA + (size_t)(t + 2) * kstep; const char* b2 = last ? nB : cB + (size_t)(t + 2) * kstep;
;             const char* a3 = a2 + kstep; const char* b3 = b2 + kstep;
;             if constexpr (SP2) {
;             PG8_LDB(B0, 0, 0); PG8_LDB(B1, 0, 1); PG8_SCHED; PG8_LDA(At, 0, 0); PG8_STAGE(PG8_SA(1, 1), a1 + hstep, voffA);
;             PG8_WAIT_V(8); PG8_WAIT_L(0); PG8_BAR; PG8_MMA(0, 0, At, B0); PG8_MMA(0, 1, At, B1); PG8_BAR; PG8_SCHED;
;             PG8_LDA(At, 0, 1); PG8_STAGE(PG8_SB(0, 0), b2, voffB); PG8_STAGE(PG8_SB(0, 1), b2 + hstep, voffB); PG8_STAGE(PG8_SA(0, 0), a2, voffA);
.LBB0_1051:
	ds_read_b128 v[128:131], v205
	ds_read_b128 v[132:135], v205 offset:1024
	ds_read_b128 v[154:157], v205 offset:2048
	ds_read_b128 v[158:161], v205 offset:3072
	ds_read_b128 v[162:165], v206
	ds_read_b128 v[166:169], v206 offset:1024
	ds_read_b128 v[170:173], v206 offset:2048
	ds_read_b128 v[174:177], v206 offset:3072
	s_add_u32 s54, s52, 0xfff80080
	s_addc_u32 s55, s53, -1
	s_cmp_eq_u32 s77, 28
	s_cselect_b32 s57, s43, s55
	s_cselect_b32 s56, s49, s54
	s_cselect_b32 s55, s37, s76
	s_cselect_b32 s54, s51, s75
	v_lshl_add_u64 v[218:219], s[52:53], 0, v[144:145]
	s_add_i32 m0, s61, 0xc000
	ds_read_b128 v[178:181], v207
	ds_read_b128 v[182:185], v207 offset:1024
	ds_read_b128 v[186:189], v207 offset:2048
	ds_read_b128 v[190:193], v207 offset:3072
	ds_read_b128 v[194:197], v207 offset:4096
	ds_read_b128 v[198:201], v207 offset:5120
	ds_read_b128 v[210:213], v207 offset:6144
	ds_read_b128 v[214:217], v207 offset:7168
	global_load_lds_dwordx4 v[218:219], off
	v_lshl_add_u64 v[218:219], s[52:53], 0, v[148:149]
	s_add_i32 m0, s61, 0xe000
	s_nop 0
	global_load_lds_dwordx4 v[218:219], off
	s_waitcnt vmcnt(8)
	s_waitcnt lgkmcnt(0)
	s_setprio 1
	s_barrier
	v_mfma_f32_16x16x32_bf16 v[124:127], v[128:131], v[178:181], v[124:127]
	v_mfma_f32_16x16x32_bf16 v[120:123], v[154:157], v[178:181], v[120:123]
	v_mfma_f32_16x16x32_bf16 v[116:119], v[128:131], v[186:189], v[116:119]
	v_mfma_f32_16x16x32_bf16 v[112:115], v[154:157], v[186:189], v[112:115]
	v_mfma_f32_16x16x32_bf16 v[108:111], v[128:131], v[194:197], v[108:111]
	v_mfma_f32_16x16x32_bf16 v[104:107], v[154:157], v[194:197], v[104:107]
	v_mfma_f32_16x16x32_bf16 v[100:103], v[128:131], v[210:213], v[100:103]
	v_mfma_f32_16x16x32_bf16 v[96:99], v[154:157], v[210:213], v[96:99]
	v_mfma_f32_16x16x32_bf16 v[124:127], v[132:135], v[182:185], v[124:127]
	v_mfma_f32_16x16x32_bf16 v[120:123], v[158:161], v[182:185], v[120:123]
	v_mfma_f32_16x16x32_bf16 v[116:119], v[132:135], v[190:193], v[116:119]
	v_mfma_f32_16x16x32_bf16 v[112:115], v[158:161], v[190:193], v[112:115]
	v_mfma_f32_16x16x32_bf16 v[108:111], v[132:135], v[198:201], v[108:111]
	v_mfma_f32_16x16x32_bf16 v[104:107], v[158:161], v[198:201], v[104:107]
	v_mfma_f32_16x16x32_bf16 v[100:103], v[132:135], v[214:217], v[100:103]
	v_mfma_f32_16x16x32_bf16 v[96:99], v[158:161], v[214:217], v[96:99]
	s_setprio 0
	s_setprio 1
	v_mfma_f32_16x16x32_bf16 v[60:63], v[162:165], v[178:181], v[60:63]
	v_mfma_f32_16x16x32_bf16 v[56:59], v[170:173], v[178:181], v[56:59]
	v_mfma_f32_16x16x32_bf16 v[52:55], v[162:165], v[186:189], v[52:55]
	v_mfma_f32_16x16x32_bf16 v[48:51], v[170:173], v[186:189], v[48:51]
	v_mfma_f32_16x16x32_bf16 v[44:47], v[162:165], v[194:197], v[44:47]
	v_mfma_f32_16x16x32_bf16 v[40:43], v[170:173], v[194:197], v[40:43]
	v_mfma_f32_16x16x32_bf16 v[36:39], v[162:165], v[210:213], v[36:39]
	v_mfma_f32_16x16x32_bf16 v[32:35], v[170:173], v[210:213], v[32:35]
	v_mfma_f32_16x16x32_bf16 v[60:63], v[166:169], v[182:185], v[60:63]
	v_mfma_f32_16x16x32_bf16 v[56:59], v[174:177], v[182:185], v[56:59]
	v_mfma_f32_16x16x32_bf16 v[52:55], v[166:169], v[190:193], v[52:55]
	v_mfma_f32_16x16x32_bf16 v[48:51], v[174:177], v[190:193], v[48:51]
	v_mfma_f32_16x16x32_bf16 v[44:47], v[166:169], v[198:201], v[44:47]
	s_setprio 2
	s_barrier
	v_mfma_f32_16x16x32_bf16 v[40:43], v[174:177], v[198:201], v[40:43]
	v_mfma_f32_16x16x32_bf16 v[36:39], v[166:169], v[214:217], v[36:39]
	v_mfma_f32_16x16x32_bf16 v[32:35], v[174:177], v[214:217], v[32:35]
	s_setprio 0
	s_add_i32 s78, s33, s60
	v_lshl_add_u64 v[218:219], s[54:55], 0, v[138:139]
	s_mov_b32 m0, s78
	ds_read_b128 v[178:181], v207 offset:16384
	ds_read_b128 v[182:185], v207 offset:17408
	ds_read_b128 v[186:189], v207 offset:18432
	ds_read_b128 v[190:193], v207 offset:19456
	ds_read_b128 v[194:197], v207 offset:20480
	ds_read_b128 v[198:201], v207 offset:21504
	ds_read_b128 v[210:213], v207 offset:22528
	ds_read_b128 v[214:217], v207 offset:23552
	global_load_lds_dwordx4 v[218:219], off
	s_add_i32 m0, s78, 0x2000
	s_add_u32 s78, s54, 0x80000
	v_lshl_add_u64 v[220:221], s[54:55], 0, v[142:143]
	s_addc_u32 s79, s55, 0
	s_add_i32 s80, s74, s60
	global_load_lds_dwordx4 v[220:221], off
	v_lshl_add_u64 v[222:223], s[78:79], 0, v[138:139]
	s_mov_b32 m0, s80
	v_lshl_add_u64 v[224:225], s[56:57], 0, v[140:141]
	global_load_lds_dwordx4 v[222:223], off
	v_lshl_add_u64 v[222:223], s[78:79], 0, v[142:143]
	s_add_i32 m0, s80, 0x2000
	s_nop 0
	global_load_lds_dwordx4 v[222:223], off
	v_lshl_add_u64 v[222:223], s[56:57], 0, v[136:137]
	s_mov_b32 m0, s61
	s_nop 0
	global_load_lds_dwordx4 v[222:223], off
	s_mov_b32 m0, s62
	s_nop 0
	global_load_lds_dwordx4 v[224:225], off
	s_waitcnt vmcnt(8)
	s_waitcnt lgkmcnt(0)
	s_setprio 1
	s_barrier
; #define PG8_STAGE(bufoff, gbase, voff) do { _Pragma("unroll") for (int _i = 0; _i < 2; ++_i) \
;         __builtin_amdgcn_global_load_lds((const unsigned*)((const char*)(gbase) + (voff)[_i]), (PG8_LAS unsigned*)(lds + (bufoff) + ldsw + _i * 8192), 16, 0, 0); } while (0)
; #define PG8_LDA(dst, b, h) do { _Pragma("unroll") for (int m = 0; m < 4; ++m) _Pragma("unroll") for (int k = 0; k < 2; ++k) dst[m][k] = *(const PG8_LAS bf16x8*)(lds + PG8_SA(b, h) + aoff + m * 2048 + k * 1024); } while (0)
; #define PG8_LDB(dst, b, h) do { _Pragma("unroll") for (int n = 0; n < 2; ++n) _Pragma("unroll") for (int k = 0; k < 2; ++k) dst[n][k] = *(const PG8_LAS bf16x8*)(lds + PG8_SB(b, h) + boff + n * 2048 + k * 1024); } while (0)
; #define PG8_MMA(ai, bj, At, Bt) do { __builtin_amdgcn_s_setprio(1); _Pragma("unroll") for (int m = 0; m < 4; ++m) _Pragma("unroll") for (int n = 0; n < 2; ++n) _Pragma("unroll") for (int k = 0; k < 2; ++k) \
;         acc[ai][bj][m][n] = __builtin_amdgcn_mfma_f32_16x16x32_bf16(Bt[n][k], At[m][k], acc[ai][bj][m][n], 0, 0, 0); __builtin_amdgcn_s_setprio(0); } while (0)
; #define PG8_WAIT_V(n) asm volatile("s_waitcnt vmcnt(" #n ")" ::: "memory")
; #define PG8_WAIT_L(n) asm volatile("s_waitcnt lgkmcnt(" #n ")" ::: "memory")
; #define PG8_BAR __builtin_amdgcn_s_barrier()
; #define PG8_SCHED __builtin_amdgcn_sched_barrier(0)
; template <class Epi, class Sched, bool ALIGN_EPI = false, bool SP2 = false>
; __device__ __forceinline__ void gemm_phase(PG8_LAS unsigned char* lds, const Gemm g, const Sched& S, const Epi& E) {
;     ...
;             PG8_WAIT_V(8); PG8_WAIT_L(0); PG8_BAR; PG8_MMA(1, 0, At, B0); PG8_MMA(1, 1, At, B1); PG8_BAR; PG8_SCHED;
;             PG8_LDB(B0, 1, 0); PG8_LDB(B1, 1, 1); PG8_SCHED; PG8_LDA(At, 1, 0); PG8_STAGE(PG8_SA(0, 1), a2 + hstep, voffA);
;             PG8_WAIT_V(8); PG8_WAIT_L(0); PG8_BAR; PG8_MMA(0, 0, At, B0); PG8_MMA(0, 1, At, B1); PG8_BAR; PG8_SCHED;
	v_mfma_f32_16x16x32_bf16 v[92:95], v[128:131], v[178:181], v[92:95]
	v_mfma_f32_16x16x32_bf16 v[88:91], v[154:157], v[178:181], v[88:91]
	v_mfma_f32_16x16x32_bf16 v[84:87], v[128:131], v[186:189], v[84:87]
	v_mfma_f32_16x16x32_bf16 v[80:83], v[154:157], v[186:189], v[80:83]
	v_mfma_f32_16x16x32_bf16 v[76:79], v[128:131], v[194:197], v[76:79]
	v_mfma_f32_16x16x32_bf16 v[72:75], v[154:157], v[194:197], v[72:75]
	v_mfma_f32_16x16x32_bf16 v[68:71], v[128:131], v[210:213], v[68:71]
	v_mfma_f32_16x16x32_bf16 v[64:67], v[154:157], v[210:213], v[64:67]
	v_mfma_f32_16x16x32_bf16 v[92:95], v[132:135], v[182:185], v[92:95]
	v_mfma_f32_16x16x32_bf16 v[88:91], v[158:161], v[182:185], v[88:91]
	v_mfma_f32_16x16x32_bf16 v[84:87], v[132:135], v[190:193], v[84:87]
	v_mfma_f32_16x16x32_bf16 v[80:83], v[158:161], v[190:193], v[80:83]
	v_mfma_f32_16x16x32_bf16 v[76:79], v[132:135], v[198:201], v[76:79]
	v_mfma_f32_16x16x32_bf16 v[72:75], v[158:161], v[198:201], v[72:75]
	v_mfma_f32_16x16x32_bf16 v[68:71], v[132:135], v[214:217], v[68:71]
	v_mfma_f32_16x16x32_bf16 v[64:67], v[158:161], v[214:217], v[64:67]
	s_setprio 0
	s_setprio 1
	v_mfma_f32_16x16x32_bf16 v[28:31], v[162:165], v[178:181], v[28:31]
	v_mfma_f32_16x16x32_bf16 v[24:27], v[170:173], v[178:181], v[24:27]
	v_mfma_f32_16x16x32_bf16 v[20:23], v[162:165], v[186:189], v[20:23]
	v_mfma_f32_16x16x32_bf16 v[16:19], v[170:173], v[186:189], v[16:19]
	v_mfma_f32_16x16x32_bf16 v[12:15], v[162:165], v[194:197], v[12:15]
	v_mfma_f32_16x16x32_bf16 v[8:11], v[170:173], v[194:197], v[8:11]
	v_mfma_f32_16x16x32_bf16 v[4:7], v[162:165], v[210:213], v[4:7]
	v_mfma_f32_16x16x32_bf16 v[0:3], v[170:173], v[210:213], v[0:3]
	v_mfma_f32_16x16x32_bf16 v[28:31], v[166:169], v[182:185], v[28:31]
	v_mfma_f32_16x16x32_bf16 v[24:27], v[174:177], v[182:185], v[24:27]
	v_mfma_f32_16x16x32_bf16 v[20:23], v[166:169], v[190:193], v[20:23]
	v_mfma_f32_16x16x32_bf16 v[16:19], v[174:177], v[190:193], v[16:19]
	v_mfma_f32_16x16x32_bf16 v[12:15], v[166:169], v[198:201], v[12:15]
	s_setprio 2
	s_barrier
	v_mfma_f32_16x16x32_bf16 v[8:11], v[174:177], v[198:201], v[8:11]
	v_mfma_f32_16x16x32_bf16 v[4:7], v[166:169], v[214:217], v[4:7]
	v_mfma_f32_16x16x32_bf16 v[0:3], v[174:177], v[214:217], v[0:3]
	s_setprio 0
	s_add_i32 s78, 0, 0x18000
	s_add_i32 s79, 0, 0x1c000
	v_add_u32_e32 v158, s78, v203
	v_add_u32_e32 v174, s79, v203
	ds_read_b128 v[128:131], v158
	ds_read_b128 v[132:135], v158 offset:1024
	ds_read_b128 v[154:157], v158 offset:2048
	ds_read_b128 v[158:161], v158 offset:3072
	ds_read_b128 v[162:165], v174
	ds_read_b128 v[166:169], v174 offset:1024
	ds_read_b128 v[170:173], v174 offset:2048
	ds_read_b128 v[174:177], v174 offset:3072
	s_add_u32 s56, s56, 0x80000
	s_addc_u32 s57, s57, 0
	s_mov_b32 m0, s63
	v_lshl_add_u64 v[226:227], s[56:57], 0, v[136:137]
	ds_read_b128 v[178:181], v207 offset:32768
	ds_read_b128 v[182:185], v207 offset:33792
	ds_read_b128 v[186:189], v207 offset:34816
	ds_read_b128 v[190:193], v207 offset:35840
	ds_read_b128 v[194:197], v207 offset:36864
	ds_read_b128 v[198:201], v207 offset:37888
	ds_read_b128 v[210:213], v207 offset:38912
	ds_read_b128 v[214:217], v207 offset:39936
	global_load_lds_dwordx4 v[226:227], off
	v_lshl_add_u64 v[226:227], s[56:57], 0, v[140:141]
	s_mov_b32 m0, s64
	s_nop 0
	global_load_lds_dwordx4 v[226:227], off
	s_waitcnt vmcnt(8)
	s_waitcnt lgkmcnt(0)
	s_setprio 1
	s_barrier
	v_mfma_f32_16x16x32_bf16 v[124:127], v[128:131], v[178:181], v[124:127]
	v_mfma_f32_16x16x32_bf16 v[120:123], v[154:157], v[178:181], v[120:123]
	v_mfma_f32_16x16x32_bf16 v[116:119], v[128:131], v[186:189], v[116:119]
	v_mfma_f32_16x16x32_bf16 v[112:115], v[154:157], v[186:189], v[112:115]
	v_mfma_f32_16x16x32_bf16 v[108:111], v[128:131], v[194:197], v[108:111]
	v_mfma_f32_16x16x32_bf16 v[104:107], v[154:157], v[194:197], v[104:107]
	v_mfma_f32_16x16x32_bf16 v[100:103], v[128:131], v[210:213], v[100:103]
	v_mfma_f32_16x16x32_bf16 v[96:99], v[154:157], v[210:213], v[96:99]
	v_mfma_f32_16x16x32_bf16 v[124:127], v[132:135], v[182:185], v[124:127]
	v_mfma_f32_16x16x32_bf16 v[120:123], v[158:161], v[182:185], v[120:123]
	v_mfma_f32_16x16x32_bf16 v[116:119], v[132:135], v[190:193], v[116:119]
	v_mfma_f32_16x16x32_bf16 v[112:115], v[158:161], v[190:193], v[112:115]
	v_mfma_f32_16x16x32_bf16 v[108:111], v[132:135], v[198:201], v[108:111]
	v_mfma_f32_16x16x32_bf16 v[104:107], v[158:161], v[198:201], v[104:107]
	v_mfma_f32_16x16x32_bf16 v[100:103], v[132:135], v[214:217], v[100:103]
	v_mfma_f32_16x16x32_bf16 v[96:99], v[158:161], v[214:217], v[96:99]
	s_setprio 0
	s_setprio 1
	v_mfma_f32_16x16x32_bf16 v[60:63], v[162:165], v[178:181], v[60:63]
	v_mfma_f32_16x16x32_bf16 v[56:59], v[170:173], v[178:181], v[56:59]
	v_mfma_f32_16x16x32_bf16 v[52:55], v[162:165], v[186:189], v[52:55]
	v_mfma_f32_16x16x32_bf16 v[48:51], v[170:173], v[186:189], v[48:51]
	v_mfma_f32_16x16x32_bf16 v[44:47], v[162:165], v[194:197], v[44:47]
	v_mfma_f32_16x16x32_bf16 v[40:43], v[170:173], v[194:197], v[40:43]
	v_mfma_f32_16x16x32_bf16 v[36:39], v[162:165], v[210:213], v[36:39]
	v_mfma_f32_16x16x32_bf16 v[32:35], v[170:173], v[210:213], v[32:35]
	v_mfma_f32_16x16x32_bf16 v[60:63], v[166:169], v[182:185], v[60:63]
	v_mfma_f32_16x16x32_bf16 v[56:59], v[174:177], v[182:185], v[56:59]
	v_mfma_f32_16x16x32_bf16 v[52:55], v[166:169], v[190:193], v[52:55]
	v_mfma_f32_16x16x32_bf16 v[48:51], v[174:177], v[190:193], v[48:51]
	v_mfma_f32_16x16x32_bf16 v[44:47], v[166:169], v[198:201], v[44:47]
	s_setprio 2
	s_barrier
; #define PG8_STAGE(bufoff, gbase, voff) do { _Pragma("unroll") for (int _i = 0; _i < 2; ++_i) \
;         __builtin_amdgcn_global_load_lds((const unsigned*)((const char*)(gbase) + (voff)[_i]), (PG8_LAS unsigned*)(lds + (bufoff) + ldsw + _i * 8192), 16, 0, 0); } while (0)
; #define PG8_LDA(dst, b, h) do { _Pragma("unroll") for (int m = 0; m < 4; ++m) _Pragma("unroll") for (int k = 0; k < 2; ++k) dst[m][k] = *(const PG8_LAS bf16x8*)(lds + PG8_SA(b, h) + aoff + m * 2048 + k * 1024); } while (0)
; #define PG8_MMA(ai, bj, At, Bt) do { __builtin_amdgcn_s_setprio(1); _Pragma("unroll") for (int m = 0; m < 4; ++m) _Pragma("unroll") for (int n = 0; n < 2; ++n) _Pragma("unroll") for (int k = 0; k < 2; ++k) \
;         acc[ai][bj][m][n] = __builtin_amdgcn_mfma_f32_16x16x32_bf16(Bt[n][k], At[m][k], acc[ai][bj][m][n], 0, 0, 0); __builtin_amdgcn_s_setprio(0); } while (0)
; #define PG8_WAIT_V(n) asm volatile("s_waitcnt vmcnt(" #n ")" ::: "memory")
; #define PG8_WAIT_L(n) asm volatile("s_waitcnt lgkmcnt(" #n ")" ::: "memory")
; #define PG8_BAR __builtin_amdgcn_s_barrier()
; #define PG8_SCHED __builtin_amdgcn_sched_barrier(0)
; template <class Epi, class Sched, bool ALIGN_EPI = false, bool SP2 = false>
; __device__ __forceinline__ void gemm_phase(PG8_LAS unsigned char* lds, const Gemm g, const Sched& S, const Epi& E) {
;     ...
;             PG8_WAIT_V(8); PG8_WAIT_L(0); PG8_BAR; PG8_MMA(0, 0, At, B0); PG8_MMA(0, 1, At, B1); PG8_BAR; PG8_SCHED;
;             PG8_LDA(At, 1, 1); PG8_STAGE(PG8_SB(1, 0), b3, voffB); PG8_STAGE(PG8_SB(1, 1), b3 + hstep, voffB); PG8_STAGE(PG8_SA(1, 0), a3, voffA);
;             PG8_WAIT_V(8); PG8_WAIT_L(0); PG8_BAR; PG8_MMA(1, 0, At, B0); PG8_MMA(1, 1, At, B1); PG8_BAR; PG8_SCHED;
;     ...
;         if constexpr (ALIGN_EPI) { if (wr == 0) PG8_BAR; }
	v_mfma_f32_16x16x32_bf16 v[40:43], v[174:177], v[198:201], v[40:43]
	v_mfma_f32_16x16x32_bf16 v[36:39], v[166:169], v[214:217], v[36:39]
	v_mfma_f32_16x16x32_bf16 v[32:35], v[174:177], v[214:217], v[32:35]
	s_setprio 0
	s_add_i32 s56, s78, s60
	v_lshl_add_u64 v[218:219], v[218:219], 0, s[12:13]
	s_mov_b32 m0, s56
	ds_read_b128 v[178:181], v207 offset:49152
	ds_read_b128 v[182:185], v207 offset:50176
	ds_read_b128 v[186:189], v207 offset:51200
	ds_read_b128 v[190:193], v207 offset:52224
	ds_read_b128 v[194:197], v207 offset:53248
	ds_read_b128 v[198:201], v207 offset:54272
	ds_read_b128 v[210:213], v207 offset:55296
	ds_read_b128 v[214:217], v207 offset:56320
	global_load_lds_dwordx4 v[218:219], off
	s_add_i32 m0, s56, 0x2000
	s_add_u32 s54, s54, 0x80080
	v_lshl_add_u64 v[218:219], v[220:221], 0, s[12:13]
	s_addc_u32 s55, s55, 0
	s_add_i32 s56, s79, s60
	global_load_lds_dwordx4 v[218:219], off
	v_lshl_add_u64 v[218:219], s[54:55], 0, v[138:139]
	s_mov_b32 m0, s56
	s_nop 0
	global_load_lds_dwordx4 v[218:219], off
	v_lshl_add_u64 v[218:219], s[54:55], 0, v[142:143]
	s_add_i32 m0, s56, 0x2000
	s_nop 0
	global_load_lds_dwordx4 v[218:219], off
	v_lshl_add_u64 v[218:219], v[222:223], 0, s[12:13]
	s_mov_b32 m0, s70
	s_nop 0
	global_load_lds_dwordx4 v[218:219], off
	v_lshl_add_u64 v[218:219], v[224:225], 0, s[12:13]
	s_mov_b32 m0, s71
	s_nop 0
	global_load_lds_dwordx4 v[218:219], off
	s_waitcnt vmcnt(8)
	s_waitcnt lgkmcnt(0)
	s_setprio 1
	s_barrier
	v_mfma_f32_16x16x32_bf16 v[92:95], v[128:131], v[178:181], v[92:95]
	v_mfma_f32_16x16x32_bf16 v[88:91], v[154:157], v[178:181], v[88:91]
	v_mfma_f32_16x16x32_bf16 v[84:87], v[128:131], v[186:189], v[84:87]
	v_mfma_f32_16x16x32_bf16 v[80:83], v[154:157], v[186:189], v[80:83]
	v_mfma_f32_16x16x32_bf16 v[76:79], v[128:131], v[194:197], v[76:79]
	v_mfma_f32_16x16x32_bf16 v[72:75], v[154:157], v[194:197], v[72:75]
	v_mfma_f32_16x16x32_bf16 v[68:71], v[128:131], v[210:213], v[68:71]
	v_mfma_f32_16x16x32_bf16 v[64:67], v[154:157], v[210:213], v[64:67]
	v_mfma_f32_16x16x32_bf16 v[92:95], v[132:135], v[182:185], v[92:95]
	v_mfma_f32_16x16x32_bf16 v[88:91], v[158:161], v[182:185], v[88:91]
	v_mfma_f32_16x16x32_bf16 v[84:87], v[132:135], v[190:193], v[84:87]
	v_mfma_f32_16x16x32_bf16 v[80:83], v[158:161], v[190:193], v[80:83]
	v_mfma_f32_16x16x32_bf16 v[76:79], v[132:135], v[198:201], v[76:79]
	v_mfma_f32_16x16x32_bf16 v[72:75], v[158:161], v[198:201], v[72:75]
	v_mfma_f32_16x16x32_bf16 v[68:71], v[132:135], v[214:217], v[68:71]
	v_mfma_f32_16x16x32_bf16 v[64:67], v[158:161], v[214:217], v[64:67]
	s_setprio 0
	s_setprio 1
	v_mfma_f32_16x16x32_bf16 v[28:31], v[162:165], v[178:181], v[28:31]
	v_mfma_f32_16x16x32_bf16 v[24:27], v[170:173], v[178:181], v[24:27]
	v_mfma_f32_16x16x32_bf16 v[20:23], v[162:165], v[186:189], v[20:23]
	v_mfma_f32_16x16x32_bf16 v[16:19], v[170:173], v[186:189], v[16:19]
	v_mfma_f32_16x16x32_bf16 v[12:15], v[162:165], v[194:197], v[12:15]
	v_mfma_f32_16x16x32_bf16 v[8:11], v[170:173], v[194:197], v[8:11]
	v_mfma_f32_16x16x32_bf16 v[4:7], v[162:165], v[210:213], v[4:7]
	v_mfma_f32_16x16x32_bf16 v[0:3], v[170:173], v[210:213], v[0:3]
	v_mfma_f32_16x16x32_bf16 v[28:31], v[166:169], v[182:185], v[28:31]
	v_mfma_f32_16x16x32_bf16 v[24:27], v[174:177], v[182:185], v[24:27]
	v_mfma_f32_16x16x32_bf16 v[20:23], v[166:169], v[190:193], v[20:23]
	v_mfma_f32_16x16x32_bf16 v[16:19], v[174:177], v[190:193], v[16:19]
	v_mfma_f32_16x16x32_bf16 v[12:15], v[166:169], v[198:201], v[12:15]
	s_setprio 2
	s_barrier
	v_mfma_f32_16x16x32_bf16 v[8:11], v[174:177], v[198:201], v[8:11]
	v_mfma_f32_16x16x32_bf16 v[4:7], v[166:169], v[214:217], v[4:7]
	v_mfma_f32_16x16x32_bf16 v[0:3], v[174:177], v[214:217], v[0:3]
	s_setprio 0
	s_add_i32 s77, s77, 2
	s_add_u32 s52, s52, 0x100
	s_addc_u32 s53, s53, 0
	s_add_u32 s75, s75, 0x100
	s_addc_u32 s76, s76, 0
	s_cmp_gt_u32 s77, 29
	s_cbranch_scc0 .LBB0_1051
	s_and_b64 vcc, exec, s[14:15]
	s_cbranch_vccz .LBB0_1054
	s_barrier

; #define PG8_STAGE(bufoff, gbase, voff) do { _Pragma("unroll") for (int _i = 0; _i < 2; ++_i) \
;         __builtin_amdgcn_global_load_lds((const unsigned*)((const char*)(gbase) + (voff)[_i]), (PG8_LAS unsigned*)(lds + (bufoff) + ldsw + _i * 8192), 16, 0, 0); } while (0)
; #define PG8_LDA(dst, b, h) do { _Pragma("unroll") for (int m = 0; m < 4; ++m) _Pragma("unroll") for (int k = 0; k < 2; ++k) dst[m][k] = *(const PG8_LAS bf16x8*)(lds + PG8_SA(b, h) + aoff + m * 2048 + k * 1024); } while (0)
; #define PG8_LDB(dst, b, h) do { _Pragma("unroll") for (int n = 0; n < 2; ++n) _Pragma("unroll") for (int k = 0; k < 2; ++k) dst[n][k] = *(const PG8_LAS bf16x8*)(lds + PG8_SB(b, h) + boff + n * 2048 + k * 1024); } while (0)
; #define PG8_MMA(ai, bj, At, Bt) do { __builtin_amdgcn_s_setprio(1); _Pragma("unroll") for (int m = 0; m < 4; ++m) _Pragma("unroll") for (int n = 0; n < 2; ++n) _Pragma("unroll") for (int k = 0; k < 2; ++k) \
;         acc[ai][bj][m][n] = __builtin_amdgcn_mfma_f32_16x16x32_bf16(Bt[n][k], At[m][k], acc[ai][bj][m][n], 0, 0, 0); __builtin_amdgcn_s_setprio(0); } while (0)
; #define PG8_WAIT_V(n) asm volatile("s_waitcnt vmcnt(" #n ")" ::: "memory")
; #define PG8_WAIT_L(n) asm volatile("s_waitcnt lgkmcnt(" #n ")" ::: "memory")
; #define PG8_BAR __builtin_amdgcn_s_barrier()
; #define PG8_SCHED __builtin_amdgcn_sched_barrier(0)
; template <class Epi, class Sched, bool ALIGN_EPI = false, bool SP2 = false>
; __device__ __forceinline__ void gemm_phase(PG8_LAS unsigned char* lds, const Gemm g, const Sched& S, const Epi& E) {
;     ...
;             const bool last = (t == nt - 2);
;             const char* a1 = cA + (size_t)(t + 1) * kstep;
;             const char* a2 = last ? nA : cA + (size_t)(t + 2) * kstep; const char* b2 = last ? nB : cB + (size_t)(t + 2) * kstep;
;             const char* a3 = a2 + kstep; const char* b3 = b2 + kstep;
;             if constexpr (SP2) {
;             PG8_LDB(B0, 0, 0); PG8_LDB(B1, 0, 1); PG8_SCHED; PG8_LDA(At, 0, 0); PG8_STAGE(PG8_SA(1, 1), a1 + hstep, voffA);
;             PG8_WAIT_V(8); PG8_WAIT_L(0); PG8_BAR; PG8_MMA(0, 0, At, B0); PG8_MMA(0, 1, At, B1); PG8_BAR; PG8_SCHED;
;             PG8_LDA(At, 0, 1); PG8_STAGE(PG8_SB(0, 0), b2, voffB); PG8_STAGE(PG8_SB(0, 1), b2 + hstep, voffB); PG8_STAGE(PG8_SA(0, 0), a2, voffA);
.LBB0_1142:
	ds_read_b128 v[80:83], v171
	ds_read_b128 v[84:87], v171 offset:1024
	ds_read_b128 v[88:91], v171 offset:2048
	ds_read_b128 v[92:95], v171 offset:3072
	ds_read_b128 v[164:167], v172
	ds_read_b128 v[176:179], v172 offset:1024
	ds_read_b128 v[180:183], v172 offset:2048
	ds_read_b128 v[184:187], v172 offset:3072
	s_add_u32 s44, s42, 0xfff80080
	s_addc_u32 s45, s43, -1
	s_cmp_eq_u32 s64, 28
	s_cselect_b32 s47, s15, s45
	s_cselect_b32 s46, s60, s44
	s_cselect_b32 s45, s13, s63
	s_cselect_b32 s44, s61, s62
	v_lshl_add_u64 v[220:221], s[42:43], 0, v[156:157]
	s_add_i32 m0, s41, 0xc000
	ds_read_b128 v[188:191], v173
	ds_read_b128 v[192:195], v173 offset:1024
	ds_read_b128 v[196:199], v173 offset:2048
	ds_read_b128 v[200:203], v173 offset:3072
	ds_read_b128 v[204:207], v173 offset:4096
	ds_read_b128 v[208:211], v173 offset:5120
	ds_read_b128 v[212:215], v173 offset:6144
	ds_read_b128 v[216:219], v173 offset:7168
	global_load_lds_dwordx4 v[220:221], off
	v_lshl_add_u64 v[220:221], s[42:43], 0, v[158:159]
	s_add_i32 m0, s41, 0xe000
	s_nop 0
	global_load_lds_dwordx4 v[220:221], off
	s_waitcnt vmcnt(8)
	s_waitcnt lgkmcnt(0)
	s_setprio 1
	s_barrier
	v_mfma_f32_16x16x32_bf16 v[140:143], v[80:83], v[188:191], v[140:143]
	v_mfma_f32_16x16x32_bf16 v[136:139], v[88:91], v[188:191], v[136:139]
	v_mfma_f32_16x16x32_bf16 v[124:127], v[80:83], v[196:199], v[124:127]
	v_mfma_f32_16x16x32_bf16 v[120:123], v[88:91], v[196:199], v[120:123]
	v_mfma_f32_16x16x32_bf16 v[108:111], v[80:83], v[204:207], v[108:111]
	v_mfma_f32_16x16x32_bf16 v[104:107], v[88:91], v[204:207], v[104:107]
	v_mfma_f32_16x16x32_bf16 v[76:79], v[80:83], v[212:215], v[76:79]
	v_mfma_f32_16x16x32_bf16 v[72:75], v[88:91], v[212:215], v[72:75]
	v_mfma_f32_16x16x32_bf16 v[140:143], v[84:87], v[192:195], v[140:143]
	v_mfma_f32_16x16x32_bf16 v[136:139], v[92:95], v[192:195], v[136:139]
	v_mfma_f32_16x16x32_bf16 v[124:127], v[84:87], v[200:203], v[124:127]
	v_mfma_f32_16x16x32_bf16 v[120:123], v[92:95], v[200:203], v[120:123]
	v_mfma_f32_16x16x32_bf16 v[108:111], v[84:87], v[208:211], v[108:111]
	v_mfma_f32_16x16x32_bf16 v[104:107], v[92:95], v[208:211], v[104:107]
	v_mfma_f32_16x16x32_bf16 v[76:79], v[84:87], v[216:219], v[76:79]
	v_mfma_f32_16x16x32_bf16 v[72:75], v[92:95], v[216:219], v[72:75]
	s_setprio 0
	s_setprio 1
	v_mfma_f32_16x16x32_bf16 v[132:135], v[164:167], v[188:191], v[132:135]
	v_mfma_f32_16x16x32_bf16 v[128:131], v[180:183], v[188:191], v[128:131]
	v_mfma_f32_16x16x32_bf16 v[116:119], v[164:167], v[196:199], v[116:119]
	v_mfma_f32_16x16x32_bf16 v[112:115], v[180:183], v[196:199], v[112:115]
	v_mfma_f32_16x16x32_bf16 v[100:103], v[164:167], v[204:207], v[100:103]
	v_mfma_f32_16x16x32_bf16 v[96:99], v[180:183], v[204:207], v[96:99]
	v_mfma_f32_16x16x32_bf16 v[68:71], v[164:167], v[212:215], v[68:71]
	v_mfma_f32_16x16x32_bf16 v[64:67], v[180:183], v[212:215], v[64:67]
	v_mfma_f32_16x16x32_bf16 v[132:135], v[176:179], v[192:195], v[132:135]
	v_mfma_f32_16x16x32_bf16 v[128:131], v[184:187], v[192:195], v[128:131]
	v_mfma_f32_16x16x32_bf16 v[116:119], v[176:179], v[200:203], v[116:119]
	v_mfma_f32_16x16x32_bf16 v[112:115], v[184:187], v[200:203], v[112:115]
	v_mfma_f32_16x16x32_bf16 v[100:103], v[176:179], v[208:211], v[100:103]
	s_setprio 2
	s_barrier
	v_mfma_f32_16x16x32_bf16 v[96:99], v[184:187], v[208:211], v[96:99]
	v_mfma_f32_16x16x32_bf16 v[68:71], v[176:179], v[216:219], v[68:71]
	v_mfma_f32_16x16x32_bf16 v[64:67], v[184:187], v[216:219], v[64:67]
	s_setprio 0
	s_add_i32 s65, s56, s33
	v_lshl_add_u64 v[220:221], s[44:45], 0, v[148:149]
	s_mov_b32 m0, s65
	ds_read_b128 v[188:191], v173 offset:16384
	ds_read_b128 v[192:195], v173 offset:17408
	ds_read_b128 v[196:199], v173 offset:18432
	ds_read_b128 v[200:203], v173 offset:19456
	ds_read_b128 v[204:207], v173 offset:20480
	ds_read_b128 v[208:211], v173 offset:21504
	ds_read_b128 v[212:215], v173 offset:22528
	ds_read_b128 v[216:219], v173 offset:23552
	global_load_lds_dwordx4 v[220:221], off
	s_add_i32 m0, s65, 0x2000
	s_add_u32 s66, s44, 0x80000
	v_lshl_add_u64 v[222:223], s[44:45], 0, v[152:153]
	s_addc_u32 s67, s45, 0
	s_add_i32 s65, s57, s33
	global_load_lds_dwordx4 v[222:223], off
	v_lshl_add_u64 v[224:225], s[66:67], 0, v[148:149]
	s_mov_b32 m0, s65
	v_lshl_add_u64 v[226:227], s[46:47], 0, v[150:151]
	global_load_lds_dwordx4 v[224:225], off
	v_lshl_add_u64 v[224:225], s[66:67], 0, v[152:153]
	s_add_i32 m0, s65, 0x2000
	s_nop 0
	global_load_lds_dwordx4 v[224:225], off
	v_lshl_add_u64 v[224:225], s[46:47], 0, v[144:145]
	s_mov_b32 m0, s41
	s_nop 0
	global_load_lds_dwordx4 v[224:225], off
	s_mov_b32 m0, s48
	s_nop 0
	global_load_lds_dwordx4 v[226:227], off
	s_waitcnt vmcnt(8)
	s_waitcnt lgkmcnt(0)
	s_setprio 1
	s_barrier
; #define PG8_STAGE(bufoff, gbase, voff) do { _Pragma("unroll") for (int _i = 0; _i < 2; ++_i) \
;         __builtin_amdgcn_global_load_lds((const unsigned*)((const char*)(gbase) + (voff)[_i]), (PG8_LAS unsigned*)(lds + (bufoff) + ldsw + _i * 8192), 16, 0, 0); } while (0)
; #define PG8_LDA(dst, b, h) do { _Pragma("unroll") for (int m = 0; m < 4; ++m) _Pragma("unroll") for (int k = 0; k < 2; ++k) dst[m][k] = *(const PG8_LAS bf16x8*)(lds + PG8_SA(b, h) + aoff + m * 2048 + k * 1024); } while (0)
; #define PG8_LDB(dst, b, h) do { _Pragma("unroll") for (int n = 0; n < 2; ++n) _Pragma("unroll") for (int k = 0; k < 2; ++k) dst[n][k] = *(const PG8_LAS bf16x8*)(lds + PG8_SB(b, h) + boff + n * 2048 + k * 1024); } while (0)
; #define PG8_MMA(ai, bj, At, Bt) do { __builtin_amdgcn_s_setprio(1); _Pragma("unroll") for (int m = 0; m < 4; ++m) _Pragma("unroll") for (int n = 0; n < 2; ++n) _Pragma("unroll") for (int k = 0; k < 2; ++k) \
;         acc[ai][bj][m][n] = __builtin_amdgcn_mfma_f32_16x16x32_bf16(Bt[n][k], At[m][k], acc[ai][bj][m][n], 0, 0, 0); __builtin_amdgcn_s_setprio(0); } while (0)
; #define PG8_WAIT_V(n) asm volatile("s_waitcnt vmcnt(" #n ")" ::: "memory")
; #define PG8_WAIT_L(n) asm volatile("s_waitcnt lgkmcnt(" #n ")" ::: "memory")
; #define PG8_BAR __builtin_amdgcn_s_barrier()
; #define PG8_SCHED __builtin_amdgcn_sched_barrier(0)
; template <class Epi, class Sched, bool ALIGN_EPI = false, bool SP2 = false>
; __device__ __forceinline__ void gemm_phase(PG8_LAS unsigned char* lds, const Gemm g, const Sched& S, const Epi& E) {
;     ...
;             PG8_WAIT_V(8); PG8_WAIT_L(0); PG8_BAR; PG8_MMA(1, 0, At, B0); PG8_MMA(1, 1, At, B1); PG8_BAR; PG8_SCHED;
;             PG8_LDB(B0, 1, 0); PG8_LDB(B1, 1, 1); PG8_SCHED; PG8_LDA(At, 1, 0); PG8_STAGE(PG8_SA(0, 1), a2 + hstep, voffA);
;             PG8_WAIT_V(8); PG8_WAIT_L(0); PG8_BAR; PG8_MMA(0, 0, At, B0); PG8_MMA(0, 1, At, B1); PG8_BAR; PG8_SCHED;
	v_mfma_f32_16x16x32_bf16 v[60:63], v[80:83], v[188:191], v[60:63]
	v_mfma_f32_16x16x32_bf16 v[56:59], v[88:91], v[188:191], v[56:59]
	v_mfma_f32_16x16x32_bf16 v[44:47], v[80:83], v[196:199], v[44:47]
	v_mfma_f32_16x16x32_bf16 v[40:43], v[88:91], v[196:199], v[40:43]
	v_mfma_f32_16x16x32_bf16 v[28:31], v[80:83], v[204:207], v[28:31]
	v_mfma_f32_16x16x32_bf16 v[24:27], v[88:91], v[204:207], v[24:27]
	v_mfma_f32_16x16x32_bf16 v[12:15], v[80:83], v[212:215], v[12:15]
	v_mfma_f32_16x16x32_bf16 v[8:11], v[88:91], v[212:215], v[8:11]
	v_mfma_f32_16x16x32_bf16 v[60:63], v[84:87], v[192:195], v[60:63]
	v_mfma_f32_16x16x32_bf16 v[56:59], v[92:95], v[192:195], v[56:59]
	v_mfma_f32_16x16x32_bf16 v[44:47], v[84:87], v[200:203], v[44:47]
	v_mfma_f32_16x16x32_bf16 v[40:43], v[92:95], v[200:203], v[40:43]
	v_mfma_f32_16x16x32_bf16 v[28:31], v[84:87], v[208:211], v[28:31]
	v_mfma_f32_16x16x32_bf16 v[24:27], v[92:95], v[208:211], v[24:27]
	v_mfma_f32_16x16x32_bf16 v[12:15], v[84:87], v[216:219], v[12:15]
	v_mfma_f32_16x16x32_bf16 v[8:11], v[92:95], v[216:219], v[8:11]
	s_setprio 0
	s_setprio 1
	v_mfma_f32_16x16x32_bf16 v[52:55], v[164:167], v[188:191], v[52:55]
	v_mfma_f32_16x16x32_bf16 v[48:51], v[180:183], v[188:191], v[48:51]
	v_mfma_f32_16x16x32_bf16 v[36:39], v[164:167], v[196:199], v[36:39]
	v_mfma_f32_16x16x32_bf16 v[32:35], v[180:183], v[196:199], v[32:35]
	v_mfma_f32_16x16x32_bf16 v[20:23], v[164:167], v[204:207], v[20:23]
	v_mfma_f32_16x16x32_bf16 v[16:19], v[180:183], v[204:207], v[16:19]
	v_mfma_f32_16x16x32_bf16 v[4:7], v[164:167], v[212:215], v[4:7]
	v_mfma_f32_16x16x32_bf16 v[0:3], v[180:183], v[212:215], v[0:3]
	v_mfma_f32_16x16x32_bf16 v[52:55], v[176:179], v[192:195], v[52:55]
	v_mfma_f32_16x16x32_bf16 v[48:51], v[184:187], v[192:195], v[48:51]
	v_mfma_f32_16x16x32_bf16 v[36:39], v[176:179], v[200:203], v[36:39]
	v_mfma_f32_16x16x32_bf16 v[32:35], v[184:187], v[200:203], v[32:35]
	v_mfma_f32_16x16x32_bf16 v[20:23], v[176:179], v[208:211], v[20:23]
	s_setprio 2
	s_barrier
	v_mfma_f32_16x16x32_bf16 v[16:19], v[184:187], v[208:211], v[16:19]
	v_mfma_f32_16x16x32_bf16 v[4:7], v[176:179], v[216:219], v[4:7]
	v_mfma_f32_16x16x32_bf16 v[0:3], v[184:187], v[216:219], v[0:3]
	s_setprio 0
	s_add_i32 s65, 0, 0x18000
	s_add_i32 s66, 0, 0x1c000
	v_add_u32_e32 v92, s65, v169
	v_add_u32_e32 v184, s66, v169
	ds_read_b128 v[80:83], v92
	ds_read_b128 v[84:87], v92 offset:1024
	ds_read_b128 v[88:91], v92 offset:2048
	ds_read_b128 v[92:95], v92 offset:3072
	ds_read_b128 v[164:167], v184
	ds_read_b128 v[176:179], v184 offset:1024
	ds_read_b128 v[180:183], v184 offset:2048
	ds_read_b128 v[184:187], v184 offset:3072
	s_add_u32 s46, s46, 0x80000
	s_addc_u32 s47, s47, 0
	s_mov_b32 m0, s49
	v_lshl_add_u64 v[228:229], s[46:47], 0, v[144:145]
	ds_read_b128 v[188:191], v173 offset:32768
	ds_read_b128 v[192:195], v173 offset:33792
	ds_read_b128 v[196:199], v173 offset:34816
	ds_read_b128 v[200:203], v173 offset:35840
	ds_read_b128 v[204:207], v173 offset:36864
	ds_read_b128 v[208:211], v173 offset:37888
	ds_read_b128 v[212:215], v173 offset:38912
	ds_read_b128 v[216:219], v173 offset:39936
	global_load_lds_dwordx4 v[228:229], off
	v_lshl_add_u64 v[228:229], s[46:47], 0, v[150:151]
	s_mov_b32 m0, s50
	s_nop 0
	global_load_lds_dwordx4 v[228:229], off
	s_waitcnt vmcnt(8)
	s_waitcnt lgkmcnt(0)
	s_setprio 1
	s_barrier
	v_mfma_f32_16x16x32_bf16 v[140:143], v[80:83], v[188:191], v[140:143]
	v_mfma_f32_16x16x32_bf16 v[136:139], v[88:91], v[188:191], v[136:139]
	v_mfma_f32_16x16x32_bf16 v[124:127], v[80:83], v[196:199], v[124:127]
	v_mfma_f32_16x16x32_bf16 v[120:123], v[88:91], v[196:199], v[120:123]
	v_mfma_f32_16x16x32_bf16 v[108:111], v[80:83], v[204:207], v[108:111]
	v_mfma_f32_16x16x32_bf16 v[104:107], v[88:91], v[204:207], v[104:107]
	v_mfma_f32_16x16x32_bf16 v[76:79], v[80:83], v[212:215], v[76:79]
	v_mfma_f32_16x16x32_bf16 v[72:75], v[88:91], v[212:215], v[72:75]
	v_mfma_f32_16x16x32_bf16 v[140:143], v[84:87], v[192:195], v[140:143]
	v_mfma_f32_16x16x32_bf16 v[136:139], v[92:95], v[192:195], v[136:139]
	v_mfma_f32_16x16x32_bf16 v[124:127], v[84:87], v[200:203], v[124:127]
	v_mfma_f32_16x16x32_bf16 v[120:123], v[92:95], v[200:203], v[120:123]
	v_mfma_f32_16x16x32_bf16 v[108:111], v[84:87], v[208:211], v[108:111]
	v_mfma_f32_16x16x32_bf16 v[104:107], v[92:95], v[208:211], v[104:107]
	v_mfma_f32_16x16x32_bf16 v[76:79], v[84:87], v[216:219], v[76:79]
	v_mfma_f32_16x16x32_bf16 v[72:75], v[92:95], v[216:219], v[72:75]
	s_setprio 0
	s_setprio 1
	v_mfma_f32_16x16x32_bf16 v[132:135], v[164:167], v[188:191], v[132:135]
	v_mfma_f32_16x16x32_bf16 v[128:131], v[180:183], v[188:191], v[128:131]
	v_mfma_f32_16x16x32_bf16 v[116:119], v[164:167], v[196:199], v[116:119]
	v_mfma_f32_16x16x32_bf16 v[112:115], v[180:183], v[196:199], v[112:115]
	v_mfma_f32_16x16x32_bf16 v[100:103], v[164:167], v[204:207], v[100:103]
	v_mfma_f32_16x16x32_bf16 v[96:99], v[180:183], v[204:207], v[96:99]
	v_mfma_f32_16x16x32_bf16 v[68:71], v[164:167], v[212:215], v[68:71]
	v_mfma_f32_16x16x32_bf16 v[64:67], v[180:183], v[212:215], v[64:67]
	v_mfma_f32_16x16x32_bf16 v[132:135], v[176:179], v[192:195], v[132:135]
	v_mfma_f32_16x16x32_bf16 v[128:131], v[184:187], v[192:195], v[128:131]
	v_mfma_f32_16x16x32_bf16 v[116:119], v[176:179], v[200:203], v[116:119]
	v_mfma_f32_16x16x32_bf16 v[112:115], v[184:187], v[200:203], v[112:115]
	v_mfma_f32_16x16x32_bf16 v[100:103], v[176:179], v[208:211], v[100:103]
	s_setprio 2
	s_barrier
; #define PG8_STAGE(bufoff, gbase, voff) do { _Pragma("unroll") for (int _i = 0; _i < 2; ++_i) \
;         __builtin_amdgcn_global_load_lds((const unsigned*)((const char*)(gbase) + (voff)[_i]), (PG8_LAS unsigned*)(lds + (bufoff) + ldsw + _i * 8192), 16, 0, 0); } while (0)
; #define PG8_LDA(dst, b, h) do { _Pragma("unroll") for (int m = 0; m < 4; ++m) _Pragma("unroll") for (int k = 0; k < 2; ++k) dst[m][k] = *(const PG8_LAS bf16x8*)(lds + PG8_SA(b, h) + aoff + m * 2048 + k * 1024); } while (0)
; #define PG8_MMA(ai, bj, At, Bt) do { __builtin_amdgcn_s_setprio(1); _Pragma("unroll") for (int m = 0; m < 4; ++m) _Pragma("unroll") for (int n = 0; n < 2; ++n) _Pragma("unroll") for (int k = 0; k < 2; ++k) \
;         acc[ai][bj][m][n] = __builtin_amdgcn_mfma_f32_16x16x32_bf16(Bt[n][k], At[m][k], acc[ai][bj][m][n], 0, 0, 0); __builtin_amdgcn_s_setprio(0); } while (0)
; #define PG8_WAIT_V(n) asm volatile("s_waitcnt vmcnt(" #n ")" ::: "memory")
; #define PG8_WAIT_L(n) asm volatile("s_waitcnt lgkmcnt(" #n ")" ::: "memory")
; #define PG8_BAR __builtin_amdgcn_s_barrier()
; #define PG8_SCHED __builtin_amdgcn_sched_barrier(0)
; template <class Epi, class Sched, bool ALIGN_EPI = false, bool SP2 = false>
; __device__ __forceinline__ void gemm_phase(PG8_LAS unsigned char* lds, const Gemm g, const Sched& S, const Epi& E) {
;     ...
;             PG8_WAIT_V(8); PG8_WAIT_L(0); PG8_BAR; PG8_MMA(0, 0, At, B0); PG8_MMA(0, 1, At, B1); PG8_BAR; PG8_SCHED;
;             PG8_LDA(At, 1, 1); PG8_STAGE(PG8_SB(1, 0), b3, voffB); PG8_STAGE(PG8_SB(1, 1), b3 + hstep, voffB); PG8_STAGE(PG8_SA(1, 0), a3, voffA);
;             PG8_WAIT_V(8); PG8_WAIT_L(0); PG8_BAR; PG8_MMA(1, 0, At, B0); PG8_MMA(1, 1, At, B1); PG8_BAR; PG8_SCHED;
;     ...
;         if constexpr (ALIGN_EPI) { if (wr == 0) PG8_BAR; }
	v_mfma_f32_16x16x32_bf16 v[96:99], v[184:187], v[208:211], v[96:99]
	v_mfma_f32_16x16x32_bf16 v[68:71], v[176:179], v[216:219], v[68:71]
	v_mfma_f32_16x16x32_bf16 v[64:67], v[184:187], v[216:219], v[64:67]
	s_setprio 0
	s_add_i32 s46, s65, s33
	v_lshl_add_u64 v[220:221], v[220:221], 0, s[8:9]
	s_mov_b32 m0, s46
	ds_read_b128 v[188:191], v173 offset:49152
	ds_read_b128 v[192:195], v173 offset:50176
	ds_read_b128 v[196:199], v173 offset:51200
	ds_read_b128 v[200:203], v173 offset:52224
	ds_read_b128 v[204:207], v173 offset:53248
	ds_read_b128 v[208:211], v173 offset:54272
	ds_read_b128 v[212:215], v173 offset:55296
	ds_read_b128 v[216:219], v173 offset:56320
	global_load_lds_dwordx4 v[220:221], off
	s_add_i32 m0, s46, 0x2000
	s_add_u32 s44, s44, 0x80080
	v_lshl_add_u64 v[220:221], v[222:223], 0, s[8:9]
	s_addc_u32 s45, s45, 0
	s_add_i32 s46, s66, s33
	global_load_lds_dwordx4 v[220:221], off
	v_lshl_add_u64 v[220:221], s[44:45], 0, v[148:149]
	s_mov_b32 m0, s46
	s_nop 0
	global_load_lds_dwordx4 v[220:221], off
	v_lshl_add_u64 v[220:221], s[44:45], 0, v[152:153]
	s_add_i32 m0, s46, 0x2000
	s_nop 0
	global_load_lds_dwordx4 v[220:221], off
	v_lshl_add_u64 v[220:221], v[224:225], 0, s[8:9]
	s_mov_b32 m0, s52
	s_nop 0
	global_load_lds_dwordx4 v[220:221], off
	v_lshl_add_u64 v[220:221], v[226:227], 0, s[8:9]
	s_mov_b32 m0, s53
	s_nop 0
	global_load_lds_dwordx4 v[220:221], off
	s_waitcnt vmcnt(8)
	s_waitcnt lgkmcnt(0)
	s_setprio 1
	s_barrier
	v_mfma_f32_16x16x32_bf16 v[60:63], v[80:83], v[188:191], v[60:63]
	v_mfma_f32_16x16x32_bf16 v[56:59], v[88:91], v[188:191], v[56:59]
	v_mfma_f32_16x16x32_bf16 v[44:47], v[80:83], v[196:199], v[44:47]
	v_mfma_f32_16x16x32_bf16 v[40:43], v[88:91], v[196:199], v[40:43]
	v_mfma_f32_16x16x32_bf16 v[28:31], v[80:83], v[204:207], v[28:31]
	v_mfma_f32_16x16x32_bf16 v[24:27], v[88:91], v[204:207], v[24:27]
	v_mfma_f32_16x16x32_bf16 v[12:15], v[80:83], v[212:215], v[12:15]
	v_mfma_f32_16x16x32_bf16 v[8:11], v[88:91], v[212:215], v[8:11]
	v_mfma_f32_16x16x32_bf16 v[60:63], v[84:87], v[192:195], v[60:63]
	v_mfma_f32_16x16x32_bf16 v[56:59], v[92:95], v[192:195], v[56:59]
	v_mfma_f32_16x16x32_bf16 v[44:47], v[84:87], v[200:203], v[44:47]
	v_mfma_f32_16x16x32_bf16 v[40:43], v[92:95], v[200:203], v[40:43]
	v_mfma_f32_16x16x32_bf16 v[28:31], v[84:87], v[208:211], v[28:31]
	v_mfma_f32_16x16x32_bf16 v[24:27], v[92:95], v[208:211], v[24:27]
	v_mfma_f32_16x16x32_bf16 v[12:15], v[84:87], v[216:219], v[12:15]
	v_mfma_f32_16x16x32_bf16 v[8:11], v[92:95], v[216:219], v[8:11]
	s_setprio 0
	s_setprio 1
	v_mfma_f32_16x16x32_bf16 v[52:55], v[164:167], v[188:191], v[52:55]
	v_mfma_f32_16x16x32_bf16 v[48:51], v[180:183], v[188:191], v[48:51]
	v_mfma_f32_16x16x32_bf16 v[36:39], v[164:167], v[196:199], v[36:39]
	v_mfma_f32_16x16x32_bf16 v[32:35], v[180:183], v[196:199], v[32:35]
	v_mfma_f32_16x16x32_bf16 v[20:23], v[164:167], v[204:207], v[20:23]
	v_mfma_f32_16x16x32_bf16 v[16:19], v[180:183], v[204:207], v[16:19]
	v_mfma_f32_16x16x32_bf16 v[4:7], v[164:167], v[212:215], v[4:7]
	v_mfma_f32_16x16x32_bf16 v[0:3], v[180:183], v[212:215], v[0:3]
	v_mfma_f32_16x16x32_bf16 v[52:55], v[176:179], v[192:195], v[52:55]
	v_mfma_f32_16x16x32_bf16 v[48:51], v[184:187], v[192:195], v[48:51]
	v_mfma_f32_16x16x32_bf16 v[36:39], v[176:179], v[200:203], v[36:39]
	v_mfma_f32_16x16x32_bf16 v[32:35], v[184:187], v[200:203], v[32:35]
	v_mfma_f32_16x16x32_bf16 v[20:23], v[176:179], v[208:211], v[20:23]
	s_setprio 2
	s_barrier
	v_mfma_f32_16x16x32_bf16 v[16:19], v[184:187], v[208:211], v[16:19]
	v_mfma_f32_16x16x32_bf16 v[4:7], v[176:179], v[216:219], v[4:7]
	v_mfma_f32_16x16x32_bf16 v[0:3], v[184:187], v[216:219], v[0:3]
	s_setprio 0
	s_add_i32 s64, s64, 2
	s_add_u32 s42, s42, 0x100
	s_addc_u32 s43, s43, 0
	s_add_u32 s62, s62, 0x100
	s_addc_u32 s63, s63, 0
	s_cmp_gt_u32 s64, 29
	s_cbranch_scc0 .LBB0_1142
	s_and_b64 vcc, exec, s[10:11]
	s_cbranch_vccz .LBB0_1145
	s_barrier

; #define PG8_STAGE(bufoff, gbase, voff) do { _Pragma("unroll") for (int _i = 0; _i < 2; ++_i) \
;         __builtin_amdgcn_global_load_lds((const unsigned*)((const char*)(gbase) + (voff)[_i]), (PG8_LAS unsigned*)(lds + (bufoff) + ldsw + _i * 8192), 16, 0, 0); } while (0)
; #define PG8_LDA(dst, b, h) do { _Pragma("unroll") for (int m = 0; m < 4; ++m) _Pragma("unroll") for (int k = 0; k < 2; ++k) dst[m][k] = *(const PG8_LAS bf16x8*)(lds + PG8_SA(b, h) + aoff + m * 2048 + k * 1024); } while (0)
; #define PG8_LDB(dst, b, h) do { _Pragma("unroll") for (int n = 0; n < 2; ++n) _Pragma("unroll") for (int k = 0; k < 2; ++k) dst[n][k] = *(const PG8_LAS bf16x8*)(lds + PG8_SB(b, h) + boff + n * 2048 + k * 1024); } while (0)
; #define PG8_MMA(ai, bj, At, Bt) do { __builtin_amdgcn_s_setprio(1); _Pragma("unroll") for (int m = 0; m < 4; ++m) _Pragma("unroll") for (int n = 0; n < 2; ++n) _Pragma("unroll") for (int k = 0; k < 2; ++k) \
;         acc[ai][bj][m][n] = __builtin_amdgcn_mfma_f32_16x16x32_bf16(Bt[n][k], At[m][k], acc[ai][bj][m][n], 0, 0, 0); __builtin_amdgcn_s_setprio(0); } while (0)
; #define PG8_WAIT_V(n) asm volatile("s_waitcnt vmcnt(" #n ")" ::: "memory")
; #define PG8_WAIT_L(n) asm volatile("s_waitcnt lgkmcnt(" #n ")" ::: "memory")
; #define PG8_BAR __builtin_amdgcn_s_barrier()
; template <class Epi, class Sched, bool ALIGN_EPI = false, bool SP2 = false>
; __device__ __forceinline__ void gemm_phase(PG8_LAS unsigned char* lds, const Gemm g, const Sched& S, const Epi& E) {
;     ...
;         for (int t = 0; t < nt; t += 2) {
;             const bool last = (t == nt - 2);
;             const char* a1 = cA + (size_t)(t + 1) * kstep;
;             const char* a2 = last ? nA : cA + (size_t)(t + 2) * kstep; const char* b2 = last ? nB : cB + (size_t)(t + 2) * kstep;
;             const char* a3 = a2 + kstep; const char* b3 = b2 + kstep;
;             if constexpr (SP2) {
;             PG8_LDB(B0, 0, 0); PG8_LDB(B1, 0, 1); PG8_SCHED; PG8_LDA(At, 0, 0); PG8_STAGE(PG8_SA(1, 1), a1 + hstep, voffA);
;             PG8_WAIT_V(8); PG8_WAIT_L(0); PG8_BAR; PG8_MMA(0, 0, At, B0); PG8_MMA(0, 1, At, B1); PG8_BAR; PG8_SCHED;
;             PG8_LDA(At, 0, 1); PG8_STAGE(PG8_SB(0, 0), b2, voffB); PG8_STAGE(PG8_SB(0, 1), b2 + hstep, voffB); PG8_STAGE(PG8_SA(0, 0), a2, voffA);
;             PG8_WAIT_V(8); PG8_WAIT_L(0); PG8_BAR; PG8_MMA(1, 0, At, B0); PG8_MMA(1, 1, At, B1); PG8_BAR; PG8_SCHED;
.LBB0_1219:
	ds_read_b128 v[128:131], v167
	ds_read_b128 v[132:135], v167 offset:1024
	ds_read_b128 v[154:157], v167 offset:2048
	ds_read_b128 v[158:161], v167 offset:3072
	ds_read_b128 v[170:173], v168
	ds_read_b128 v[174:177], v168 offset:1024
	ds_read_b128 v[178:181], v168 offset:2048
	ds_read_b128 v[182:185], v168 offset:3072
	s_add_u32 s42, s40, 0xffe00080
	s_addc_u32 s43, s41, -1
	s_cmpk_eq_i32 s63, 0x7c
	s_cselect_b32 s45, s15, s43
	s_cselect_b32 s44, s59, s42
	s_cselect_b32 s43, s13, s62
	s_cselect_b32 s42, s60, s61
	v_lshl_add_u64 v[162:163], s[40:41], 0, v[144:145]
	s_add_i32 m0, s39, 0xc000
	ds_read_b128 v[186:189], v169
	ds_read_b128 v[190:193], v169 offset:1024
	ds_read_b128 v[194:197], v169 offset:2048
	ds_read_b128 v[198:201], v169 offset:3072
	ds_read_b128 v[202:205], v169 offset:4096
	ds_read_b128 v[206:209], v169 offset:5120
	ds_read_b128 v[210:213], v169 offset:6144
	ds_read_b128 v[214:217], v169 offset:7168
	global_load_lds_dwordx4 v[162:163], off
	v_lshl_add_u64 v[162:163], s[40:41], 0, v[148:149]
	s_add_i32 m0, s39, 0xe000
	s_nop 0
	global_load_lds_dwordx4 v[162:163], off
	s_waitcnt vmcnt(8)
	s_waitcnt lgkmcnt(0)
	s_setprio 1
	s_barrier
	v_mfma_f32_16x16x32_bf16 v[124:127], v[128:131], v[186:189], v[124:127]
	v_mfma_f32_16x16x32_bf16 v[120:123], v[154:157], v[186:189], v[120:123]
	v_mfma_f32_16x16x32_bf16 v[116:119], v[128:131], v[194:197], v[116:119]
	v_mfma_f32_16x16x32_bf16 v[112:115], v[154:157], v[194:197], v[112:115]
	v_mfma_f32_16x16x32_bf16 v[108:111], v[128:131], v[202:205], v[108:111]
	v_mfma_f32_16x16x32_bf16 v[104:107], v[154:157], v[202:205], v[104:107]
	v_mfma_f32_16x16x32_bf16 v[100:103], v[128:131], v[210:213], v[100:103]
	v_mfma_f32_16x16x32_bf16 v[96:99], v[154:157], v[210:213], v[96:99]
	v_mfma_f32_16x16x32_bf16 v[124:127], v[132:135], v[190:193], v[124:127]
	v_mfma_f32_16x16x32_bf16 v[120:123], v[158:161], v[190:193], v[120:123]
	v_mfma_f32_16x16x32_bf16 v[116:119], v[132:135], v[198:201], v[116:119]
	v_mfma_f32_16x16x32_bf16 v[112:115], v[158:161], v[198:201], v[112:115]
	v_mfma_f32_16x16x32_bf16 v[108:111], v[132:135], v[206:209], v[108:111]
	v_mfma_f32_16x16x32_bf16 v[104:107], v[158:161], v[206:209], v[104:107]
	v_mfma_f32_16x16x32_bf16 v[100:103], v[132:135], v[214:217], v[100:103]
	v_mfma_f32_16x16x32_bf16 v[96:99], v[158:161], v[214:217], v[96:99]
	s_setprio 0
	s_setprio 1
	v_mfma_f32_16x16x32_bf16 v[68:71], v[170:173], v[186:189], v[68:71]
	v_mfma_f32_16x16x32_bf16 v[60:63], v[178:181], v[186:189], v[60:63]
	v_mfma_f32_16x16x32_bf16 v[52:55], v[170:173], v[194:197], v[52:55]
	v_mfma_f32_16x16x32_bf16 v[48:51], v[178:181], v[194:197], v[48:51]
	v_mfma_f32_16x16x32_bf16 v[44:47], v[170:173], v[202:205], v[44:47]
	v_mfma_f32_16x16x32_bf16 v[40:43], v[178:181], v[202:205], v[40:43]
	v_mfma_f32_16x16x32_bf16 v[36:39], v[170:173], v[210:213], v[36:39]
	v_mfma_f32_16x16x32_bf16 v[32:35], v[178:181], v[210:213], v[32:35]
	v_mfma_f32_16x16x32_bf16 v[68:71], v[174:177], v[190:193], v[68:71]
	v_mfma_f32_16x16x32_bf16 v[60:63], v[182:185], v[190:193], v[60:63]
	v_mfma_f32_16x16x32_bf16 v[52:55], v[174:177], v[198:201], v[52:55]
	v_mfma_f32_16x16x32_bf16 v[48:51], v[182:185], v[198:201], v[48:51]
	v_mfma_f32_16x16x32_bf16 v[44:47], v[174:177], v[206:209], v[44:47]
	s_setprio 2
	s_barrier
	v_mfma_f32_16x16x32_bf16 v[40:43], v[182:185], v[206:209], v[40:43]
	v_mfma_f32_16x16x32_bf16 v[36:39], v[174:177], v[214:217], v[36:39]
	v_mfma_f32_16x16x32_bf16 v[32:35], v[182:185], v[214:217], v[32:35]
	s_setprio 0
	s_add_i32 s64, s56, s33
	v_lshl_add_u64 v[162:163], s[42:43], 0, v[138:139]
	s_mov_b32 m0, s64
	ds_read_b128 v[186:189], v169 offset:16384
	ds_read_b128 v[190:193], v169 offset:17408
	ds_read_b128 v[194:197], v169 offset:18432
	ds_read_b128 v[198:201], v169 offset:19456
	ds_read_b128 v[202:205], v169 offset:20480
	ds_read_b128 v[206:209], v169 offset:21504
	ds_read_b128 v[210:213], v169 offset:22528
	ds_read_b128 v[214:217], v169 offset:23552
	global_load_lds_dwordx4 v[162:163], off
	s_add_i32 m0, s64, 0x2000
	s_add_u32 s64, s42, 0x200000
	v_lshl_add_u64 v[218:219], s[42:43], 0, v[142:143]
	s_addc_u32 s65, s43, 0
	s_add_i32 s66, s57, s33
	global_load_lds_dwordx4 v[218:219], off
	v_lshl_add_u64 v[220:221], s[64:65], 0, v[138:139]
	s_mov_b32 m0, s66
	v_lshl_add_u64 v[222:223], s[44:45], 0, v[140:141]
	global_load_lds_dwordx4 v[220:221], off
	v_lshl_add_u64 v[220:221], s[64:65], 0, v[142:143]
	s_add_i32 m0, s66, 0x2000
	s_nop 0
	global_load_lds_dwordx4 v[220:221], off
	v_lshl_add_u64 v[220:221], s[44:45], 0, v[136:137]
	s_mov_b32 m0, s39
	s_nop 0
	global_load_lds_dwordx4 v[220:221], off
	s_mov_b32 m0, s46
	s_nop 0
	global_load_lds_dwordx4 v[222:223], off
	s_waitcnt vmcnt(8)
	s_waitcnt lgkmcnt(0)
	s_setprio 1
	s_barrier
; #define PG8_STAGE(bufoff, gbase, voff) do { _Pragma("unroll") for (int _i = 0; _i < 2; ++_i) \
;         __builtin_amdgcn_global_load_lds((const unsigned*)((const char*)(gbase) + (voff)[_i]), (PG8_LAS unsigned*)(lds + (bufoff) + ldsw + _i * 8192), 16, 0, 0); } while (0)
; #define PG8_LDA(dst, b, h) do { _Pragma("unroll") for (int m = 0; m < 4; ++m) _Pragma("unroll") for (int k = 0; k < 2; ++k) dst[m][k] = *(const PG8_LAS bf16x8*)(lds + PG8_SA(b, h) + aoff + m * 2048 + k * 1024); } while (0)
; #define PG8_LDB(dst, b, h) do { _Pragma("unroll") for (int n = 0; n < 2; ++n) _Pragma("unroll") for (int k = 0; k < 2; ++k) dst[n][k] = *(const PG8_LAS bf16x8*)(lds + PG8_SB(b, h) + boff + n * 2048 + k * 1024); } while (0)
; #define PG8_MMA(ai, bj, At, Bt) do { __builtin_amdgcn_s_setprio(1); _Pragma("unroll") for (int m = 0; m < 4; ++m) _Pragma("unroll") for (int n = 0; n < 2; ++n) _Pragma("unroll") for (int k = 0; k < 2; ++k) \
;         acc[ai][bj][m][n] = __builtin_amdgcn_mfma_f32_16x16x32_bf16(Bt[n][k], At[m][k], acc[ai][bj][m][n], 0, 0, 0); __builtin_amdgcn_s_setprio(0); } while (0)
; #define PG8_WAIT_V(n) asm volatile("s_waitcnt vmcnt(" #n ")" ::: "memory")
; #define PG8_WAIT_L(n) asm volatile("s_waitcnt lgkmcnt(" #n ")" ::: "memory")
; #define PG8_BAR __builtin_amdgcn_s_barrier()
; #define PG8_SCHED __builtin_amdgcn_sched_barrier(0)
; template <class Epi, class Sched, bool ALIGN_EPI = false, bool SP2 = false>
; __device__ __forceinline__ void gemm_phase(PG8_LAS unsigned char* lds, const Gemm g, const Sched& S, const Epi& E) {
;     ...
;             PG8_WAIT_V(8); PG8_WAIT_L(0); PG8_BAR; PG8_MMA(1, 0, At, B0); PG8_MMA(1, 1, At, B1); PG8_BAR; PG8_SCHED;
;             PG8_LDB(B0, 1, 0); PG8_LDB(B1, 1, 1); PG8_SCHED; PG8_LDA(At, 1, 0); PG8_STAGE(PG8_SA(0, 1), a2 + hstep, voffA);
;             PG8_WAIT_V(8); PG8_WAIT_L(0); PG8_BAR; PG8_MMA(0, 0, At, B0); PG8_MMA(0, 1, At, B1); PG8_BAR; PG8_SCHED;
	v_mfma_f32_16x16x32_bf16 v[92:95], v[128:131], v[186:189], v[92:95]
	v_mfma_f32_16x16x32_bf16 v[88:91], v[154:157], v[186:189], v[88:91]
	v_mfma_f32_16x16x32_bf16 v[84:87], v[128:131], v[194:197], v[84:87]
	v_mfma_f32_16x16x32_bf16 v[80:83], v[154:157], v[194:197], v[80:83]
	v_mfma_f32_16x16x32_bf16 v[76:79], v[128:131], v[202:205], v[76:79]
	v_mfma_f32_16x16x32_bf16 v[72:75], v[154:157], v[202:205], v[72:75]
	v_mfma_f32_16x16x32_bf16 v[64:67], v[128:131], v[210:213], v[64:67]
	v_mfma_f32_16x16x32_bf16 v[56:59], v[154:157], v[210:213], v[56:59]
	v_mfma_f32_16x16x32_bf16 v[92:95], v[132:135], v[190:193], v[92:95]
	v_mfma_f32_16x16x32_bf16 v[88:91], v[158:161], v[190:193], v[88:91]
	v_mfma_f32_16x16x32_bf16 v[84:87], v[132:135], v[198:201], v[84:87]
	v_mfma_f32_16x16x32_bf16 v[80:83], v[158:161], v[198:201], v[80:83]
	v_mfma_f32_16x16x32_bf16 v[76:79], v[132:135], v[206:209], v[76:79]
	v_mfma_f32_16x16x32_bf16 v[72:75], v[158:161], v[206:209], v[72:75]
	v_mfma_f32_16x16x32_bf16 v[64:67], v[132:135], v[214:217], v[64:67]
	v_mfma_f32_16x16x32_bf16 v[56:59], v[158:161], v[214:217], v[56:59]
	s_setprio 0
	s_setprio 1
	v_mfma_f32_16x16x32_bf16 v[28:31], v[170:173], v[186:189], v[28:31]
	v_mfma_f32_16x16x32_bf16 v[24:27], v[178:181], v[186:189], v[24:27]
	v_mfma_f32_16x16x32_bf16 v[20:23], v[170:173], v[194:197], v[20:23]
	v_mfma_f32_16x16x32_bf16 v[16:19], v[178:181], v[194:197], v[16:19]
	v_mfma_f32_16x16x32_bf16 v[12:15], v[170:173], v[202:205], v[12:15]
	v_mfma_f32_16x16x32_bf16 v[8:11], v[178:181], v[202:205], v[8:11]
	v_mfma_f32_16x16x32_bf16 v[4:7], v[170:173], v[210:213], v[4:7]
	v_mfma_f32_16x16x32_bf16 v[0:3], v[178:181], v[210:213], v[0:3]
	v_mfma_f32_16x16x32_bf16 v[28:31], v[174:177], v[190:193], v[28:31]
	v_mfma_f32_16x16x32_bf16 v[24:27], v[182:185], v[190:193], v[24:27]
	v_mfma_f32_16x16x32_bf16 v[20:23], v[174:177], v[198:201], v[20:23]
	v_mfma_f32_16x16x32_bf16 v[16:19], v[182:185], v[198:201], v[16:19]
	v_mfma_f32_16x16x32_bf16 v[12:15], v[174:177], v[206:209], v[12:15]
	s_setprio 2
	s_barrier
	v_mfma_f32_16x16x32_bf16 v[8:11], v[182:185], v[206:209], v[8:11]
	v_mfma_f32_16x16x32_bf16 v[4:7], v[174:177], v[214:217], v[4:7]
	v_mfma_f32_16x16x32_bf16 v[0:3], v[182:185], v[214:217], v[0:3]
	s_setprio 0
	s_add_i32 s64, 0, 0x18000
	s_add_i32 s65, 0, 0x1c000
	v_add_u32_e32 v158, s64, v165
	v_add_u32_e32 v182, s65, v165
	ds_read_b128 v[128:131], v158
	ds_read_b128 v[132:135], v158 offset:1024
	ds_read_b128 v[154:157], v158 offset:2048
	ds_read_b128 v[158:161], v158 offset:3072
	ds_read_b128 v[170:173], v182
	ds_read_b128 v[174:177], v182 offset:1024
	ds_read_b128 v[178:181], v182 offset:2048
	ds_read_b128 v[182:185], v182 offset:3072
	s_add_u32 s44, s44, 0x200000
	s_addc_u32 s45, s45, 0
	s_mov_b32 m0, s47
	v_lshl_add_u64 v[224:225], s[44:45], 0, v[136:137]
	ds_read_b128 v[186:189], v169 offset:32768
	ds_read_b128 v[190:193], v169 offset:33792
	ds_read_b128 v[194:197], v169 offset:34816
	ds_read_b128 v[198:201], v169 offset:35840
	ds_read_b128 v[202:205], v169 offset:36864
	ds_read_b128 v[206:209], v169 offset:37888
	ds_read_b128 v[210:213], v169 offset:38912
	ds_read_b128 v[214:217], v169 offset:39936
	global_load_lds_dwordx4 v[224:225], off
	v_lshl_add_u64 v[224:225], s[44:45], 0, v[140:141]
	s_mov_b32 m0, s48
	s_nop 0
	global_load_lds_dwordx4 v[224:225], off
	s_waitcnt vmcnt(8)
	s_waitcnt lgkmcnt(0)
	s_setprio 1
	s_barrier
	v_mfma_f32_16x16x32_bf16 v[124:127], v[128:131], v[186:189], v[124:127]
	v_mfma_f32_16x16x32_bf16 v[120:123], v[154:157], v[186:189], v[120:123]
	v_mfma_f32_16x16x32_bf16 v[116:119], v[128:131], v[194:197], v[116:119]
	v_mfma_f32_16x16x32_bf16 v[112:115], v[154:157], v[194:197], v[112:115]
	v_mfma_f32_16x16x32_bf16 v[108:111], v[128:131], v[202:205], v[108:111]
	v_mfma_f32_16x16x32_bf16 v[104:107], v[154:157], v[202:205], v[104:107]
	v_mfma_f32_16x16x32_bf16 v[100:103], v[128:131], v[210:213], v[100:103]
	v_mfma_f32_16x16x32_bf16 v[96:99], v[154:157], v[210:213], v[96:99]
	v_mfma_f32_16x16x32_bf16 v[124:127], v[132:135], v[190:193], v[124:127]
	v_mfma_f32_16x16x32_bf16 v[120:123], v[158:161], v[190:193], v[120:123]
	v_mfma_f32_16x16x32_bf16 v[116:119], v[132:135], v[198:201], v[116:119]
	v_mfma_f32_16x16x32_bf16 v[112:115], v[158:161], v[198:201], v[112:115]
	v_mfma_f32_16x16x32_bf16 v[108:111], v[132:135], v[206:209], v[108:111]
	v_mfma_f32_16x16x32_bf16 v[104:107], v[158:161], v[206:209], v[104:107]
	v_mfma_f32_16x16x32_bf16 v[100:103], v[132:135], v[214:217], v[100:103]
	v_mfma_f32_16x16x32_bf16 v[96:99], v[158:161], v[214:217], v[96:99]
	s_setprio 0
	s_setprio 1
	v_mfma_f32_16x16x32_bf16 v[68:71], v[170:173], v[186:189], v[68:71]
	v_mfma_f32_16x16x32_bf16 v[60:63], v[178:181], v[186:189], v[60:63]
	v_mfma_f32_16x16x32_bf16 v[52:55], v[170:173], v[194:197], v[52:55]
	v_mfma_f32_16x16x32_bf16 v[48:51], v[178:181], v[194:197], v[48:51]
	v_mfma_f32_16x16x32_bf16 v[44:47], v[170:173], v[202:205], v[44:47]
	v_mfma_f32_16x16x32_bf16 v[40:43], v[178:181], v[202:205], v[40:43]
	v_mfma_f32_16x16x32_bf16 v[36:39], v[170:173], v[210:213], v[36:39]
	v_mfma_f32_16x16x32_bf16 v[32:35], v[178:181], v[210:213], v[32:35]
	v_mfma_f32_16x16x32_bf16 v[68:71], v[174:177], v[190:193], v[68:71]
	v_mfma_f32_16x16x32_bf16 v[60:63], v[182:185], v[190:193], v[60:63]
	v_mfma_f32_16x16x32_bf16 v[52:55], v[174:177], v[198:201], v[52:55]
	v_mfma_f32_16x16x32_bf16 v[48:51], v[182:185], v[198:201], v[48:51]
	v_mfma_f32_16x16x32_bf16 v[44:47], v[174:177], v[206:209], v[44:47]
	s_setprio 2
	s_barrier
; #define PG8_STAGE(bufoff, gbase, voff) do { _Pragma("unroll") for (int _i = 0; _i < 2; ++_i) \
;         __builtin_amdgcn_global_load_lds((const unsigned*)((const char*)(gbase) + (voff)[_i]), (PG8_LAS unsigned*)(lds + (bufoff) + ldsw + _i * 8192), 16, 0, 0); } while (0)
; #define PG8_LDA(dst, b, h) do { _Pragma("unroll") for (int m = 0; m < 4; ++m) _Pragma("unroll") for (int k = 0; k < 2; ++k) dst[m][k] = *(const PG8_LAS bf16x8*)(lds + PG8_SA(b, h) + aoff + m * 2048 + k * 1024); } while (0)
; #define PG8_MMA(ai, bj, At, Bt) do { __builtin_amdgcn_s_setprio(1); _Pragma("unroll") for (int m = 0; m < 4; ++m) _Pragma("unroll") for (int n = 0; n < 2; ++n) _Pragma("unroll") for (int k = 0; k < 2; ++k) \
;         acc[ai][bj][m][n] = __builtin_amdgcn_mfma_f32_16x16x32_bf16(Bt[n][k], At[m][k], acc[ai][bj][m][n], 0, 0, 0); __builtin_amdgcn_s_setprio(0); } while (0)
; #define PG8_WAIT_V(n) asm volatile("s_waitcnt vmcnt(" #n ")" ::: "memory")
; #define PG8_WAIT_L(n) asm volatile("s_waitcnt lgkmcnt(" #n ")" ::: "memory")
; #define PG8_BAR __builtin_amdgcn_s_barrier()
; #define PG8_SCHED __builtin_amdgcn_sched_barrier(0)
; template <class Epi, class Sched, bool ALIGN_EPI = false, bool SP2 = false>
; __device__ __forceinline__ void gemm_phase(PG8_LAS unsigned char* lds, const Gemm g, const Sched& S, const Epi& E) {
;     ...
;             PG8_WAIT_V(8); PG8_WAIT_L(0); PG8_BAR; PG8_MMA(0, 0, At, B0); PG8_MMA(0, 1, At, B1); PG8_BAR; PG8_SCHED;
;             PG8_LDA(At, 1, 1); PG8_STAGE(PG8_SB(1, 0), b3, voffB); PG8_STAGE(PG8_SB(1, 1), b3 + hstep, voffB); PG8_STAGE(PG8_SA(1, 0), a3, voffA);
;             PG8_WAIT_V(8); PG8_WAIT_L(0); PG8_BAR; PG8_MMA(1, 0, At, B0); PG8_MMA(1, 1, At, B1); PG8_BAR; PG8_SCHED;
;     ...
;         if constexpr (ALIGN_EPI) { if (wr == 0) PG8_BAR; }
	v_mfma_f32_16x16x32_bf16 v[40:43], v[182:185], v[206:209], v[40:43]
	v_mfma_f32_16x16x32_bf16 v[36:39], v[174:177], v[214:217], v[36:39]
	v_mfma_f32_16x16x32_bf16 v[32:35], v[182:185], v[214:217], v[32:35]
	s_setprio 0
	s_add_i32 s44, s64, s33
	v_lshl_add_u64 v[162:163], v[162:163], 0, s[8:9]
	s_mov_b32 m0, s44
	ds_read_b128 v[186:189], v169 offset:49152
	ds_read_b128 v[190:193], v169 offset:50176
	ds_read_b128 v[194:197], v169 offset:51200
	ds_read_b128 v[198:201], v169 offset:52224
	ds_read_b128 v[202:205], v169 offset:53248
	ds_read_b128 v[206:209], v169 offset:54272
	ds_read_b128 v[210:213], v169 offset:55296
	ds_read_b128 v[214:217], v169 offset:56320
	global_load_lds_dwordx4 v[162:163], off
	s_add_i32 m0, s44, 0x2000
	s_add_u32 s42, s42, 0x200080
	v_lshl_add_u64 v[162:163], v[218:219], 0, s[8:9]
	s_addc_u32 s43, s43, 0
	s_add_i32 s44, s65, s33
	global_load_lds_dwordx4 v[162:163], off
	v_lshl_add_u64 v[162:163], s[42:43], 0, v[138:139]
	s_mov_b32 m0, s44
	s_nop 0
	global_load_lds_dwordx4 v[162:163], off
	v_lshl_add_u64 v[162:163], s[42:43], 0, v[142:143]
	s_add_i32 m0, s44, 0x2000
	s_nop 0
	global_load_lds_dwordx4 v[162:163], off
	v_lshl_add_u64 v[162:163], v[220:221], 0, s[8:9]
	s_mov_b32 m0, s52
	s_nop 0
	global_load_lds_dwordx4 v[162:163], off
	v_lshl_add_u64 v[162:163], v[222:223], 0, s[8:9]
	s_mov_b32 m0, s53
	s_nop 0
	global_load_lds_dwordx4 v[162:163], off
	s_waitcnt vmcnt(8)
	s_waitcnt lgkmcnt(0)
	s_setprio 1
	s_barrier
	v_mfma_f32_16x16x32_bf16 v[92:95], v[128:131], v[186:189], v[92:95]
	v_mfma_f32_16x16x32_bf16 v[88:91], v[154:157], v[186:189], v[88:91]
	v_mfma_f32_16x16x32_bf16 v[84:87], v[128:131], v[194:197], v[84:87]
	v_mfma_f32_16x16x32_bf16 v[80:83], v[154:157], v[194:197], v[80:83]
	v_mfma_f32_16x16x32_bf16 v[76:79], v[128:131], v[202:205], v[76:79]
	v_mfma_f32_16x16x32_bf16 v[72:75], v[154:157], v[202:205], v[72:75]
	v_mfma_f32_16x16x32_bf16 v[64:67], v[128:131], v[210:213], v[64:67]
	v_mfma_f32_16x16x32_bf16 v[56:59], v[154:157], v[210:213], v[56:59]
	v_mfma_f32_16x16x32_bf16 v[92:95], v[132:135], v[190:193], v[92:95]
	v_mfma_f32_16x16x32_bf16 v[88:91], v[158:161], v[190:193], v[88:91]
	v_mfma_f32_16x16x32_bf16 v[84:87], v[132:135], v[198:201], v[84:87]
	v_mfma_f32_16x16x32_bf16 v[80:83], v[158:161], v[198:201], v[80:83]
	v_mfma_f32_16x16x32_bf16 v[76:79], v[132:135], v[206:209], v[76:79]
	v_mfma_f32_16x16x32_bf16 v[72:75], v[158:161], v[206:209], v[72:75]
	v_mfma_f32_16x16x32_bf16 v[64:67], v[132:135], v[214:217], v[64:67]
	v_mfma_f32_16x16x32_bf16 v[56:59], v[158:161], v[214:217], v[56:59]
	s_setprio 0
	s_setprio 1
	v_mfma_f32_16x16x32_bf16 v[28:31], v[170:173], v[186:189], v[28:31]
	v_mfma_f32_16x16x32_bf16 v[24:27], v[178:181], v[186:189], v[24:27]
	v_mfma_f32_16x16x32_bf16 v[20:23], v[170:173], v[194:197], v[20:23]
	v_mfma_f32_16x16x32_bf16 v[16:19], v[178:181], v[194:197], v[16:19]
	v_mfma_f32_16x16x32_bf16 v[12:15], v[170:173], v[202:205], v[12:15]
	v_mfma_f32_16x16x32_bf16 v[8:11], v[178:181], v[202:205], v[8:11]
	v_mfma_f32_16x16x32_bf16 v[4:7], v[170:173], v[210:213], v[4:7]
	v_mfma_f32_16x16x32_bf16 v[0:3], v[178:181], v[210:213], v[0:3]
	v_mfma_f32_16x16x32_bf16 v[28:31], v[174:177], v[190:193], v[28:31]
	v_mfma_f32_16x16x32_bf16 v[24:27], v[182:185], v[190:193], v[24:27]
	v_mfma_f32_16x16x32_bf16 v[20:23], v[174:177], v[198:201], v[20:23]
	v_mfma_f32_16x16x32_bf16 v[16:19], v[182:185], v[198:201], v[16:19]
	v_mfma_f32_16x16x32_bf16 v[12:15], v[174:177], v[206:209], v[12:15]
	s_setprio 2
	s_barrier
	v_mfma_f32_16x16x32_bf16 v[8:11], v[182:185], v[206:209], v[8:11]
	v_mfma_f32_16x16x32_bf16 v[4:7], v[174:177], v[214:217], v[4:7]
	v_mfma_f32_16x16x32_bf16 v[0:3], v[182:185], v[214:217], v[0:3]
	s_setprio 0
	s_add_i32 s63, s63, 2
	s_add_u32 s40, s40, 0x100
	s_addc_u32 s41, s41, 0
	s_add_u32 s61, s61, 0x100
	s_addc_u32 s62, s62, 0
	s_cmpk_gt_u32 s63, 0x7d
	s_cbranch_scc0 .LBB0_1219
	s_and_b64 vcc, exec, s[10:11]
	s_cbranch_vccz .LBB0_1222
	s_barrier
